# POST phase (7) on the hand-written GEMM core: B rows permuted so a lane owns 8 consecutive channels, fused LayerNorm/token-shift/gate epilogue with 16-byte accesses and prefetch of the next head/row b
# speedup vs baseline: 1.1881x; 1.0074x over previous
; #define PH(n, sync_) if (plo <= (n) && (n) <= phi) { if ((n) > plo && (sync_)) { if ((n) == 1) { grid.sync(); xb = xcd_barrier_post((unsigned*)(ws + O_XBAR), (volatile LAS unsigned*)&xb_words); } else xcd_barrier(xb); }
; __global__ void __launch_bounds__(512) mega(Params p, int plo, int phi) {
;     ...
;   PH(7, 1) gemm_phase<EPI_POST>(p, WSB(O_LIN + 256), 256, WSB(O_WLG), 128, 128, 768, nullptr, 0, 0, 0); PHEND
.LBB0_999:
	s_mov_b32 s101, 7
	s_branch .Lgm_entry

; #define PH(n, sync_) if (plo <= (n) && (n) <= phi) { if ((n) > plo && (sync_)) { if ((n) == 1) { grid.sync(); xb = xcd_barrier_post((unsigned*)(ws + O_XBAR), (volatile LAS unsigned*)&xb_words); } else xcd_barrier(xb); }
; __global__ void __launch_bounds__(512) mega(Params p, int plo, int phi) {
;     ...
;   PH(0, 1) phase0(p); PHEND
;   PH(1, 1) gemm_phase<EPI_SCALE>(p, WSB(O_XB), 1024, WSB(O_WIN0), 1024, 1024, 2816, WSO(O_P), 2816, 0, 0); PHEND
;   PH(2, 1) pool_phase(p); PHEND
;   PH(3, 1) gemm_phase<EPI_PLAIN>(p, WSB(O_LIN), 256, WSB(O_WLW), 64, 64, 768, WSO(O_WPRE), 768, 0, 0); PHEND
;   PH(4, 0) gemm_phase<EPI_PLAIN>(p, WSB(O_LIN + 128), 256, WSB(O_WLA), 64, 64, 768, WSO(O_APRE), 768, 0, 140); PHEND
;   PH(5, 1) rwkv_prep_phase(p); PHEND
;   PH(6, 1) scan_phase(p, 0, 0, 3264); pool_queue(p); PHEND
;   PH(7, 1) gemm_phase<EPI_POST>(p, WSB(O_LIN + 256), 256, WSB(O_WLG), 128, 128, 768, nullptr, 0, 0, 0); PHEND
;   PH(8, 1) gemm_phase<EPI_RES>(p, WSB(O_Y), 1024, WSB(O_WOUT0), 1024, 1024, 1024, WSO(O_XB), 1024, 1, 0); PHEND
;   PH(9, 1) res_fix_phase(p); PHEND
;   PH(10, 1) gemm_phase<EPI_FF1>(p, WSB(O_XB), 1024, WSB(O_WF10), 1024, 1024, 4096, WSO(O_H), 4096, 0, 0); PHEND
;   PH(11, 1) gemm_phase<EPI_RES>(p, WSB(O_H), 4096, WSB(O_WF20), 4096, 4096, 1024, WSO(O_XB), 1024, 0, 0); PHEND
;   PH(12, 1) res_fix_phase(p); PHEND
;   PH(13, 1) gemm_phase<EPI_SCALE>(p, WSB(O_XB), 1024, WSB(O_WIN1), 1024, 1024, 2048, WSO(O_P), 2048, 0, 0); PHEND
;   PH(14, 1) mix1_phase(p); PHEND
;   PH(15, 1) lru_fix_phase(p, xb); PHEND
;   PH(16, 1) gemm_phase<EPI_RES>(p, WSB(O_Y), 1024, WSB(O_WOUT1), 1024, 1024, 1024, WSO(O_XB), 1024, 0, 0); PHEND
;   PH(17, 1) res_fix_phase(p); PHEND
;   PH(18, 1) gemm_phase<EPI_FF1>(p, WSB(O_XB), 1024, WSB(O_WF11), 1024, 1024, 4096, WSO(O_H), 4096, 0, 0); PHEND
;   PH(19, 1) gemm_phase<EPI_RES>(p, WSB(O_H), 4096, WSB(O_WF21), 4096, 4096, 1024, WSO(O_XB), 1024, 0, 0); PHEND
;   PH(20, 1) res_fix_phase(p); PHEND
;   PH(21, 1) final_phase(p); PHEND
.Lgm_entry_nosave:
	s_cmp_eq_u32 s101, 1
	s_cbranch_scc1 .Lgm_par1
	s_cmp_eq_u32 s101, 7
	s_cbranch_scc1 .Lgm_par7
	s_cmp_eq_u32 s101, 8
	s_cbranch_scc1 .Lgm_par8
	s_cmp_eq_u32 s101, 10
	s_cbranch_scc1 .Lgm_par10
	s_cmp_eq_u32 s101, 11
	s_cbranch_scc1 .Lgm_par11
	s_cmp_eq_u32 s101, 13
	s_cbranch_scc1 .Lgm_par13
	s_cmp_eq_u32 s101, 16
	s_cbranch_scc1 .Lgm_par16
	s_cmp_eq_u32 s101, 18
	s_cbranch_scc1 .Lgm_par18
	s_cmp_eq_u32 s101, 19
	s_cbranch_scc1 .Lgm_par19
	s_branch .Lgm_par19

; #define PH(n, sync_) if (plo <= (n) && (n) <= phi) { if ((n) > plo && (sync_)) { if ((n) == 1) { grid.sync(); xb = xcd_barrier_post((unsigned*)(ws + O_XBAR), (volatile LAS unsigned*)&xb_words); } else xcd_barrier(xb); }
; template <int EPI>
; __device__ __forceinline__ void gemm_phase(const Params& p, const u16* __restrict__ A, int lda, const u16* __restrict__ BT, int ldb,
;                            int K, int N, u16* __restrict__ outb, int ldo, int resid_in, int boff) {
;     ...
;   const int NT = N / 128;
;   const int tiles = (MT / 256) * NT;
;   const int KTALL = K / 64;
;   float* part = (float*)(p.ws + O_PART);
;   int bstart = (int)blockIdx.x - boff;
;   if (bstart < 0) bstart += gridDim.x;
;   const size_t a64 = (size_t)64 * lda, b64 = (size_t)64 * ldb;
;   const int G = gridDim.x;
;   int t_full = tiles, split = 1;
;   if (EPI == EPI_RES) {
;     const int tail = tiles % G;
;     if (tail > 0 && (G % tail) == 0 && (KTALL % (G / tail)) == 0) { t_full = tiles - tail; const int smax = (KTALL >= 64) ? 8 : 4; split = (G / tail) > smax ? smax : (G / tail); }
;   }
;   const int units = t_full + (tiles - t_full) * split;
; __global__ void __launch_bounds__(512) mega(Params p, int plo, int phi) {
;     ...
;   PH(7, 1) gemm_phase<EPI_POST>(p, WSB(O_LIN + 256), 256, WSB(O_WLG), 128, 128, 768, nullptr, 0, 0, 0); PHEND
.Lgm_par7:
	s_add_u32 s16, s96, 0xcbc8200
	s_addc_u32 s17, s97, 0
	s_add_u32 s20, s96, 0x2db0000
	s_addc_u32 s21, s97, 0
	s_add_u32 s22, s96, 0x5008100
	s_addc_u32 s23, s97, 0
	s_movk_i32 s24, 0x800
	s_mov_b32 s25, 6
	s_mov_b32 s26, 0x2aaaaaab
	s_mov_b32 s27, 0
	s_movk_i32 s28, 0x18c
	s_movk_i32 s29, 0x100
	s_mov_b32 s30, 5
	s_movk_i32 s38, 0x18c
	s_mov_b32 s39, 2
	s_mov_b32 s44, 0
	s_mov_b32 s45, 9
	s_mov_b32 s46, 8
	s_branch .Lgm_common

; template <int EPI> ...
;     ...
;     } else {
;       const int hh = nt * 2 + wn;
;       const u16* P = (const u16*)(p.ws + O_P);
;       u16* Y = (u16*)(p.ws + O_Y);
;       const float* bs = (const float*)(p.ws + O_BS);
;       const int ch0 = hh * 64 + (lane & 31), ch1 = ch0 + 32;
;       const float gg0 = p.in[20][ch0], gg1 = p.in[20][ch1];
;       const float gb0 = p.in[21][ch0], gb1 = p.in[21][ch1];
;       const float mu0 = p.in[11][1536 + ch0], mu1 = p.in[11][1536 + ch1];
.Lgm_common:
	s_add_u32 s14, s96, 0x2e00100
	s_addc_u32 s15, s97, 0
	v_mov_b32_e32 v190, 0x1c040
	ds_read_b64 v[192:193], v190
	v_lshrrev_b32_e32 v191, 6, v128
	s_waitcnt lgkmcnt(0)
	v_readfirstlane_b32 s98, v192
	v_readfirstlane_b32 s99, v193
	v_readfirstlane_b32 s4, v191
	v_readlane_b32 s5, v254, 0
	s_nop 3
	s_cmp_ge_u32 s4, 4
	s_cbranch_scc1 .Lgm_producer
	v_and_b32_e32 v240, 63, v128
	v_lshrrev_b32_e32 v249, 4, v240
	v_and_b32_e32 v248, 15, v240
	v_bfe_u32 v238, v240, 1, 3
	v_lshlrev_b32_e32 v239, 7, v248
	s_lshl_b32 s8, s4, 13
	v_or_b32_e32 v241, 0, v249
	v_xor_b32_e32 v241, v241, v238
	v_lshlrev_b32_e32 v241, 4, v241
	v_add_u32_e32 v241, v241, v239
	v_add_u32_e32 v226, s8, v241
	v_add_u32_e32 v228, 0x8000, v241
	v_or_b32_e32 v241, 4, v249
	v_xor_b32_e32 v241, v241, v238
	v_lshlrev_b32_e32 v241, 4, v241
	v_add_u32_e32 v241, v241, v239
	v_add_u32_e32 v227, s8, v241
	v_add_u32_e32 v229, 0x8000, v241
	v_lshlrev_b32_e32 v242, 2, v248
	s_lshl_b32 s10, s4, 8
	s_add_u32 s10, s10, 0x24000
	v_add_u32_e32 v242, s10, v242
	s_mov_b32 s13, 0
	s_mov_b32 s31, 0xc000
	s_mov_b32 s35, 0xc000
	s_mov_b32 s34, 0xfffe8000
	s_mov_b32 s33, 0
	s_cmp_lg_u32 s30, 5
	s_cbranch_scc1 .Lgc_nopost
	v_readlane_b32 s8, v254, 18
	v_readlane_b32 s9, v254, 19
	s_nop 3
	s_sub_u32 s8, s8, 0x160
	s_subb_u32 s9, s9, 0
	s_load_dwordx2 s[0:1], s[8:9], 0x58
	s_load_dwordx2 s[2:3], s[8:9], 0xa0
	s_load_dwordx2 s[16:17], s[8:9], 0xa8
	s_load_dwordx2 s[20:21], s[8:9], 0x18
	s_waitcnt lgkmcnt(0)
	s_add_u32 s0, s0, 0x1800
	s_addc_u32 s1, s1, 0
.Lgc_nopost:
	s_waitcnt lgkmcnt(0)
	s_barrier
.Lgc_unit:
	s_cmp_ge_u32 s5, s38
	s_cbranch_scc1 .Lgm_exit
	s_mov_b32 s47, 0
	s_cmp_ge_u32 s5, s28
	s_cbranch_scc1 .Lgm_split_c
	s_mov_b32 s8, 0
	s_mov_b32 s9, s39
	s_mov_b32 s10, 0
	s_cmp_eq_u32 s27, 0
	s_cbranch_scc1 .Lgm_plain_c
	s_cmp_ge_u32 s5, s29
	s_cbranch_scc1 .Lgm_plain_c
	s_lshr_b32 s6, s5, 8
	s_and_b32 s7, s5, 0xff
	s_and_b32 s36, s7, 7
	s_lshr_b32 s37, s7, 3
	s_cmp_eq_u32 s27, 3
	s_cbranch_scc1 .Lgm_map8_c
	s_cmp_eq_u32 s27, 1
	s_cbranch_scc0 .Lgm_map16_c
	s_lshl_b32 s6, s6, 3
	s_lshr_b32 s7, s36, 2
	s_lshl_b32 s7, s7, 2
	s_add_u32 s6, s6, s7
	s_lshr_b32 s7, s37, 3
	s_add_u32 s6, s6, s7
	s_and_b32 s7, s36, 3
	s_lshl_b32 s7, s7, 3
	s_and_b32 s37, s37, 7
	s_add_u32 s7, s7, s37
	s_branch .Lgm_dec_done_c

; template <int EPI> ...
;     ...
;     if (EPI == EPI_SCALE || EPI == EPI_PLAIN || EPI == EPI_FF1) {
; #pragma unroll
;       for (int i = 0; i < 16; i++) {
;         const int rl = rbase + (i & 3) + 8 * (i >> 2);
;         const int row = m0 + rl;
;         float v0 = acc0[i], v1 = acc1[i];
;         if (EPI != EPI_PLAIN) { float rs = sRs[rl]; v0 *= rs; v1 *= rs; }
;         if (EPI == EPI_FF1) { v0 = fmaxf(v0, 0.f); v1 = fmaxf(v1, 0.f); v0 *= v0; v1 *= v1; }
;         outb[(size_t)row * ldo + c0] = f2bf(v0);
;         outb[(size_t)row * ldo + c1] = f2bf(v1);
;       }
.Lgc_tailT:
	v_mfma_f32_16x16x32_bf16 v[0:3], v[194:197], v[178:181], v[0:3]
	v_mfma_f32_16x16x32_bf16 v[4:7], v[198:201], v[178:181], v[4:7]
	v_mfma_f32_16x16x32_bf16 v[8:11], v[202:205], v[178:181], v[8:11]
	v_mfma_f32_16x16x32_bf16 v[12:15], v[206:209], v[178:181], v[12:15]
	v_mfma_f32_16x16x32_bf16 v[16:19], v[210:213], v[178:181], v[16:19]
	v_mfma_f32_16x16x32_bf16 v[20:23], v[214:217], v[178:181], v[20:23]
	v_mfma_f32_16x16x32_bf16 v[24:27], v[218:221], v[178:181], v[24:27]
	v_mfma_f32_16x16x32_bf16 v[28:31], v[222:225], v[178:181], v[28:31]
	v_mfma_f32_16x16x32_bf16 v[32:35], v[194:197], v[182:185], v[32:35]
	v_mfma_f32_16x16x32_bf16 v[36:39], v[198:201], v[182:185], v[36:39]
	v_mfma_f32_16x16x32_bf16 v[40:43], v[202:205], v[182:185], v[40:43]
	v_mfma_f32_16x16x32_bf16 v[44:47], v[206:209], v[182:185], v[44:47]
	v_mfma_f32_16x16x32_bf16 v[48:51], v[210:213], v[182:185], v[48:51]
	v_mfma_f32_16x16x32_bf16 v[52:55], v[214:217], v[182:185], v[52:55]
	v_mfma_f32_16x16x32_bf16 v[56:59], v[218:221], v[182:185], v[56:59]
	v_mfma_f32_16x16x32_bf16 v[60:63], v[222:225], v[182:185], v[60:63]
	v_mfma_f32_16x16x32_bf16 v[64:67], v[194:197], v[186:189], v[64:67]
	v_mfma_f32_16x16x32_bf16 v[68:71], v[198:201], v[186:189], v[68:71]
	v_mfma_f32_16x16x32_bf16 v[72:75], v[202:205], v[186:189], v[72:75]
	v_mfma_f32_16x16x32_bf16 v[76:79], v[206:209], v[186:189], v[76:79]
	v_mfma_f32_16x16x32_bf16 v[80:83], v[210:213], v[186:189], v[80:83]
	v_mfma_f32_16x16x32_bf16 v[84:87], v[214:217], v[186:189], v[84:87]
	v_mfma_f32_16x16x32_bf16 v[88:91], v[218:221], v[186:189], v[88:91]
	v_mfma_f32_16x16x32_bf16 v[92:95], v[222:225], v[186:189], v[92:95]
	v_mfma_f32_16x16x32_bf16 v[96:99], v[194:197], v[190:193], v[96:99]
	v_mfma_f32_16x16x32_bf16 v[100:103], v[198:201], v[190:193], v[100:103]
	v_mfma_f32_16x16x32_bf16 v[104:107], v[202:205], v[190:193], v[104:107]
	v_mfma_f32_16x16x32_bf16 v[108:111], v[206:209], v[190:193], v[108:111]
	v_mfma_f32_16x16x32_bf16 v[112:115], v[210:213], v[190:193], v[112:115]
	v_mfma_f32_16x16x32_bf16 v[116:119], v[214:217], v[190:193], v[116:119]
	v_mfma_f32_16x16x32_bf16 v[120:123], v[218:221], v[190:193], v[120:123]
	v_mfma_f32_16x16x32_bf16 v[124:127], v[222:225], v[190:193], v[124:127]
	s_cmp_eq_u32 s30, 3
	s_cbranch_scc1 .Lgc_epi_res
	s_cmp_eq_u32 s30, 5
	s_cbranch_scc1 .Lgc_epi_post
	s_lshl_b32 s11, s6, 8
	s_lshl_b32 s12, s4, 6
	s_add_u32 s11, s11, s12
	v_add_u32_e32 v238, s11, v248
	v_mul_lo_u32 v230, v238, s24
	s_lshl_b32 s11, s7, 7
	s_add_u32 s11, s11, s47
	v_and_b32_e32 v239, 1, v249
	v_lshrrev_b32_e32 v240, 1, v249
	v_lshlrev_b32_e32 v239, 4, v239
	v_lshl_add_u32 v239, v240, 3, v239
	v_add_u32_e32 v239, s11, v239
	v_lshlrev_b32_e32 v239, 1, v239
	v_add_u32_e32 v230, v230, v239
	s_lshl_b32 s11, s24, 4
	v_add_u32_e32 v231, s11, v230
	v_add_u32_e32 v232, s11, v231
	v_add_u32_e32 v233, s11, v232
	s_nop 7
	s_cmp_eq_u32 s30, 4
	s_cbranch_scc1 .Lgm_norelu
	v_add_u32_e32 v239, s33, v242
	ds_read_b32 v234, v239
	ds_read_b32 v235, v239 offset:64
	ds_read_b32 v236, v239 offset:128
	ds_read_b32 v237, v239 offset:192
	s_waitcnt lgkmcnt(0)
	v_mul_f32_e32 v0, v0, v234
	v_mul_f32_e32 v1, v1, v234
	v_mul_f32_e32 v2, v2, v234
	v_mul_f32_e32 v3, v3, v234
	v_mul_f32_e32 v4, v4, v234
	v_mul_f32_e32 v5, v5, v234
	v_mul_f32_e32 v6, v6, v234
	v_mul_f32_e32 v7, v7, v234
	v_mul_f32_e32 v8, v8, v234
	v_mul_f32_e32 v9, v9, v234
	v_mul_f32_e32 v10, v10, v234
	v_mul_f32_e32 v11, v11, v234
	v_mul_f32_e32 v12, v12, v234
	v_mul_f32_e32 v13, v13, v234
	v_mul_f32_e32 v14, v14, v234
	v_mul_f32_e32 v15, v15, v234
	v_mul_f32_e32 v16, v16, v234
	v_mul_f32_e32 v17, v17, v234
	v_mul_f32_e32 v18, v18, v234
	v_mul_f32_e32 v19, v19, v234
	v_mul_f32_e32 v20, v20, v234
	v_mul_f32_e32 v21, v21, v234
	v_mul_f32_e32 v22, v22, v234
	v_mul_f32_e32 v23, v23, v234
	v_mul_f32_e32 v24, v24, v234
	v_mul_f32_e32 v25, v25, v234
	v_mul_f32_e32 v26, v26, v234
	v_mul_f32_e32 v27, v27, v234
	v_mul_f32_e32 v28, v28, v234
	v_mul_f32_e32 v29, v29, v234
	v_mul_f32_e32 v30, v30, v234
	v_mul_f32_e32 v31, v31, v234
	v_mul_f32_e32 v32, v32, v235
	v_mul_f32_e32 v33, v33, v235
	v_mul_f32_e32 v34, v34, v235
	v_mul_f32_e32 v35, v35, v235
	v_mul_f32_e32 v36, v36, v235
	v_mul_f32_e32 v37, v37, v235
	v_mul_f32_e32 v38, v38, v235
	v_mul_f32_e32 v39, v39, v235
	v_mul_f32_e32 v40, v40, v235
	v_mul_f32_e32 v41, v41, v235
	v_mul_f32_e32 v42, v42, v235
	v_mul_f32_e32 v43, v43, v235
	v_mul_f32_e32 v44, v44, v235
	v_mul_f32_e32 v45, v45, v235
	v_mul_f32_e32 v46, v46, v235
	v_mul_f32_e32 v47, v47, v235
	v_mul_f32_e32 v48, v48, v235
	v_mul_f32_e32 v49, v49, v235
	v_mul_f32_e32 v50, v50, v235
	v_mul_f32_e32 v51, v51, v235
	v_mul_f32_e32 v52, v52, v235
	v_mul_f32_e32 v53, v53, v235
	v_mul_f32_e32 v54, v54, v235
	v_mul_f32_e32 v55, v55, v235
	v_mul_f32_e32 v56, v56, v235
	v_mul_f32_e32 v57, v57, v235
	v_mul_f32_e32 v58, v58, v235
	v_mul_f32_e32 v59, v59, v235
	v_mul_f32_e32 v60, v60, v235
	v_mul_f32_e32 v61, v61, v235
	v_mul_f32_e32 v62, v62, v235
	v_mul_f32_e32 v63, v63, v235
	v_mul_f32_e32 v64, v64, v236
	v_mul_f32_e32 v65, v65, v236
	v_mul_f32_e32 v66, v66, v236
	v_mul_f32_e32 v67, v67, v236
	v_mul_f32_e32 v68, v68, v236
	v_mul_f32_e32 v69, v69, v236
	v_mul_f32_e32 v70, v70, v236
	v_mul_f32_e32 v71, v71, v236
	v_mul_f32_e32 v72, v72, v236
	v_mul_f32_e32 v73, v73, v236
	v_mul_f32_e32 v74, v74, v236
	v_mul_f32_e32 v75, v75, v236
	v_mul_f32_e32 v76, v76, v236
	v_mul_f32_e32 v77, v77, v236
	v_mul_f32_e32 v78, v78, v236
	v_mul_f32_e32 v79, v79, v236
	v_mul_f32_e32 v80, v80, v236
	v_mul_f32_e32 v81, v81, v236
	v_mul_f32_e32 v82, v82, v236
	v_mul_f32_e32 v83, v83, v236
	v_mul_f32_e32 v84, v84, v236
	v_mul_f32_e32 v85, v85, v236
	v_mul_f32_e32 v86, v86, v236
	v_mul_f32_e32 v87, v87, v236
	v_mul_f32_e32 v88, v88, v236
	v_mul_f32_e32 v89, v89, v236
	v_mul_f32_e32 v90, v90, v236
	v_mul_f32_e32 v91, v91, v236
	v_mul_f32_e32 v92, v92, v236
	v_mul_f32_e32 v93, v93, v236
	v_mul_f32_e32 v94, v94, v236
	v_mul_f32_e32 v95, v95, v236
	v_mul_f32_e32 v96, v96, v237
	v_mul_f32_e32 v97, v97, v237
	v_mul_f32_e32 v98, v98, v237
	v_mul_f32_e32 v99, v99, v237
	v_mul_f32_e32 v100, v100, v237
	v_mul_f32_e32 v101, v101, v237
	v_mul_f32_e32 v102, v102, v237
	v_mul_f32_e32 v103, v103, v237
	v_mul_f32_e32 v104, v104, v237
	v_mul_f32_e32 v105, v105, v237
	v_mul_f32_e32 v106, v106, v237
	v_mul_f32_e32 v107, v107, v237
	v_mul_f32_e32 v108, v108, v237
	v_mul_f32_e32 v109, v109, v237
	v_mul_f32_e32 v110, v110, v237
	v_mul_f32_e32 v111, v111, v237
	v_mul_f32_e32 v112, v112, v237
	v_mul_f32_e32 v113, v113, v237
	v_mul_f32_e32 v114, v114, v237
	v_mul_f32_e32 v115, v115, v237
	v_mul_f32_e32 v116, v116, v237
	v_mul_f32_e32 v117, v117, v237
	v_mul_f32_e32 v118, v118, v237
	v_mul_f32_e32 v119, v119, v237
	v_mul_f32_e32 v120, v120, v237
	v_mul_f32_e32 v121, v121, v237
	v_mul_f32_e32 v122, v122, v237
	v_mul_f32_e32 v123, v123, v237
	v_mul_f32_e32 v124, v124, v237
	v_mul_f32_e32 v125, v125, v237
	v_mul_f32_e32 v126, v126, v237
	v_mul_f32_e32 v127, v127, v237
	s_cmp_eq_u32 s30, 0
	s_cbranch_scc1 .Lgm_norelu
; template <int EPI> ...
;     ...
;         if (EPI != EPI_PLAIN) { float rs = sRs[rl]; v0 *= rs; v1 *= rs; }
;         if (EPI == EPI_FF1) { v0 = fmaxf(v0, 0.f); v1 = fmaxf(v1, 0.f); v0 *= v0; v1 *= v1; }
;         outb[(size_t)row * ldo + c0] = f2bf(v0);
	v_max_f32_e32 v0, 0, v0
	v_mul_f32_e32 v0, v0, v0
	v_max_f32_e32 v1, 0, v1
	v_mul_f32_e32 v1, v1, v1
	v_max_f32_e32 v2, 0, v2
	v_mul_f32_e32 v2, v2, v2
	v_max_f32_e32 v3, 0, v3
	v_mul_f32_e32 v3, v3, v3
	v_max_f32_e32 v4, 0, v4
	v_mul_f32_e32 v4, v4, v4
	v_max_f32_e32 v5, 0, v5
	v_mul_f32_e32 v5, v5, v5
	v_max_f32_e32 v6, 0, v6
	v_mul_f32_e32 v6, v6, v6
	v_max_f32_e32 v7, 0, v7
	v_mul_f32_e32 v7, v7, v7
	v_max_f32_e32 v8, 0, v8
	v_mul_f32_e32 v8, v8, v8
	v_max_f32_e32 v9, 0, v9
	v_mul_f32_e32 v9, v9, v9
	v_max_f32_e32 v10, 0, v10
	v_mul_f32_e32 v10, v10, v10
	v_max_f32_e32 v11, 0, v11
	v_mul_f32_e32 v11, v11, v11
	v_max_f32_e32 v12, 0, v12
	v_mul_f32_e32 v12, v12, v12
	v_max_f32_e32 v13, 0, v13
	v_mul_f32_e32 v13, v13, v13
	v_max_f32_e32 v14, 0, v14
	v_mul_f32_e32 v14, v14, v14
	v_max_f32_e32 v15, 0, v15
	v_mul_f32_e32 v15, v15, v15
	v_max_f32_e32 v16, 0, v16
	v_mul_f32_e32 v16, v16, v16
	v_max_f32_e32 v17, 0, v17
	v_mul_f32_e32 v17, v17, v17
	v_max_f32_e32 v18, 0, v18
	v_mul_f32_e32 v18, v18, v18
	v_max_f32_e32 v19, 0, v19
	v_mul_f32_e32 v19, v19, v19
	v_max_f32_e32 v20, 0, v20
	v_mul_f32_e32 v20, v20, v20
	v_max_f32_e32 v21, 0, v21
	v_mul_f32_e32 v21, v21, v21
	v_max_f32_e32 v22, 0, v22
	v_mul_f32_e32 v22, v22, v22
	v_max_f32_e32 v23, 0, v23
	v_mul_f32_e32 v23, v23, v23
	v_max_f32_e32 v24, 0, v24
	v_mul_f32_e32 v24, v24, v24
	v_max_f32_e32 v25, 0, v25
	v_mul_f32_e32 v25, v25, v25
	v_max_f32_e32 v26, 0, v26
	v_mul_f32_e32 v26, v26, v26
	v_max_f32_e32 v27, 0, v27
	v_mul_f32_e32 v27, v27, v27
	v_max_f32_e32 v28, 0, v28
	v_mul_f32_e32 v28, v28, v28
	v_max_f32_e32 v29, 0, v29
	v_mul_f32_e32 v29, v29, v29
	v_max_f32_e32 v30, 0, v30
	v_mul_f32_e32 v30, v30, v30
	v_max_f32_e32 v31, 0, v31
	v_mul_f32_e32 v31, v31, v31
	v_max_f32_e32 v32, 0, v32
	v_mul_f32_e32 v32, v32, v32
	v_max_f32_e32 v33, 0, v33
	v_mul_f32_e32 v33, v33, v33
	v_max_f32_e32 v34, 0, v34
	v_mul_f32_e32 v34, v34, v34
	v_max_f32_e32 v35, 0, v35
	v_mul_f32_e32 v35, v35, v35
	v_max_f32_e32 v36, 0, v36
	v_mul_f32_e32 v36, v36, v36
	v_max_f32_e32 v37, 0, v37
	v_mul_f32_e32 v37, v37, v37
	v_max_f32_e32 v38, 0, v38
	v_mul_f32_e32 v38, v38, v38
	v_max_f32_e32 v39, 0, v39
	v_mul_f32_e32 v39, v39, v39
	v_max_f32_e32 v40, 0, v40
	v_mul_f32_e32 v40, v40, v40
	v_max_f32_e32 v41, 0, v41
	v_mul_f32_e32 v41, v41, v41
	v_max_f32_e32 v42, 0, v42
	v_mul_f32_e32 v42, v42, v42
	v_max_f32_e32 v43, 0, v43
	v_mul_f32_e32 v43, v43, v43
	v_max_f32_e32 v44, 0, v44
	v_mul_f32_e32 v44, v44, v44
	v_max_f32_e32 v45, 0, v45
	v_mul_f32_e32 v45, v45, v45
	v_max_f32_e32 v46, 0, v46
	v_mul_f32_e32 v46, v46, v46
	v_max_f32_e32 v47, 0, v47
	v_mul_f32_e32 v47, v47, v47
	v_max_f32_e32 v48, 0, v48
	v_mul_f32_e32 v48, v48, v48
	v_max_f32_e32 v49, 0, v49
	v_mul_f32_e32 v49, v49, v49
	v_max_f32_e32 v50, 0, v50
	v_mul_f32_e32 v50, v50, v50
	v_max_f32_e32 v51, 0, v51
	v_mul_f32_e32 v51, v51, v51
	v_max_f32_e32 v52, 0, v52
	v_mul_f32_e32 v52, v52, v52
	v_max_f32_e32 v53, 0, v53
	v_mul_f32_e32 v53, v53, v53
	v_max_f32_e32 v54, 0, v54
	v_mul_f32_e32 v54, v54, v54
	v_max_f32_e32 v55, 0, v55
	v_mul_f32_e32 v55, v55, v55
	v_max_f32_e32 v56, 0, v56
	v_mul_f32_e32 v56, v56, v56
	v_max_f32_e32 v57, 0, v57
	v_mul_f32_e32 v57, v57, v57
	v_max_f32_e32 v58, 0, v58
	v_mul_f32_e32 v58, v58, v58
	v_max_f32_e32 v59, 0, v59
	v_mul_f32_e32 v59, v59, v59
	v_max_f32_e32 v60, 0, v60
	v_mul_f32_e32 v60, v60, v60
	v_max_f32_e32 v61, 0, v61
	v_mul_f32_e32 v61, v61, v61
	v_max_f32_e32 v62, 0, v62
	v_mul_f32_e32 v62, v62, v62
	v_max_f32_e32 v63, 0, v63
	v_mul_f32_e32 v63, v63, v63
	v_max_f32_e32 v64, 0, v64
	v_mul_f32_e32 v64, v64, v64
	v_max_f32_e32 v65, 0, v65
; template <int EPI> ...
;     ...
;         if (EPI != EPI_PLAIN) { float rs = sRs[rl]; v0 *= rs; v1 *= rs; }
;         if (EPI == EPI_FF1) { v0 = fmaxf(v0, 0.f); v1 = fmaxf(v1, 0.f); v0 *= v0; v1 *= v1; }
;         outb[(size_t)row * ldo + c0] = f2bf(v0);
	v_mul_f32_e32 v65, v65, v65
	v_max_f32_e32 v66, 0, v66
	v_mul_f32_e32 v66, v66, v66
	v_max_f32_e32 v67, 0, v67
	v_mul_f32_e32 v67, v67, v67
	v_max_f32_e32 v68, 0, v68
	v_mul_f32_e32 v68, v68, v68
	v_max_f32_e32 v69, 0, v69
	v_mul_f32_e32 v69, v69, v69
	v_max_f32_e32 v70, 0, v70
	v_mul_f32_e32 v70, v70, v70
	v_max_f32_e32 v71, 0, v71
	v_mul_f32_e32 v71, v71, v71
	v_max_f32_e32 v72, 0, v72
	v_mul_f32_e32 v72, v72, v72
	v_max_f32_e32 v73, 0, v73
	v_mul_f32_e32 v73, v73, v73
	v_max_f32_e32 v74, 0, v74
	v_mul_f32_e32 v74, v74, v74
	v_max_f32_e32 v75, 0, v75
	v_mul_f32_e32 v75, v75, v75
	v_max_f32_e32 v76, 0, v76
	v_mul_f32_e32 v76, v76, v76
	v_max_f32_e32 v77, 0, v77
	v_mul_f32_e32 v77, v77, v77
	v_max_f32_e32 v78, 0, v78
	v_mul_f32_e32 v78, v78, v78
	v_max_f32_e32 v79, 0, v79
	v_mul_f32_e32 v79, v79, v79
	v_max_f32_e32 v80, 0, v80
	v_mul_f32_e32 v80, v80, v80
	v_max_f32_e32 v81, 0, v81
	v_mul_f32_e32 v81, v81, v81
	v_max_f32_e32 v82, 0, v82
	v_mul_f32_e32 v82, v82, v82
	v_max_f32_e32 v83, 0, v83
	v_mul_f32_e32 v83, v83, v83
	v_max_f32_e32 v84, 0, v84
	v_mul_f32_e32 v84, v84, v84
	v_max_f32_e32 v85, 0, v85
	v_mul_f32_e32 v85, v85, v85
	v_max_f32_e32 v86, 0, v86
	v_mul_f32_e32 v86, v86, v86
	v_max_f32_e32 v87, 0, v87
	v_mul_f32_e32 v87, v87, v87
	v_max_f32_e32 v88, 0, v88
	v_mul_f32_e32 v88, v88, v88
	v_max_f32_e32 v89, 0, v89
	v_mul_f32_e32 v89, v89, v89
	v_max_f32_e32 v90, 0, v90
	v_mul_f32_e32 v90, v90, v90
	v_max_f32_e32 v91, 0, v91
	v_mul_f32_e32 v91, v91, v91
	v_max_f32_e32 v92, 0, v92
	v_mul_f32_e32 v92, v92, v92
	v_max_f32_e32 v93, 0, v93
	v_mul_f32_e32 v93, v93, v93
	v_max_f32_e32 v94, 0, v94
	v_mul_f32_e32 v94, v94, v94
	v_max_f32_e32 v95, 0, v95
	v_mul_f32_e32 v95, v95, v95
	v_max_f32_e32 v96, 0, v96
	v_mul_f32_e32 v96, v96, v96
	v_max_f32_e32 v97, 0, v97
	v_mul_f32_e32 v97, v97, v97
	v_max_f32_e32 v98, 0, v98
	v_mul_f32_e32 v98, v98, v98
	v_max_f32_e32 v99, 0, v99
	v_mul_f32_e32 v99, v99, v99
	v_max_f32_e32 v100, 0, v100
	v_mul_f32_e32 v100, v100, v100
	v_max_f32_e32 v101, 0, v101
	v_mul_f32_e32 v101, v101, v101
	v_max_f32_e32 v102, 0, v102
	v_mul_f32_e32 v102, v102, v102
	v_max_f32_e32 v103, 0, v103
	v_mul_f32_e32 v103, v103, v103
	v_max_f32_e32 v104, 0, v104
	v_mul_f32_e32 v104, v104, v104
	v_max_f32_e32 v105, 0, v105
	v_mul_f32_e32 v105, v105, v105
	v_max_f32_e32 v106, 0, v106
	v_mul_f32_e32 v106, v106, v106
	v_max_f32_e32 v107, 0, v107
	v_mul_f32_e32 v107, v107, v107
	v_max_f32_e32 v108, 0, v108
	v_mul_f32_e32 v108, v108, v108
	v_max_f32_e32 v109, 0, v109
	v_mul_f32_e32 v109, v109, v109
	v_max_f32_e32 v110, 0, v110
	v_mul_f32_e32 v110, v110, v110
	v_max_f32_e32 v111, 0, v111
	v_mul_f32_e32 v111, v111, v111
	v_max_f32_e32 v112, 0, v112
	v_mul_f32_e32 v112, v112, v112
	v_max_f32_e32 v113, 0, v113
	v_mul_f32_e32 v113, v113, v113
	v_max_f32_e32 v114, 0, v114
	v_mul_f32_e32 v114, v114, v114
	v_max_f32_e32 v115, 0, v115
	v_mul_f32_e32 v115, v115, v115
	v_max_f32_e32 v116, 0, v116
	v_mul_f32_e32 v116, v116, v116
	v_max_f32_e32 v117, 0, v117
	v_mul_f32_e32 v117, v117, v117
	v_max_f32_e32 v118, 0, v118
	v_mul_f32_e32 v118, v118, v118
	v_max_f32_e32 v119, 0, v119
	v_mul_f32_e32 v119, v119, v119
	v_max_f32_e32 v120, 0, v120
	v_mul_f32_e32 v120, v120, v120
	v_max_f32_e32 v121, 0, v121
	v_mul_f32_e32 v121, v121, v121
	v_max_f32_e32 v122, 0, v122
	v_mul_f32_e32 v122, v122, v122
	v_max_f32_e32 v123, 0, v123
	v_mul_f32_e32 v123, v123, v123
	v_max_f32_e32 v124, 0, v124
	v_mul_f32_e32 v124, v124, v124
	v_max_f32_e32 v125, 0, v125
	v_mul_f32_e32 v125, v125, v125
	v_max_f32_e32 v126, 0, v126
	v_mul_f32_e32 v126, v126, v126
	v_max_f32_e32 v127, 0, v127
	v_mul_f32_e32 v127, v127, v127

; __device__ __forceinline__ float bf2f(u16 h) { return __uint_as_float(((unsigned)h) << 16); }
; __device__ __forceinline__ float prevP(const Params& p, const u16* P, int row, int c) {
;   const int rp = row > 0 ? row - 1 : 0;
;   float v = bf2f(P[(size_t)rp * 2816 + 256 + c]);
;   const bool start = (row < NP) ? ((row & 2047) == 0) : (((row - NP) & 3) == 0);
;   if (start) v = (row < NP) ? 0.f : p.in[3][(size_t)((row - NP) >> 2) * 2560 + c];
;   return v;
; template <int EPI> ...
;     ...
;       const int hh = nt * 2 + wn;
;       const u16* P = (const u16*)(p.ws + O_P);
;       u16* Y = (u16*)(p.ws + O_Y);
;       const float* bs = (const float*)(p.ws + O_BS);
;       const int ch0 = hh * 64 + (lane & 31), ch1 = ch0 + 32;
;       const float gg0 = p.in[20][ch0], gg1 = p.in[20][ch1];
;       const float gb0 = p.in[21][ch0], gb1 = p.in[21][ch1];
;       const float mu0 = p.in[11][1536 + ch0], mu1 = p.in[11][1536 + ch1];
; #pragma unroll 16
;       for (int i = 0; i < 16; i++) {
;         const int rl = rbase + (i & 3) + 8 * (i >> 2);
;         const int row = m0 + rl;
;         float o0 = bf2f(Y[(size_t)row * 1024 + 256 + ch0]);
;         float o1 = bf2f(Y[(size_t)row * 1024 + 256 + ch1]);
;         float mean = hsum32(o0 + o1) * (1.0f / 64.0f);
;         float d0 = o0 - mean, d1 = o1 - mean;
;         float var = hsum32(d0 * d0 + d1 * d1) * (1.0f / 64.0f);
.Lgc_epi_post:
	s_lshl_b32 s11, s6, 8
	s_lshl_b32 s12, s4, 6
	s_add_u32 s11, s11, s12
	v_add_u32_e32 v238, s11, v248
	s_lshl_b32 s11, s7, 7
	v_lshl_add_u32 v239, v249, 3, s11
	v_lshlrev_b32_e32 v233, 2, v239
	v_lshlrev_b32_e32 v230, 11, v238
	v_lshl_add_u32 v230, v239, 1, v230
	v_add_u32_e32 v230, 0x200, v230
	v_mul_u32_u24_e32 v231, 0x1600, v238
	v_lshl_add_u32 v231, v239, 1, v231
	v_add_u32_e32 v231, 0x7108f00, v231
	v_mul_u32_u24_e32 v232, 0xc0, v238
	s_lshl_b32 s11, s7, 5
	s_add_u32 s11, s11, 0x47c8108
	v_add_u32_e32 v232, s11, v232
	s_cmp_ge_u32 s6, 64
	s_cbranch_scc1 .Lpo_sample
	global_load_dwordx4 v[130:133], v233, s[2:3] offset:0
	global_load_dwordx4 v[134:137], v233, s[2:3] offset:16
	global_load_dwordx4 v[138:141], v233, s[2:3] offset:128
	global_load_dwordx4 v[142:145], v233, s[2:3] offset:144
	global_load_dwordx4 v[146:149], v233, s[16:17] offset:0
	global_load_dwordx4 v[150:153], v233, s[16:17] offset:16
	global_load_dwordx4 v[154:157], v233, s[16:17] offset:128
	global_load_dwordx4 v[158:161], v233, s[16:17] offset:144
	global_load_dwordx4 v[162:165], v233, s[0:1] offset:0
	global_load_dwordx4 v[166:169], v233, s[0:1] offset:16
	global_load_dwordx4 v[170:173], v233, s[0:1] offset:128
	global_load_dwordx4 v[174:177], v233, s[0:1] offset:144
	v_add_u32_e32 v236, 0x0, v230
	v_add_u32_e32 v237, 0x0, v231
	v_subrev_u32_e32 v240, 0x1600, v237
	global_load_dwordx4 v[178:181], v236, s[22:23] offset:0
	global_load_dwordx4 v[182:185], v236, s[22:23] offset:64
	global_load_dwordx4 v[186:189], v237, s[96:97] offset:0
	global_load_dwordx4 v[190:193], v237, s[96:97] offset:64
	global_load_dwordx4 v[194:197], v240, s[96:97] offset:0
	global_load_dwordx4 v[198:201], v240, s[96:97] offset:64
	v_add_u32_e32 v236, 0x0, v232
	s_nop 0
	global_load_dword v234, v236, s[96:97] offset:0
	v_add_u32_e32 v236, 0x8000, v230
	v_add_u32_e32 v237, 0x16000, v231
	v_subrev_u32_e32 v240, 0x1600, v237
	global_load_dwordx4 v[202:205], v236, s[22:23] offset:0
	global_load_dwordx4 v[206:209], v236, s[22:23] offset:64
	global_load_dwordx4 v[210:213], v237, s[96:97] offset:0
	global_load_dwordx4 v[214:217], v237, s[96:97] offset:64
	global_load_dwordx4 v[218:221], v240, s[96:97] offset:0
	global_load_dwordx4 v[222:225], v240, s[96:97] offset:64
	v_add_u32_e32 v236, 0xc00, v232
	s_nop 0
	global_load_dword v235, v236, s[96:97] offset:0
	s_waitcnt vmcnt(14)
	s_waitcnt vmcnt(7)
	s_and_b32 s18, s6, 7
	s_or_b32 s18, s18, s4
	s_cmp_lg_u32 s18, 0
	s_cbranch_scc1 .Lpo_nostart_p0
	v_cmp_eq_u32_e32 vcc, 0, v248
	s_nop 1
	v_cndmask_b32_e64 v194, v194, 0, vcc
	v_cndmask_b32_e64 v195, v195, 0, vcc
	v_cndmask_b32_e64 v196, v196, 0, vcc
	v_cndmask_b32_e64 v197, v197, 0, vcc
	v_cndmask_b32_e64 v198, v198, 0, vcc
	v_cndmask_b32_e64 v199, v199, 0, vcc
	v_cndmask_b32_e64 v200, v200, 0, vcc
	v_cndmask_b32_e64 v201, v201, 0, vcc
.Lpo_nostart_p0:
	v_lshlrev_b32_e32 v240, 16, v178
	v_and_b32_e32 v241, 0xffff0000, v178
	v_add_f32_e32 v244, v240, v241
	v_lshlrev_b32_e32 v240, 16, v179
	v_and_b32_e32 v241, 0xffff0000, v179
	v_add_f32_e32 v244, v244, v240
	v_add_f32_e32 v244, v244, v241
	v_lshlrev_b32_e32 v240, 16, v180
	v_and_b32_e32 v241, 0xffff0000, v180
	v_add_f32_e32 v244, v244, v240
	v_add_f32_e32 v244, v244, v241
	v_lshlrev_b32_e32 v240, 16, v181
	v_and_b32_e32 v241, 0xffff0000, v181
	v_add_f32_e32 v244, v244, v240
	v_add_f32_e32 v244, v244, v241
	v_lshlrev_b32_e32 v240, 16, v182
	v_and_b32_e32 v241, 0xffff0000, v182
	v_add_f32_e32 v244, v244, v240
	v_add_f32_e32 v244, v244, v241
	v_lshlrev_b32_e32 v240, 16, v183
	v_and_b32_e32 v241, 0xffff0000, v183
	v_add_f32_e32 v244, v244, v240
	v_add_f32_e32 v244, v244, v241
	v_lshlrev_b32_e32 v240, 16, v184
	v_and_b32_e32 v241, 0xffff0000, v184
	v_add_f32_e32 v244, v244, v240
	v_add_f32_e32 v244, v244, v241
	v_lshlrev_b32_e32 v240, 16, v185
	v_and_b32_e32 v241, 0xffff0000, v185
	v_add_f32_e32 v244, v244, v240
	v_add_f32_e32 v244, v244, v241
	v_mov_b32_e32 v240, v244
	s_nop 1
	v_permlane16_swap_b32_e32 v240, v244
	v_add_f32_e32 v244, v244, v240
	v_mov_b32_e32 v240, v244
	s_nop 1
	v_permlane32_swap_b32_e32 v240, v244
	v_add_f32_e32 v244, v244, v240
	v_mul_f32_e32 v238, 0x3c800000, v244
	v_lshlrev_b32_e32 v240, 16, v178
	v_and_b32_e32 v241, 0xffff0000, v178
	v_sub_f32_e32 v240, v240, v238
	v_sub_f32_e32 v241, v241, v238
	v_mul_f32_e32 v245, v240, v240
	v_fmac_f32_e32 v245, v241, v241
	v_lshlrev_b32_e32 v240, 16, v179
	v_and_b32_e32 v241, 0xffff0000, v179
	v_sub_f32_e32 v240, v240, v238
	v_sub_f32_e32 v241, v241, v238
	v_fmac_f32_e32 v245, v240, v240
	v_fmac_f32_e32 v245, v241, v241
	v_lshlrev_b32_e32 v240, 16, v180
	v_and_b32_e32 v241, 0xffff0000, v180
	v_sub_f32_e32 v240, v240, v238
	v_sub_f32_e32 v241, v241, v238
	v_fmac_f32_e32 v245, v240, v240
	v_fmac_f32_e32 v245, v241, v241
	v_lshlrev_b32_e32 v240, 16, v181
	v_and_b32_e32 v241, 0xffff0000, v181
	v_sub_f32_e32 v240, v240, v238
	v_sub_f32_e32 v241, v241, v238
	v_fmac_f32_e32 v245, v240, v240
	v_fmac_f32_e32 v245, v241, v241
	v_lshlrev_b32_e32 v240, 16, v182
	v_and_b32_e32 v241, 0xffff0000, v182
	v_sub_f32_e32 v240, v240, v238
	v_sub_f32_e32 v241, v241, v238
	v_fmac_f32_e32 v245, v240, v240
	v_fmac_f32_e32 v245, v241, v241
	v_lshlrev_b32_e32 v240, 16, v183
	v_and_b32_e32 v241, 0xffff0000, v183
	v_sub_f32_e32 v240, v240, v238
	v_sub_f32_e32 v241, v241, v238
	v_fmac_f32_e32 v245, v240, v240
	v_fmac_f32_e32 v245, v241, v241
	v_lshlrev_b32_e32 v240, 16, v184
	v_and_b32_e32 v241, 0xffff0000, v184
	v_sub_f32_e32 v240, v240, v238
	v_sub_f32_e32 v241, v241, v238
	v_fmac_f32_e32 v245, v240, v240
	v_fmac_f32_e32 v245, v241, v241
	v_lshlrev_b32_e32 v240, 16, v185
	v_and_b32_e32 v241, 0xffff0000, v185
; __device__ __forceinline__ float bf2f(u16 h) { return __uint_as_float(((unsigned)h) << 16); }
; template <int EPI> ...
;     ...
;       for (int i = 0; i < 16; i++) {
;         const int rl = rbase + (i & 3) + 8 * (i >> 2);
;         const int row = m0 + rl;
;         float o0 = bf2f(Y[(size_t)row * 1024 + 256 + ch0]);
;         float o1 = bf2f(Y[(size_t)row * 1024 + 256 + ch1]);
;         float mean = hsum32(o0 + o1) * (1.0f / 64.0f);
;         float d0 = o0 - mean, d1 = o1 - mean;
;         float var = hsum32(d0 * d0 + d1 * d1) * (1.0f / 64.0f);
;         float rstd = rsqrtf(var + 64e-5f);
;         float pv0 = bf2f(P[(size_t)row * 2816 + 256 + 1536 + ch0]);
;         float pv1 = bf2f(P[(size_t)row * 2816 + 256 + 1536 + ch1]);
;         float pp0 = prevP(p, P, row, 1536 + ch0), pp1 = prevP(p, P, row, 1536 + ch1);
;         float vv0 = pv0 + (pp0 - pv0) * mu0, vv1 = pv1 + (pp1 - pv1) * mu1;
;         float b = bs[((size_t)row * 12 + hh) * 4 + 2];
;         float y0 = (d0 * rstd * gg0 + gb0 + b * vv0) * acc0[i];
;         float y1 = (d1 * rstd * gg1 + gb1 + b * vv1) * acc1[i];
;         Y[(size_t)row * 1024 + 256 + ch0] = f2bf(y0);
;         Y[(size_t)row * 1024 + 256 + ch1] = f2bf(y1);
;       }
	v_sub_f32_e32 v240, v240, v238
	v_sub_f32_e32 v241, v241, v238
	v_fmac_f32_e32 v245, v240, v240
	v_fmac_f32_e32 v245, v241, v241
	v_mov_b32_e32 v240, v245
	s_nop 1
	v_permlane16_swap_b32_e32 v240, v245
	v_add_f32_e32 v245, v245, v240
	v_mov_b32_e32 v240, v245
	s_nop 1
	v_permlane32_swap_b32_e32 v240, v245
	v_add_f32_e32 v245, v245, v240
	v_mov_b32_e32 v240, 0x3a27c5ac
	v_fmamk_f32 v245, v245, 0x3c800000, v240
	v_rsq_f32_e32 v239, v245
	v_add_u32_e32 v247, 0x0, v230
	v_lshlrev_b32_e32 v240, 16, v178
	v_and_b32_e32 v244, 0xffff0000, v178
	v_sub_f32_e32 v240, v240, v238
	v_sub_f32_e32 v244, v244, v238
	v_mul_f32_e32 v240, v240, v239
	v_mul_f32_e32 v244, v244, v239
	v_fma_f32 v240, v130, v240, v146
	v_fma_f32 v244, v131, v244, v147
	v_lshlrev_b32_e32 v241, 16, v186
	v_and_b32_e32 v245, 0xffff0000, v186
	v_lshlrev_b32_e32 v243, 16, v194
	v_and_b32_e32 v246, 0xffff0000, v194
	v_sub_f32_e32 v243, v243, v241
	v_sub_f32_e32 v246, v246, v245
	v_fmac_f32_e32 v241, v162, v243
	v_fmac_f32_e32 v245, v163, v246
	v_fmac_f32_e32 v240, v234, v241
	v_fmac_f32_e32 v244, v234, v245
	v_mul_f32_e32 v0, v0, v240
	v_mul_f32_e32 v1, v1, v244
	v_lshlrev_b32_e32 v240, 16, v179
	v_and_b32_e32 v244, 0xffff0000, v179
	v_sub_f32_e32 v240, v240, v238
	v_sub_f32_e32 v244, v244, v238
	v_mul_f32_e32 v240, v240, v239
	v_mul_f32_e32 v244, v244, v239
	v_fma_f32 v240, v132, v240, v148
	v_fma_f32 v244, v133, v244, v149
	v_lshlrev_b32_e32 v241, 16, v187
	v_and_b32_e32 v245, 0xffff0000, v187
	v_lshlrev_b32_e32 v243, 16, v195
	v_and_b32_e32 v246, 0xffff0000, v195
	v_sub_f32_e32 v243, v243, v241
	v_sub_f32_e32 v246, v246, v245
	v_fmac_f32_e32 v241, v164, v243
	v_fmac_f32_e32 v245, v165, v246
	v_fmac_f32_e32 v240, v234, v241
	v_fmac_f32_e32 v244, v234, v245
	v_mul_f32_e32 v2, v2, v240
	v_mul_f32_e32 v3, v3, v244
	v_lshlrev_b32_e32 v240, 16, v180
	v_and_b32_e32 v244, 0xffff0000, v180
	v_sub_f32_e32 v240, v240, v238
	v_sub_f32_e32 v244, v244, v238
	v_mul_f32_e32 v240, v240, v239
	v_mul_f32_e32 v244, v244, v239
	v_fma_f32 v240, v134, v240, v150
	v_fma_f32 v244, v135, v244, v151
	v_lshlrev_b32_e32 v241, 16, v188
	v_and_b32_e32 v245, 0xffff0000, v188
	v_lshlrev_b32_e32 v243, 16, v196
	v_and_b32_e32 v246, 0xffff0000, v196
	v_sub_f32_e32 v243, v243, v241
	v_sub_f32_e32 v246, v246, v245
	v_fmac_f32_e32 v241, v166, v243
	v_fmac_f32_e32 v245, v167, v246
	v_fmac_f32_e32 v240, v234, v241
	v_fmac_f32_e32 v244, v234, v245
	v_mul_f32_e32 v4, v4, v240
	v_mul_f32_e32 v5, v5, v244
	v_lshlrev_b32_e32 v240, 16, v181
	v_and_b32_e32 v244, 0xffff0000, v181
	v_sub_f32_e32 v240, v240, v238
	v_sub_f32_e32 v244, v244, v238
	v_mul_f32_e32 v240, v240, v239
	v_mul_f32_e32 v244, v244, v239
	v_fma_f32 v240, v136, v240, v152
	v_fma_f32 v244, v137, v244, v153
	v_lshlrev_b32_e32 v241, 16, v189
	v_and_b32_e32 v245, 0xffff0000, v189
	v_lshlrev_b32_e32 v243, 16, v197
	v_and_b32_e32 v246, 0xffff0000, v197
	v_sub_f32_e32 v243, v243, v241
	v_sub_f32_e32 v246, v246, v245
	v_fmac_f32_e32 v241, v168, v243
	v_fmac_f32_e32 v245, v169, v246
	v_fmac_f32_e32 v240, v234, v241
	v_fmac_f32_e32 v244, v234, v245
	v_mul_f32_e32 v6, v6, v240
	v_mul_f32_e32 v7, v7, v244
	v_cvt_pk_bf16_f32 v0, v0, v1
	v_cvt_pk_bf16_f32 v1, v2, v3
	v_cvt_pk_bf16_f32 v2, v4, v5
	v_cvt_pk_bf16_f32 v3, v6, v7
	global_store_dwordx4 v247, v[0:3], s[22:23] offset:0
	v_lshlrev_b32_e32 v240, 16, v182
	v_and_b32_e32 v244, 0xffff0000, v182
	v_sub_f32_e32 v240, v240, v238
	v_sub_f32_e32 v244, v244, v238
	v_mul_f32_e32 v240, v240, v239
	v_mul_f32_e32 v244, v244, v239
	v_fma_f32 v240, v138, v240, v154
	v_fma_f32 v244, v139, v244, v155
	v_lshlrev_b32_e32 v241, 16, v190
	v_and_b32_e32 v245, 0xffff0000, v190
	v_lshlrev_b32_e32 v243, 16, v198
	v_and_b32_e32 v246, 0xffff0000, v198
	v_sub_f32_e32 v243, v243, v241
	v_sub_f32_e32 v246, v246, v245
	v_fmac_f32_e32 v241, v170, v243
	v_fmac_f32_e32 v245, v171, v246
	v_fmac_f32_e32 v240, v234, v241
	v_fmac_f32_e32 v244, v234, v245
	v_mul_f32_e32 v8, v8, v240
	v_mul_f32_e32 v9, v9, v244
	v_lshlrev_b32_e32 v240, 16, v183
	v_and_b32_e32 v244, 0xffff0000, v183
	v_sub_f32_e32 v240, v240, v238
	v_sub_f32_e32 v244, v244, v238
	v_mul_f32_e32 v240, v240, v239
	v_mul_f32_e32 v244, v244, v239
	v_fma_f32 v240, v140, v240, v156
	v_fma_f32 v244, v141, v244, v157
	v_lshlrev_b32_e32 v241, 16, v191
	v_and_b32_e32 v245, 0xffff0000, v191
	v_lshlrev_b32_e32 v243, 16, v199
	v_and_b32_e32 v246, 0xffff0000, v199
	v_sub_f32_e32 v243, v243, v241
	v_sub_f32_e32 v246, v246, v245
	v_fmac_f32_e32 v241, v172, v243
	v_fmac_f32_e32 v245, v173, v246
	v_fmac_f32_e32 v240, v234, v241
	v_fmac_f32_e32 v244, v234, v245
	v_mul_f32_e32 v10, v10, v240
	v_mul_f32_e32 v11, v11, v244
	v_lshlrev_b32_e32 v240, 16, v184
	v_and_b32_e32 v244, 0xffff0000, v184
	v_sub_f32_e32 v240, v240, v238
	v_sub_f32_e32 v244, v244, v238
	v_mul_f32_e32 v240, v240, v239
	v_mul_f32_e32 v244, v244, v239
	v_fma_f32 v240, v142, v240, v158
	v_fma_f32 v244, v143, v244, v159
	v_lshlrev_b32_e32 v241, 16, v192
	v_and_b32_e32 v245, 0xffff0000, v192
	v_lshlrev_b32_e32 v243, 16, v200
	v_and_b32_e32 v246, 0xffff0000, v200
	v_sub_f32_e32 v243, v243, v241
	v_sub_f32_e32 v246, v246, v245
	v_fmac_f32_e32 v241, v174, v243
	v_fmac_f32_e32 v245, v175, v246
	v_fmac_f32_e32 v240, v234, v241
	v_fmac_f32_e32 v244, v234, v245
	v_mul_f32_e32 v12, v12, v240
	v_mul_f32_e32 v13, v13, v244
	v_lshlrev_b32_e32 v240, 16, v185
	v_and_b32_e32 v244, 0xffff0000, v185
	v_sub_f32_e32 v240, v240, v238
	v_sub_f32_e32 v244, v244, v238
	v_mul_f32_e32 v240, v240, v239
	v_mul_f32_e32 v244, v244, v239
	v_fma_f32 v240, v144, v240, v160
	v_fma_f32 v244, v145, v244, v161
	v_lshlrev_b32_e32 v241, 16, v193
	v_and_b32_e32 v245, 0xffff0000, v193
	v_lshlrev_b32_e32 v243, 16, v201
	v_and_b32_e32 v246, 0xffff0000, v201
	v_sub_f32_e32 v243, v243, v241
	v_sub_f32_e32 v246, v246, v245
	v_fmac_f32_e32 v241, v176, v243
	v_fmac_f32_e32 v245, v177, v246
	v_fmac_f32_e32 v240, v234, v241
	v_fmac_f32_e32 v244, v234, v245
	v_mul_f32_e32 v14, v14, v240
	v_mul_f32_e32 v15, v15, v244
	v_cvt_pk_bf16_f32 v8, v8, v9
	v_cvt_pk_bf16_f32 v9, v10, v11
	v_cvt_pk_bf16_f32 v10, v12, v13
	v_cvt_pk_bf16_f32 v11, v14, v15
	global_store_dwordx4 v247, v[8:11], s[22:23] offset:64
	v_add_u32_e32 v236, 0x10000, v230
	v_add_u32_e32 v237, 0x2c000, v231
	v_subrev_u32_e32 v240, 0x1600, v237
	global_load_dwordx4 v[178:181], v236, s[22:23] offset:0
	global_load_dwordx4 v[182:185], v236, s[22:23] offset:64
	global_load_dwordx4 v[186:189], v237, s[96:97] offset:0
	global_load_dwordx4 v[190:193], v237, s[96:97] offset:64
	global_load_dwordx4 v[194:197], v240, s[96:97] offset:0
	global_load_dwordx4 v[198:201], v240, s[96:97] offset:64
	v_add_u32_e32 v236, 0x1800, v232
	s_nop 0
	global_load_dword v234, v236, s[96:97] offset:0
	s_waitcnt vmcnt(9)
; __device__ __forceinline__ float bf2f(u16 h) { return __uint_as_float(((unsigned)h) << 16); }
; template <int EPI> ...
;     ...
;       for (int i = 0; i < 16; i++) {
;         const int rl = rbase + (i & 3) + 8 * (i >> 2);
;         const int row = m0 + rl;
;         float o0 = bf2f(Y[(size_t)row * 1024 + 256 + ch0]);
;         float o1 = bf2f(Y[(size_t)row * 1024 + 256 + ch1]);
;         float mean = hsum32(o0 + o1) * (1.0f / 64.0f);
;         float d0 = o0 - mean, d1 = o1 - mean;
;         float var = hsum32(d0 * d0 + d1 * d1) * (1.0f / 64.0f);
;         float rstd = rsqrtf(var + 64e-5f);
;         float pv0 = bf2f(P[(size_t)row * 2816 + 256 + 1536 + ch0]);
;         float pv1 = bf2f(P[(size_t)row * 2816 + 256 + 1536 + ch1]);
;         float pp0 = prevP(p, P, row, 1536 + ch0), pp1 = prevP(p, P, row, 1536 + ch1);
;         float vv0 = pv0 + (pp0 - pv0) * mu0, vv1 = pv1 + (pp1 - pv1) * mu1;
;         float b = bs[((size_t)row * 12 + hh) * 4 + 2];
;         float y0 = (d0 * rstd * gg0 + gb0 + b * vv0) * acc0[i];
;         float y1 = (d1 * rstd * gg1 + gb1 + b * vv1) * acc1[i];
;         Y[(size_t)row * 1024 + 256 + ch0] = f2bf(y0);
;         Y[(size_t)row * 1024 + 256 + ch1] = f2bf(y1);
;       }
	v_lshlrev_b32_e32 v240, 16, v202
	v_and_b32_e32 v241, 0xffff0000, v202
	v_add_f32_e32 v244, v240, v241
	v_lshlrev_b32_e32 v240, 16, v203
	v_and_b32_e32 v241, 0xffff0000, v203
	v_add_f32_e32 v244, v244, v240
	v_add_f32_e32 v244, v244, v241
	v_lshlrev_b32_e32 v240, 16, v204
	v_and_b32_e32 v241, 0xffff0000, v204
	v_add_f32_e32 v244, v244, v240
	v_add_f32_e32 v244, v244, v241
	v_lshlrev_b32_e32 v240, 16, v205
	v_and_b32_e32 v241, 0xffff0000, v205
	v_add_f32_e32 v244, v244, v240
	v_add_f32_e32 v244, v244, v241
	v_lshlrev_b32_e32 v240, 16, v206
	v_and_b32_e32 v241, 0xffff0000, v206
	v_add_f32_e32 v244, v244, v240
	v_add_f32_e32 v244, v244, v241
	v_lshlrev_b32_e32 v240, 16, v207
	v_and_b32_e32 v241, 0xffff0000, v207
	v_add_f32_e32 v244, v244, v240
	v_add_f32_e32 v244, v244, v241
	v_lshlrev_b32_e32 v240, 16, v208
	v_and_b32_e32 v241, 0xffff0000, v208
	v_add_f32_e32 v244, v244, v240
	v_add_f32_e32 v244, v244, v241
	v_lshlrev_b32_e32 v240, 16, v209
	v_and_b32_e32 v241, 0xffff0000, v209
	v_add_f32_e32 v244, v244, v240
	v_add_f32_e32 v244, v244, v241
	v_mov_b32_e32 v240, v244
	s_nop 1
	v_permlane16_swap_b32_e32 v240, v244
	v_add_f32_e32 v244, v244, v240
	v_mov_b32_e32 v240, v244
	s_nop 1
	v_permlane32_swap_b32_e32 v240, v244
	v_add_f32_e32 v244, v244, v240
	v_mul_f32_e32 v238, 0x3c800000, v244
	v_lshlrev_b32_e32 v240, 16, v202
	v_and_b32_e32 v241, 0xffff0000, v202
	v_sub_f32_e32 v240, v240, v238
	v_sub_f32_e32 v241, v241, v238
	v_mul_f32_e32 v245, v240, v240
	v_fmac_f32_e32 v245, v241, v241
	v_lshlrev_b32_e32 v240, 16, v203
	v_and_b32_e32 v241, 0xffff0000, v203
	v_sub_f32_e32 v240, v240, v238
	v_sub_f32_e32 v241, v241, v238
	v_fmac_f32_e32 v245, v240, v240
	v_fmac_f32_e32 v245, v241, v241
	v_lshlrev_b32_e32 v240, 16, v204
	v_and_b32_e32 v241, 0xffff0000, v204
	v_sub_f32_e32 v240, v240, v238
	v_sub_f32_e32 v241, v241, v238
	v_fmac_f32_e32 v245, v240, v240
	v_fmac_f32_e32 v245, v241, v241
	v_lshlrev_b32_e32 v240, 16, v205
	v_and_b32_e32 v241, 0xffff0000, v205
	v_sub_f32_e32 v240, v240, v238
	v_sub_f32_e32 v241, v241, v238
	v_fmac_f32_e32 v245, v240, v240
	v_fmac_f32_e32 v245, v241, v241
	v_lshlrev_b32_e32 v240, 16, v206
	v_and_b32_e32 v241, 0xffff0000, v206
	v_sub_f32_e32 v240, v240, v238
	v_sub_f32_e32 v241, v241, v238
	v_fmac_f32_e32 v245, v240, v240
	v_fmac_f32_e32 v245, v241, v241
	v_lshlrev_b32_e32 v240, 16, v207
	v_and_b32_e32 v241, 0xffff0000, v207
	v_sub_f32_e32 v240, v240, v238
	v_sub_f32_e32 v241, v241, v238
	v_fmac_f32_e32 v245, v240, v240
	v_fmac_f32_e32 v245, v241, v241
	v_lshlrev_b32_e32 v240, 16, v208
	v_and_b32_e32 v241, 0xffff0000, v208
	v_sub_f32_e32 v240, v240, v238
	v_sub_f32_e32 v241, v241, v238
	v_fmac_f32_e32 v245, v240, v240
	v_fmac_f32_e32 v245, v241, v241
	v_lshlrev_b32_e32 v240, 16, v209
	v_and_b32_e32 v241, 0xffff0000, v209
	v_sub_f32_e32 v240, v240, v238
	v_sub_f32_e32 v241, v241, v238
	v_fmac_f32_e32 v245, v240, v240
	v_fmac_f32_e32 v245, v241, v241
	v_mov_b32_e32 v240, v245
	s_nop 1
	v_permlane16_swap_b32_e32 v240, v245
	v_add_f32_e32 v245, v245, v240
	v_mov_b32_e32 v240, v245
	s_nop 1
	v_permlane32_swap_b32_e32 v240, v245
	v_add_f32_e32 v245, v245, v240
	v_mov_b32_e32 v240, 0x3a27c5ac
	v_fmamk_f32 v245, v245, 0x3c800000, v240
	v_rsq_f32_e32 v239, v245
	v_add_u32_e32 v247, 0x8000, v230
	v_lshlrev_b32_e32 v240, 16, v202
	v_and_b32_e32 v244, 0xffff0000, v202
	v_sub_f32_e32 v240, v240, v238
	v_sub_f32_e32 v244, v244, v238
	v_mul_f32_e32 v240, v240, v239
	v_mul_f32_e32 v244, v244, v239
	v_fma_f32 v240, v130, v240, v146
	v_fma_f32 v244, v131, v244, v147
	v_lshlrev_b32_e32 v241, 16, v210
	v_and_b32_e32 v245, 0xffff0000, v210
	v_lshlrev_b32_e32 v243, 16, v218
	v_and_b32_e32 v246, 0xffff0000, v218
	v_sub_f32_e32 v243, v243, v241
	v_sub_f32_e32 v246, v246, v245
	v_fmac_f32_e32 v241, v162, v243
	v_fmac_f32_e32 v245, v163, v246
	v_fmac_f32_e32 v240, v235, v241
	v_fmac_f32_e32 v244, v235, v245
	v_mul_f32_e32 v32, v32, v240
	v_mul_f32_e32 v33, v33, v244
	v_lshlrev_b32_e32 v240, 16, v203
	v_and_b32_e32 v244, 0xffff0000, v203
	v_sub_f32_e32 v240, v240, v238
	v_sub_f32_e32 v244, v244, v238
	v_mul_f32_e32 v240, v240, v239
	v_mul_f32_e32 v244, v244, v239
	v_fma_f32 v240, v132, v240, v148
	v_fma_f32 v244, v133, v244, v149
	v_lshlrev_b32_e32 v241, 16, v211
	v_and_b32_e32 v245, 0xffff0000, v211
	v_lshlrev_b32_e32 v243, 16, v219
	v_and_b32_e32 v246, 0xffff0000, v219
	v_sub_f32_e32 v243, v243, v241
	v_sub_f32_e32 v246, v246, v245
	v_fmac_f32_e32 v241, v164, v243
	v_fmac_f32_e32 v245, v165, v246
	v_fmac_f32_e32 v240, v235, v241
	v_fmac_f32_e32 v244, v235, v245
	v_mul_f32_e32 v34, v34, v240
	v_mul_f32_e32 v35, v35, v244
	v_lshlrev_b32_e32 v240, 16, v204
	v_and_b32_e32 v244, 0xffff0000, v204
	v_sub_f32_e32 v240, v240, v238
	v_sub_f32_e32 v244, v244, v238
	v_mul_f32_e32 v240, v240, v239
	v_mul_f32_e32 v244, v244, v239
	v_fma_f32 v240, v134, v240, v150
	v_fma_f32 v244, v135, v244, v151
	v_lshlrev_b32_e32 v241, 16, v212
	v_and_b32_e32 v245, 0xffff0000, v212
	v_lshlrev_b32_e32 v243, 16, v220
	v_and_b32_e32 v246, 0xffff0000, v220
	v_sub_f32_e32 v243, v243, v241
	v_sub_f32_e32 v246, v246, v245
	v_fmac_f32_e32 v241, v166, v243
	v_fmac_f32_e32 v245, v167, v246
	v_fmac_f32_e32 v240, v235, v241
	v_fmac_f32_e32 v244, v235, v245
	v_mul_f32_e32 v36, v36, v240
	v_mul_f32_e32 v37, v37, v244
	v_lshlrev_b32_e32 v240, 16, v205
	v_and_b32_e32 v244, 0xffff0000, v205
	v_sub_f32_e32 v240, v240, v238
	v_sub_f32_e32 v244, v244, v238
	v_mul_f32_e32 v240, v240, v239
	v_mul_f32_e32 v244, v244, v239
	v_fma_f32 v240, v136, v240, v152
	v_fma_f32 v244, v137, v244, v153
	v_lshlrev_b32_e32 v241, 16, v213
	v_and_b32_e32 v245, 0xffff0000, v213
	v_lshlrev_b32_e32 v243, 16, v221
; __device__ __forceinline__ float bf2f(u16 h) { return __uint_as_float(((unsigned)h) << 16); }
; template <int EPI> ...
;     ...
;       for (int i = 0; i < 16; i++) {
;         const int rl = rbase + (i & 3) + 8 * (i >> 2);
;         const int row = m0 + rl;
;         float o0 = bf2f(Y[(size_t)row * 1024 + 256 + ch0]);
;         float o1 = bf2f(Y[(size_t)row * 1024 + 256 + ch1]);
;         float mean = hsum32(o0 + o1) * (1.0f / 64.0f);
;         float d0 = o0 - mean, d1 = o1 - mean;
;         float var = hsum32(d0 * d0 + d1 * d1) * (1.0f / 64.0f);
;         float rstd = rsqrtf(var + 64e-5f);
;         float pv0 = bf2f(P[(size_t)row * 2816 + 256 + 1536 + ch0]);
;         float pv1 = bf2f(P[(size_t)row * 2816 + 256 + 1536 + ch1]);
;         float pp0 = prevP(p, P, row, 1536 + ch0), pp1 = prevP(p, P, row, 1536 + ch1);
;         float vv0 = pv0 + (pp0 - pv0) * mu0, vv1 = pv1 + (pp1 - pv1) * mu1;
;         float b = bs[((size_t)row * 12 + hh) * 4 + 2];
;         float y0 = (d0 * rstd * gg0 + gb0 + b * vv0) * acc0[i];
;         float y1 = (d1 * rstd * gg1 + gb1 + b * vv1) * acc1[i];
;         Y[(size_t)row * 1024 + 256 + ch0] = f2bf(y0);
;         Y[(size_t)row * 1024 + 256 + ch1] = f2bf(y1);
;       }
	v_and_b32_e32 v246, 0xffff0000, v221
	v_sub_f32_e32 v243, v243, v241
	v_sub_f32_e32 v246, v246, v245
	v_fmac_f32_e32 v241, v168, v243
	v_fmac_f32_e32 v245, v169, v246
	v_fmac_f32_e32 v240, v235, v241
	v_fmac_f32_e32 v244, v235, v245
	v_mul_f32_e32 v38, v38, v240
	v_mul_f32_e32 v39, v39, v244
	v_cvt_pk_bf16_f32 v32, v32, v33
	v_cvt_pk_bf16_f32 v33, v34, v35
	v_cvt_pk_bf16_f32 v34, v36, v37
	v_cvt_pk_bf16_f32 v35, v38, v39
	global_store_dwordx4 v247, v[32:35], s[22:23] offset:0
	v_lshlrev_b32_e32 v240, 16, v206
	v_and_b32_e32 v244, 0xffff0000, v206
	v_sub_f32_e32 v240, v240, v238
	v_sub_f32_e32 v244, v244, v238
	v_mul_f32_e32 v240, v240, v239
	v_mul_f32_e32 v244, v244, v239
	v_fma_f32 v240, v138, v240, v154
	v_fma_f32 v244, v139, v244, v155
	v_lshlrev_b32_e32 v241, 16, v214
	v_and_b32_e32 v245, 0xffff0000, v214
	v_lshlrev_b32_e32 v243, 16, v222
	v_and_b32_e32 v246, 0xffff0000, v222
	v_sub_f32_e32 v243, v243, v241
	v_sub_f32_e32 v246, v246, v245
	v_fmac_f32_e32 v241, v170, v243
	v_fmac_f32_e32 v245, v171, v246
	v_fmac_f32_e32 v240, v235, v241
	v_fmac_f32_e32 v244, v235, v245
	v_mul_f32_e32 v40, v40, v240
	v_mul_f32_e32 v41, v41, v244
	v_lshlrev_b32_e32 v240, 16, v207
	v_and_b32_e32 v244, 0xffff0000, v207
	v_sub_f32_e32 v240, v240, v238
	v_sub_f32_e32 v244, v244, v238
	v_mul_f32_e32 v240, v240, v239
	v_mul_f32_e32 v244, v244, v239
	v_fma_f32 v240, v140, v240, v156
	v_fma_f32 v244, v141, v244, v157
	v_lshlrev_b32_e32 v241, 16, v215
	v_and_b32_e32 v245, 0xffff0000, v215
	v_lshlrev_b32_e32 v243, 16, v223
	v_and_b32_e32 v246, 0xffff0000, v223
	v_sub_f32_e32 v243, v243, v241
	v_sub_f32_e32 v246, v246, v245
	v_fmac_f32_e32 v241, v172, v243
	v_fmac_f32_e32 v245, v173, v246
	v_fmac_f32_e32 v240, v235, v241
	v_fmac_f32_e32 v244, v235, v245
	v_mul_f32_e32 v42, v42, v240
	v_mul_f32_e32 v43, v43, v244
	v_lshlrev_b32_e32 v240, 16, v208
	v_and_b32_e32 v244, 0xffff0000, v208
	v_sub_f32_e32 v240, v240, v238
	v_sub_f32_e32 v244, v244, v238
	v_mul_f32_e32 v240, v240, v239
	v_mul_f32_e32 v244, v244, v239
	v_fma_f32 v240, v142, v240, v158
	v_fma_f32 v244, v143, v244, v159
	v_lshlrev_b32_e32 v241, 16, v216
	v_and_b32_e32 v245, 0xffff0000, v216
	v_lshlrev_b32_e32 v243, 16, v224
	v_and_b32_e32 v246, 0xffff0000, v224
	v_sub_f32_e32 v243, v243, v241
	v_sub_f32_e32 v246, v246, v245
	v_fmac_f32_e32 v241, v174, v243
	v_fmac_f32_e32 v245, v175, v246
	v_fmac_f32_e32 v240, v235, v241
	v_fmac_f32_e32 v244, v235, v245
	v_mul_f32_e32 v44, v44, v240
	v_mul_f32_e32 v45, v45, v244
	v_lshlrev_b32_e32 v240, 16, v209
	v_and_b32_e32 v244, 0xffff0000, v209
	v_sub_f32_e32 v240, v240, v238
	v_sub_f32_e32 v244, v244, v238
	v_mul_f32_e32 v240, v240, v239
	v_mul_f32_e32 v244, v244, v239
	v_fma_f32 v240, v144, v240, v160
	v_fma_f32 v244, v145, v244, v161
	v_lshlrev_b32_e32 v241, 16, v217
	v_and_b32_e32 v245, 0xffff0000, v217
	v_lshlrev_b32_e32 v243, 16, v225
	v_and_b32_e32 v246, 0xffff0000, v225
	v_sub_f32_e32 v243, v243, v241
	v_sub_f32_e32 v246, v246, v245
	v_fmac_f32_e32 v241, v176, v243
	v_fmac_f32_e32 v245, v177, v246
	v_fmac_f32_e32 v240, v235, v241
	v_fmac_f32_e32 v244, v235, v245
	v_mul_f32_e32 v46, v46, v240
	v_mul_f32_e32 v47, v47, v244
	v_cvt_pk_bf16_f32 v40, v40, v41
	v_cvt_pk_bf16_f32 v41, v42, v43
	v_cvt_pk_bf16_f32 v42, v44, v45
	v_cvt_pk_bf16_f32 v43, v46, v47
	global_store_dwordx4 v247, v[40:43], s[22:23] offset:64
	v_add_u32_e32 v236, 0x18000, v230
	v_add_u32_e32 v237, 0x42000, v231
	v_subrev_u32_e32 v240, 0x1600, v237
	global_load_dwordx4 v[202:205], v236, s[22:23] offset:0
	global_load_dwordx4 v[206:209], v236, s[22:23] offset:64
	global_load_dwordx4 v[210:213], v237, s[96:97] offset:0
	global_load_dwordx4 v[214:217], v237, s[96:97] offset:64
	global_load_dwordx4 v[218:221], v240, s[96:97] offset:0
	global_load_dwordx4 v[222:225], v240, s[96:97] offset:64
	v_add_u32_e32 v236, 0x2400, v232
	s_nop 0
	global_load_dword v235, v236, s[96:97] offset:0
	s_waitcnt vmcnt(9)
	v_lshlrev_b32_e32 v240, 16, v178
	v_and_b32_e32 v241, 0xffff0000, v178
	v_add_f32_e32 v244, v240, v241
	v_lshlrev_b32_e32 v240, 16, v179
	v_and_b32_e32 v241, 0xffff0000, v179
	v_add_f32_e32 v244, v244, v240
	v_add_f32_e32 v244, v244, v241
	v_lshlrev_b32_e32 v240, 16, v180
	v_and_b32_e32 v241, 0xffff0000, v180
	v_add_f32_e32 v244, v244, v240
	v_add_f32_e32 v244, v244, v241
	v_lshlrev_b32_e32 v240, 16, v181
	v_and_b32_e32 v241, 0xffff0000, v181
	v_add_f32_e32 v244, v244, v240
	v_add_f32_e32 v244, v244, v241
	v_lshlrev_b32_e32 v240, 16, v182
	v_and_b32_e32 v241, 0xffff0000, v182
	v_add_f32_e32 v244, v244, v240
	v_add_f32_e32 v244, v244, v241
	v_lshlrev_b32_e32 v240, 16, v183
	v_and_b32_e32 v241, 0xffff0000, v183
	v_add_f32_e32 v244, v244, v240
	v_add_f32_e32 v244, v244, v241
	v_lshlrev_b32_e32 v240, 16, v184
	v_and_b32_e32 v241, 0xffff0000, v184
	v_add_f32_e32 v244, v244, v240
	v_add_f32_e32 v244, v244, v241
	v_lshlrev_b32_e32 v240, 16, v185
	v_and_b32_e32 v241, 0xffff0000, v185
	v_add_f32_e32 v244, v244, v240
	v_add_f32_e32 v244, v244, v241
	v_mov_b32_e32 v240, v244
	s_nop 1
	v_permlane16_swap_b32_e32 v240, v244
	v_add_f32_e32 v244, v244, v240
	v_mov_b32_e32 v240, v244
	s_nop 1
	v_permlane32_swap_b32_e32 v240, v244
	v_add_f32_e32 v244, v244, v240
	v_mul_f32_e32 v238, 0x3c800000, v244
	v_lshlrev_b32_e32 v240, 16, v178
	v_and_b32_e32 v241, 0xffff0000, v178
	v_sub_f32_e32 v240, v240, v238
	v_sub_f32_e32 v241, v241, v238
	v_mul_f32_e32 v245, v240, v240
	v_fmac_f32_e32 v245, v241, v241
	v_lshlrev_b32_e32 v240, 16, v179
	v_and_b32_e32 v241, 0xffff0000, v179
	v_sub_f32_e32 v240, v240, v238
	v_sub_f32_e32 v241, v241, v238
	v_fmac_f32_e32 v245, v240, v240
	v_fmac_f32_e32 v245, v241, v241
	v_lshlrev_b32_e32 v240, 16, v180
; __device__ __forceinline__ float bf2f(u16 h) { return __uint_as_float(((unsigned)h) << 16); }
; template <int EPI> ...
;     ...
;       for (int i = 0; i < 16; i++) {
;         const int rl = rbase + (i & 3) + 8 * (i >> 2);
;         const int row = m0 + rl;
;         float o0 = bf2f(Y[(size_t)row * 1024 + 256 + ch0]);
;         float o1 = bf2f(Y[(size_t)row * 1024 + 256 + ch1]);
;         float mean = hsum32(o0 + o1) * (1.0f / 64.0f);
;         float d0 = o0 - mean, d1 = o1 - mean;
;         float var = hsum32(d0 * d0 + d1 * d1) * (1.0f / 64.0f);
;         float rstd = rsqrtf(var + 64e-5f);
;         float pv0 = bf2f(P[(size_t)row * 2816 + 256 + 1536 + ch0]);
;         float pv1 = bf2f(P[(size_t)row * 2816 + 256 + 1536 + ch1]);
;         float pp0 = prevP(p, P, row, 1536 + ch0), pp1 = prevP(p, P, row, 1536 + ch1);
;         float vv0 = pv0 + (pp0 - pv0) * mu0, vv1 = pv1 + (pp1 - pv1) * mu1;
;         float b = bs[((size_t)row * 12 + hh) * 4 + 2];
;         float y0 = (d0 * rstd * gg0 + gb0 + b * vv0) * acc0[i];
;         float y1 = (d1 * rstd * gg1 + gb1 + b * vv1) * acc1[i];
;         Y[(size_t)row * 1024 + 256 + ch0] = f2bf(y0);
;         Y[(size_t)row * 1024 + 256 + ch1] = f2bf(y1);
;       }
	v_and_b32_e32 v241, 0xffff0000, v180
	v_sub_f32_e32 v240, v240, v238
	v_sub_f32_e32 v241, v241, v238
	v_fmac_f32_e32 v245, v240, v240
	v_fmac_f32_e32 v245, v241, v241
	v_lshlrev_b32_e32 v240, 16, v181
	v_and_b32_e32 v241, 0xffff0000, v181
	v_sub_f32_e32 v240, v240, v238
	v_sub_f32_e32 v241, v241, v238
	v_fmac_f32_e32 v245, v240, v240
	v_fmac_f32_e32 v245, v241, v241
	v_lshlrev_b32_e32 v240, 16, v182
	v_and_b32_e32 v241, 0xffff0000, v182
	v_sub_f32_e32 v240, v240, v238
	v_sub_f32_e32 v241, v241, v238
	v_fmac_f32_e32 v245, v240, v240
	v_fmac_f32_e32 v245, v241, v241
	v_lshlrev_b32_e32 v240, 16, v183
	v_and_b32_e32 v241, 0xffff0000, v183
	v_sub_f32_e32 v240, v240, v238
	v_sub_f32_e32 v241, v241, v238
	v_fmac_f32_e32 v245, v240, v240
	v_fmac_f32_e32 v245, v241, v241
	v_lshlrev_b32_e32 v240, 16, v184
	v_and_b32_e32 v241, 0xffff0000, v184
	v_sub_f32_e32 v240, v240, v238
	v_sub_f32_e32 v241, v241, v238
	v_fmac_f32_e32 v245, v240, v240
	v_fmac_f32_e32 v245, v241, v241
	v_lshlrev_b32_e32 v240, 16, v185
	v_and_b32_e32 v241, 0xffff0000, v185
	v_sub_f32_e32 v240, v240, v238
	v_sub_f32_e32 v241, v241, v238
	v_fmac_f32_e32 v245, v240, v240
	v_fmac_f32_e32 v245, v241, v241
	v_mov_b32_e32 v240, v245
	s_nop 1
	v_permlane16_swap_b32_e32 v240, v245
	v_add_f32_e32 v245, v245, v240
	v_mov_b32_e32 v240, v245
	s_nop 1
	v_permlane32_swap_b32_e32 v240, v245
	v_add_f32_e32 v245, v245, v240
	v_mov_b32_e32 v240, 0x3a27c5ac
	v_fmamk_f32 v245, v245, 0x3c800000, v240
	v_rsq_f32_e32 v239, v245
	v_add_u32_e32 v247, 0x10000, v230
	v_lshlrev_b32_e32 v240, 16, v178
	v_and_b32_e32 v244, 0xffff0000, v178
	v_sub_f32_e32 v240, v240, v238
	v_sub_f32_e32 v244, v244, v238
	v_mul_f32_e32 v240, v240, v239
	v_mul_f32_e32 v244, v244, v239
	v_fma_f32 v240, v130, v240, v146
	v_fma_f32 v244, v131, v244, v147
	v_lshlrev_b32_e32 v241, 16, v186
	v_and_b32_e32 v245, 0xffff0000, v186
	v_lshlrev_b32_e32 v243, 16, v194
	v_and_b32_e32 v246, 0xffff0000, v194
	v_sub_f32_e32 v243, v243, v241
	v_sub_f32_e32 v246, v246, v245
	v_fmac_f32_e32 v241, v162, v243
	v_fmac_f32_e32 v245, v163, v246
	v_fmac_f32_e32 v240, v234, v241
	v_fmac_f32_e32 v244, v234, v245
	v_mul_f32_e32 v64, v64, v240
	v_mul_f32_e32 v65, v65, v244
	v_lshlrev_b32_e32 v240, 16, v179
	v_and_b32_e32 v244, 0xffff0000, v179
	v_sub_f32_e32 v240, v240, v238
	v_sub_f32_e32 v244, v244, v238
	v_mul_f32_e32 v240, v240, v239
	v_mul_f32_e32 v244, v244, v239
	v_fma_f32 v240, v132, v240, v148
	v_fma_f32 v244, v133, v244, v149
	v_lshlrev_b32_e32 v241, 16, v187
	v_and_b32_e32 v245, 0xffff0000, v187
	v_lshlrev_b32_e32 v243, 16, v195
	v_and_b32_e32 v246, 0xffff0000, v195
	v_sub_f32_e32 v243, v243, v241
	v_sub_f32_e32 v246, v246, v245
	v_fmac_f32_e32 v241, v164, v243
	v_fmac_f32_e32 v245, v165, v246
	v_fmac_f32_e32 v240, v234, v241
	v_fmac_f32_e32 v244, v234, v245
	v_mul_f32_e32 v66, v66, v240
	v_mul_f32_e32 v67, v67, v244
	v_lshlrev_b32_e32 v240, 16, v180
	v_and_b32_e32 v244, 0xffff0000, v180
	v_sub_f32_e32 v240, v240, v238
	v_sub_f32_e32 v244, v244, v238
	v_mul_f32_e32 v240, v240, v239
	v_mul_f32_e32 v244, v244, v239
	v_fma_f32 v240, v134, v240, v150
	v_fma_f32 v244, v135, v244, v151
	v_lshlrev_b32_e32 v241, 16, v188
	v_and_b32_e32 v245, 0xffff0000, v188
	v_lshlrev_b32_e32 v243, 16, v196
	v_and_b32_e32 v246, 0xffff0000, v196
	v_sub_f32_e32 v243, v243, v241
	v_sub_f32_e32 v246, v246, v245
	v_fmac_f32_e32 v241, v166, v243
	v_fmac_f32_e32 v245, v167, v246
	v_fmac_f32_e32 v240, v234, v241
	v_fmac_f32_e32 v244, v234, v245
	v_mul_f32_e32 v68, v68, v240
	v_mul_f32_e32 v69, v69, v244
	v_lshlrev_b32_e32 v240, 16, v181
	v_and_b32_e32 v244, 0xffff0000, v181
	v_sub_f32_e32 v240, v240, v238
	v_sub_f32_e32 v244, v244, v238
	v_mul_f32_e32 v240, v240, v239
	v_mul_f32_e32 v244, v244, v239
	v_fma_f32 v240, v136, v240, v152
	v_fma_f32 v244, v137, v244, v153
	v_lshlrev_b32_e32 v241, 16, v189
	v_and_b32_e32 v245, 0xffff0000, v189
	v_lshlrev_b32_e32 v243, 16, v197
	v_and_b32_e32 v246, 0xffff0000, v197
	v_sub_f32_e32 v243, v243, v241
	v_sub_f32_e32 v246, v246, v245
	v_fmac_f32_e32 v241, v168, v243
	v_fmac_f32_e32 v245, v169, v246
	v_fmac_f32_e32 v240, v234, v241
	v_fmac_f32_e32 v244, v234, v245
	v_mul_f32_e32 v70, v70, v240
	v_mul_f32_e32 v71, v71, v244
	v_cvt_pk_bf16_f32 v64, v64, v65
	v_cvt_pk_bf16_f32 v65, v66, v67
	v_cvt_pk_bf16_f32 v66, v68, v69
	v_cvt_pk_bf16_f32 v67, v70, v71
	global_store_dwordx4 v247, v[64:67], s[22:23] offset:0
	v_lshlrev_b32_e32 v240, 16, v182
	v_and_b32_e32 v244, 0xffff0000, v182
	v_sub_f32_e32 v240, v240, v238
	v_sub_f32_e32 v244, v244, v238
	v_mul_f32_e32 v240, v240, v239
	v_mul_f32_e32 v244, v244, v239
	v_fma_f32 v240, v138, v240, v154
	v_fma_f32 v244, v139, v244, v155
	v_lshlrev_b32_e32 v241, 16, v190
	v_and_b32_e32 v245, 0xffff0000, v190
	v_lshlrev_b32_e32 v243, 16, v198
	v_and_b32_e32 v246, 0xffff0000, v198
	v_sub_f32_e32 v243, v243, v241
	v_sub_f32_e32 v246, v246, v245
	v_fmac_f32_e32 v241, v170, v243
	v_fmac_f32_e32 v245, v171, v246
	v_fmac_f32_e32 v240, v234, v241
	v_fmac_f32_e32 v244, v234, v245
	v_mul_f32_e32 v72, v72, v240
	v_mul_f32_e32 v73, v73, v244
	v_lshlrev_b32_e32 v240, 16, v183
	v_and_b32_e32 v244, 0xffff0000, v183
	v_sub_f32_e32 v240, v240, v238
	v_sub_f32_e32 v244, v244, v238
	v_mul_f32_e32 v240, v240, v239
	v_mul_f32_e32 v244, v244, v239
	v_fma_f32 v240, v140, v240, v156
	v_fma_f32 v244, v141, v244, v157
	v_lshlrev_b32_e32 v241, 16, v191
	v_and_b32_e32 v245, 0xffff0000, v191
	v_lshlrev_b32_e32 v243, 16, v199
	v_and_b32_e32 v246, 0xffff0000, v199
	v_sub_f32_e32 v243, v243, v241
	v_sub_f32_e32 v246, v246, v245
	v_fmac_f32_e32 v241, v172, v243
	v_fmac_f32_e32 v245, v173, v246
	v_fmac_f32_e32 v240, v234, v241
; __device__ __forceinline__ float bf2f(u16 h) { return __uint_as_float(((unsigned)h) << 16); }
; template <int EPI> ...
;     ...
;       for (int i = 0; i < 16; i++) {
;         const int rl = rbase + (i & 3) + 8 * (i >> 2);
;         const int row = m0 + rl;
;         float o0 = bf2f(Y[(size_t)row * 1024 + 256 + ch0]);
;         float o1 = bf2f(Y[(size_t)row * 1024 + 256 + ch1]);
;         float mean = hsum32(o0 + o1) * (1.0f / 64.0f);
;         float d0 = o0 - mean, d1 = o1 - mean;
;         float var = hsum32(d0 * d0 + d1 * d1) * (1.0f / 64.0f);
;         float rstd = rsqrtf(var + 64e-5f);
;         float pv0 = bf2f(P[(size_t)row * 2816 + 256 + 1536 + ch0]);
;         float pv1 = bf2f(P[(size_t)row * 2816 + 256 + 1536 + ch1]);
;         float pp0 = prevP(p, P, row, 1536 + ch0), pp1 = prevP(p, P, row, 1536 + ch1);
;         float vv0 = pv0 + (pp0 - pv0) * mu0, vv1 = pv1 + (pp1 - pv1) * mu1;
;         float b = bs[((size_t)row * 12 + hh) * 4 + 2];
;         float y0 = (d0 * rstd * gg0 + gb0 + b * vv0) * acc0[i];
;         float y1 = (d1 * rstd * gg1 + gb1 + b * vv1) * acc1[i];
;         Y[(size_t)row * 1024 + 256 + ch0] = f2bf(y0);
;         Y[(size_t)row * 1024 + 256 + ch1] = f2bf(y1);
;       }
	v_fmac_f32_e32 v244, v234, v245
	v_mul_f32_e32 v74, v74, v240
	v_mul_f32_e32 v75, v75, v244
	v_lshlrev_b32_e32 v240, 16, v184
	v_and_b32_e32 v244, 0xffff0000, v184
	v_sub_f32_e32 v240, v240, v238
	v_sub_f32_e32 v244, v244, v238
	v_mul_f32_e32 v240, v240, v239
	v_mul_f32_e32 v244, v244, v239
	v_fma_f32 v240, v142, v240, v158
	v_fma_f32 v244, v143, v244, v159
	v_lshlrev_b32_e32 v241, 16, v192
	v_and_b32_e32 v245, 0xffff0000, v192
	v_lshlrev_b32_e32 v243, 16, v200
	v_and_b32_e32 v246, 0xffff0000, v200
	v_sub_f32_e32 v243, v243, v241
	v_sub_f32_e32 v246, v246, v245
	v_fmac_f32_e32 v241, v174, v243
	v_fmac_f32_e32 v245, v175, v246
	v_fmac_f32_e32 v240, v234, v241
	v_fmac_f32_e32 v244, v234, v245
	v_mul_f32_e32 v76, v76, v240
	v_mul_f32_e32 v77, v77, v244
	v_lshlrev_b32_e32 v240, 16, v185
	v_and_b32_e32 v244, 0xffff0000, v185
	v_sub_f32_e32 v240, v240, v238
	v_sub_f32_e32 v244, v244, v238
	v_mul_f32_e32 v240, v240, v239
	v_mul_f32_e32 v244, v244, v239
	v_fma_f32 v240, v144, v240, v160
	v_fma_f32 v244, v145, v244, v161
	v_lshlrev_b32_e32 v241, 16, v193
	v_and_b32_e32 v245, 0xffff0000, v193
	v_lshlrev_b32_e32 v243, 16, v201
	v_and_b32_e32 v246, 0xffff0000, v201
	v_sub_f32_e32 v243, v243, v241
	v_sub_f32_e32 v246, v246, v245
	v_fmac_f32_e32 v241, v176, v243
	v_fmac_f32_e32 v245, v177, v246
	v_fmac_f32_e32 v240, v234, v241
	v_fmac_f32_e32 v244, v234, v245
	v_mul_f32_e32 v78, v78, v240
	v_mul_f32_e32 v79, v79, v244
	v_cvt_pk_bf16_f32 v72, v72, v73
	v_cvt_pk_bf16_f32 v73, v74, v75
	v_cvt_pk_bf16_f32 v74, v76, v77
	v_cvt_pk_bf16_f32 v75, v78, v79
	global_store_dwordx4 v247, v[72:75], s[22:23] offset:64
	v_add_u32_e32 v236, 0x0, v230
	v_add_u32_e32 v237, 0x0, v231
	v_subrev_u32_e32 v240, 0x1600, v237
	global_load_dwordx4 v[178:181], v236, s[22:23] offset:128
	global_load_dwordx4 v[182:185], v236, s[22:23] offset:192
	global_load_dwordx4 v[186:189], v237, s[96:97] offset:128
	global_load_dwordx4 v[190:193], v237, s[96:97] offset:192
	global_load_dwordx4 v[194:197], v240, s[96:97] offset:128
	global_load_dwordx4 v[198:201], v240, s[96:97] offset:192
	v_add_u32_e32 v236, 0x0, v232
	s_nop 0
	global_load_dword v234, v236, s[96:97] offset:16
	s_waitcnt vmcnt(9)
	v_lshlrev_b32_e32 v240, 16, v202
	v_and_b32_e32 v241, 0xffff0000, v202
	v_add_f32_e32 v244, v240, v241
	v_lshlrev_b32_e32 v240, 16, v203
	v_and_b32_e32 v241, 0xffff0000, v203
	v_add_f32_e32 v244, v244, v240
	v_add_f32_e32 v244, v244, v241
	v_lshlrev_b32_e32 v240, 16, v204
	v_and_b32_e32 v241, 0xffff0000, v204
	v_add_f32_e32 v244, v244, v240
	v_add_f32_e32 v244, v244, v241
	v_lshlrev_b32_e32 v240, 16, v205
	v_and_b32_e32 v241, 0xffff0000, v205
	v_add_f32_e32 v244, v244, v240
	v_add_f32_e32 v244, v244, v241
	v_lshlrev_b32_e32 v240, 16, v206
	v_and_b32_e32 v241, 0xffff0000, v206
	v_add_f32_e32 v244, v244, v240
	v_add_f32_e32 v244, v244, v241
	v_lshlrev_b32_e32 v240, 16, v207
	v_and_b32_e32 v241, 0xffff0000, v207
	v_add_f32_e32 v244, v244, v240
	v_add_f32_e32 v244, v244, v241
	v_lshlrev_b32_e32 v240, 16, v208
	v_and_b32_e32 v241, 0xffff0000, v208
	v_add_f32_e32 v244, v244, v240
	v_add_f32_e32 v244, v244, v241
	v_lshlrev_b32_e32 v240, 16, v209
	v_and_b32_e32 v241, 0xffff0000, v209
	v_add_f32_e32 v244, v244, v240
	v_add_f32_e32 v244, v244, v241
	v_mov_b32_e32 v240, v244
	s_nop 1
	v_permlane16_swap_b32_e32 v240, v244
	v_add_f32_e32 v244, v244, v240
	v_mov_b32_e32 v240, v244
	s_nop 1
	v_permlane32_swap_b32_e32 v240, v244
	v_add_f32_e32 v244, v244, v240
	v_mul_f32_e32 v238, 0x3c800000, v244
	v_lshlrev_b32_e32 v240, 16, v202
	v_and_b32_e32 v241, 0xffff0000, v202
	v_sub_f32_e32 v240, v240, v238
	v_sub_f32_e32 v241, v241, v238
	v_mul_f32_e32 v245, v240, v240
	v_fmac_f32_e32 v245, v241, v241
	v_lshlrev_b32_e32 v240, 16, v203
	v_and_b32_e32 v241, 0xffff0000, v203
	v_sub_f32_e32 v240, v240, v238
	v_sub_f32_e32 v241, v241, v238
	v_fmac_f32_e32 v245, v240, v240
	v_fmac_f32_e32 v245, v241, v241
	v_lshlrev_b32_e32 v240, 16, v204
	v_and_b32_e32 v241, 0xffff0000, v204
	v_sub_f32_e32 v240, v240, v238
	v_sub_f32_e32 v241, v241, v238
	v_fmac_f32_e32 v245, v240, v240
	v_fmac_f32_e32 v245, v241, v241
	v_lshlrev_b32_e32 v240, 16, v205
	v_and_b32_e32 v241, 0xffff0000, v205
	v_sub_f32_e32 v240, v240, v238
	v_sub_f32_e32 v241, v241, v238
	v_fmac_f32_e32 v245, v240, v240
	v_fmac_f32_e32 v245, v241, v241
	v_lshlrev_b32_e32 v240, 16, v206
	v_and_b32_e32 v241, 0xffff0000, v206
	v_sub_f32_e32 v240, v240, v238
	v_sub_f32_e32 v241, v241, v238
	v_fmac_f32_e32 v245, v240, v240
	v_fmac_f32_e32 v245, v241, v241
	v_lshlrev_b32_e32 v240, 16, v207
	v_and_b32_e32 v241, 0xffff0000, v207
	v_sub_f32_e32 v240, v240, v238
	v_sub_f32_e32 v241, v241, v238
	v_fmac_f32_e32 v245, v240, v240
	v_fmac_f32_e32 v245, v241, v241
	v_lshlrev_b32_e32 v240, 16, v208
	v_and_b32_e32 v241, 0xffff0000, v208
	v_sub_f32_e32 v240, v240, v238
	v_sub_f32_e32 v241, v241, v238
	v_fmac_f32_e32 v245, v240, v240
	v_fmac_f32_e32 v245, v241, v241
	v_lshlrev_b32_e32 v240, 16, v209
	v_and_b32_e32 v241, 0xffff0000, v209
	v_sub_f32_e32 v240, v240, v238
	v_sub_f32_e32 v241, v241, v238
	v_fmac_f32_e32 v245, v240, v240
	v_fmac_f32_e32 v245, v241, v241
	v_mov_b32_e32 v240, v245
	s_nop 1
	v_permlane16_swap_b32_e32 v240, v245
	v_add_f32_e32 v245, v245, v240
	v_mov_b32_e32 v240, v245
	s_nop 1
	v_permlane32_swap_b32_e32 v240, v245
	v_add_f32_e32 v245, v245, v240
	v_mov_b32_e32 v240, 0x3a27c5ac
	v_fmamk_f32 v245, v245, 0x3c800000, v240
	v_rsq_f32_e32 v239, v245
	v_add_u32_e32 v247, 0x18000, v230
	v_lshlrev_b32_e32 v240, 16, v202
	v_and_b32_e32 v244, 0xffff0000, v202
	v_sub_f32_e32 v240, v240, v238
	v_sub_f32_e32 v244, v244, v238
	v_mul_f32_e32 v240, v240, v239
	v_mul_f32_e32 v244, v244, v239
; __device__ __forceinline__ float bf2f(u16 h) { return __uint_as_float(((unsigned)h) << 16); }
; __device__ __forceinline__ float prevP(const Params& p, const u16* P, int row, int c) {
;   const int rp = row > 0 ? row - 1 : 0;
;   float v = bf2f(P[(size_t)rp * 2816 + 256 + c]);
;   const bool start = (row < NP) ? ((row & 2047) == 0) : (((row - NP) & 3) == 0);
;   if (start) v = (row < NP) ? 0.f : p.in[3][(size_t)((row - NP) >> 2) * 2560 + c];
;   return v;
; template <int EPI> ...
;     ...
;       for (int i = 0; i < 16; i++) {
;         const int rl = rbase + (i & 3) + 8 * (i >> 2);
;         const int row = m0 + rl;
;         float o0 = bf2f(Y[(size_t)row * 1024 + 256 + ch0]);
;         float o1 = bf2f(Y[(size_t)row * 1024 + 256 + ch1]);
;         float mean = hsum32(o0 + o1) * (1.0f / 64.0f);
;         float d0 = o0 - mean, d1 = o1 - mean;
;         float var = hsum32(d0 * d0 + d1 * d1) * (1.0f / 64.0f);
;         float rstd = rsqrtf(var + 64e-5f);
;         float pv0 = bf2f(P[(size_t)row * 2816 + 256 + 1536 + ch0]);
;         float pv1 = bf2f(P[(size_t)row * 2816 + 256 + 1536 + ch1]);
;         float pp0 = prevP(p, P, row, 1536 + ch0), pp1 = prevP(p, P, row, 1536 + ch1);
;         float vv0 = pv0 + (pp0 - pv0) * mu0, vv1 = pv1 + (pp1 - pv1) * mu1;
;         float b = bs[((size_t)row * 12 + hh) * 4 + 2];
;         float y0 = (d0 * rstd * gg0 + gb0 + b * vv0) * acc0[i];
;         float y1 = (d1 * rstd * gg1 + gb1 + b * vv1) * acc1[i];
;         Y[(size_t)row * 1024 + 256 + ch0] = f2bf(y0);
;         Y[(size_t)row * 1024 + 256 + ch1] = f2bf(y1);
;       }
	v_fma_f32 v240, v130, v240, v146
	v_fma_f32 v244, v131, v244, v147
	v_lshlrev_b32_e32 v241, 16, v210
	v_and_b32_e32 v245, 0xffff0000, v210
	v_lshlrev_b32_e32 v243, 16, v218
	v_and_b32_e32 v246, 0xffff0000, v218
	v_sub_f32_e32 v243, v243, v241
	v_sub_f32_e32 v246, v246, v245
	v_fmac_f32_e32 v241, v162, v243
	v_fmac_f32_e32 v245, v163, v246
	v_fmac_f32_e32 v240, v235, v241
	v_fmac_f32_e32 v244, v235, v245
	v_mul_f32_e32 v96, v96, v240
	v_mul_f32_e32 v97, v97, v244
	v_lshlrev_b32_e32 v240, 16, v203
	v_and_b32_e32 v244, 0xffff0000, v203
	v_sub_f32_e32 v240, v240, v238
	v_sub_f32_e32 v244, v244, v238
	v_mul_f32_e32 v240, v240, v239
	v_mul_f32_e32 v244, v244, v239
	v_fma_f32 v240, v132, v240, v148
	v_fma_f32 v244, v133, v244, v149
	v_lshlrev_b32_e32 v241, 16, v211
	v_and_b32_e32 v245, 0xffff0000, v211
	v_lshlrev_b32_e32 v243, 16, v219
	v_and_b32_e32 v246, 0xffff0000, v219
	v_sub_f32_e32 v243, v243, v241
	v_sub_f32_e32 v246, v246, v245
	v_fmac_f32_e32 v241, v164, v243
	v_fmac_f32_e32 v245, v165, v246
	v_fmac_f32_e32 v240, v235, v241
	v_fmac_f32_e32 v244, v235, v245
	v_mul_f32_e32 v98, v98, v240
	v_mul_f32_e32 v99, v99, v244
	v_lshlrev_b32_e32 v240, 16, v204
	v_and_b32_e32 v244, 0xffff0000, v204
	v_sub_f32_e32 v240, v240, v238
	v_sub_f32_e32 v244, v244, v238
	v_mul_f32_e32 v240, v240, v239
	v_mul_f32_e32 v244, v244, v239
	v_fma_f32 v240, v134, v240, v150
	v_fma_f32 v244, v135, v244, v151
	v_lshlrev_b32_e32 v241, 16, v212
	v_and_b32_e32 v245, 0xffff0000, v212
	v_lshlrev_b32_e32 v243, 16, v220
	v_and_b32_e32 v246, 0xffff0000, v220
	v_sub_f32_e32 v243, v243, v241
	v_sub_f32_e32 v246, v246, v245
	v_fmac_f32_e32 v241, v166, v243
	v_fmac_f32_e32 v245, v167, v246
	v_fmac_f32_e32 v240, v235, v241
	v_fmac_f32_e32 v244, v235, v245
	v_mul_f32_e32 v100, v100, v240
	v_mul_f32_e32 v101, v101, v244
	v_lshlrev_b32_e32 v240, 16, v205
	v_and_b32_e32 v244, 0xffff0000, v205
	v_sub_f32_e32 v240, v240, v238
	v_sub_f32_e32 v244, v244, v238
	v_mul_f32_e32 v240, v240, v239
	v_mul_f32_e32 v244, v244, v239
	v_fma_f32 v240, v136, v240, v152
	v_fma_f32 v244, v137, v244, v153
	v_lshlrev_b32_e32 v241, 16, v213
	v_and_b32_e32 v245, 0xffff0000, v213
	v_lshlrev_b32_e32 v243, 16, v221
	v_and_b32_e32 v246, 0xffff0000, v221
	v_sub_f32_e32 v243, v243, v241
	v_sub_f32_e32 v246, v246, v245
	v_fmac_f32_e32 v241, v168, v243
	v_fmac_f32_e32 v245, v169, v246
	v_fmac_f32_e32 v240, v235, v241
	v_fmac_f32_e32 v244, v235, v245
	v_mul_f32_e32 v102, v102, v240
	v_mul_f32_e32 v103, v103, v244
	v_cvt_pk_bf16_f32 v96, v96, v97
	v_cvt_pk_bf16_f32 v97, v98, v99
	v_cvt_pk_bf16_f32 v98, v100, v101
	v_cvt_pk_bf16_f32 v99, v102, v103
	global_store_dwordx4 v247, v[96:99], s[22:23] offset:0
	v_lshlrev_b32_e32 v240, 16, v206
	v_and_b32_e32 v244, 0xffff0000, v206
	v_sub_f32_e32 v240, v240, v238
	v_sub_f32_e32 v244, v244, v238
	v_mul_f32_e32 v240, v240, v239
	v_mul_f32_e32 v244, v244, v239
	v_fma_f32 v240, v138, v240, v154
	v_fma_f32 v244, v139, v244, v155
	v_lshlrev_b32_e32 v241, 16, v214
	v_and_b32_e32 v245, 0xffff0000, v214
	v_lshlrev_b32_e32 v243, 16, v222
	v_and_b32_e32 v246, 0xffff0000, v222
	v_sub_f32_e32 v243, v243, v241
	v_sub_f32_e32 v246, v246, v245
	v_fmac_f32_e32 v241, v170, v243
	v_fmac_f32_e32 v245, v171, v246
	v_fmac_f32_e32 v240, v235, v241
	v_fmac_f32_e32 v244, v235, v245
	v_mul_f32_e32 v104, v104, v240
	v_mul_f32_e32 v105, v105, v244
	v_lshlrev_b32_e32 v240, 16, v207
	v_and_b32_e32 v244, 0xffff0000, v207
	v_sub_f32_e32 v240, v240, v238
	v_sub_f32_e32 v244, v244, v238
	v_mul_f32_e32 v240, v240, v239
	v_mul_f32_e32 v244, v244, v239
	v_fma_f32 v240, v140, v240, v156
	v_fma_f32 v244, v141, v244, v157
	v_lshlrev_b32_e32 v241, 16, v215
	v_and_b32_e32 v245, 0xffff0000, v215
	v_lshlrev_b32_e32 v243, 16, v223
	v_and_b32_e32 v246, 0xffff0000, v223
	v_sub_f32_e32 v243, v243, v241
	v_sub_f32_e32 v246, v246, v245
	v_fmac_f32_e32 v241, v172, v243
	v_fmac_f32_e32 v245, v173, v246
	v_fmac_f32_e32 v240, v235, v241
	v_fmac_f32_e32 v244, v235, v245
	v_mul_f32_e32 v106, v106, v240
	v_mul_f32_e32 v107, v107, v244
	v_lshlrev_b32_e32 v240, 16, v208
	v_and_b32_e32 v244, 0xffff0000, v208
	v_sub_f32_e32 v240, v240, v238
	v_sub_f32_e32 v244, v244, v238
	v_mul_f32_e32 v240, v240, v239
	v_mul_f32_e32 v244, v244, v239
	v_fma_f32 v240, v142, v240, v158
	v_fma_f32 v244, v143, v244, v159
	v_lshlrev_b32_e32 v241, 16, v216
	v_and_b32_e32 v245, 0xffff0000, v216
	v_lshlrev_b32_e32 v243, 16, v224
	v_and_b32_e32 v246, 0xffff0000, v224
	v_sub_f32_e32 v243, v243, v241
	v_sub_f32_e32 v246, v246, v245
	v_fmac_f32_e32 v241, v174, v243
	v_fmac_f32_e32 v245, v175, v246
	v_fmac_f32_e32 v240, v235, v241
	v_fmac_f32_e32 v244, v235, v245
	v_mul_f32_e32 v108, v108, v240
	v_mul_f32_e32 v109, v109, v244
	v_lshlrev_b32_e32 v240, 16, v209
	v_and_b32_e32 v244, 0xffff0000, v209
	v_sub_f32_e32 v240, v240, v238
	v_sub_f32_e32 v244, v244, v238
	v_mul_f32_e32 v240, v240, v239
	v_mul_f32_e32 v244, v244, v239
	v_fma_f32 v240, v144, v240, v160
	v_fma_f32 v244, v145, v244, v161
	v_lshlrev_b32_e32 v241, 16, v217
	v_and_b32_e32 v245, 0xffff0000, v217
	v_lshlrev_b32_e32 v243, 16, v225
	v_and_b32_e32 v246, 0xffff0000, v225
	v_sub_f32_e32 v243, v243, v241
	v_sub_f32_e32 v246, v246, v245
	v_fmac_f32_e32 v241, v176, v243
	v_fmac_f32_e32 v245, v177, v246
	v_fmac_f32_e32 v240, v235, v241
	v_fmac_f32_e32 v244, v235, v245
	v_mul_f32_e32 v110, v110, v240
	v_mul_f32_e32 v111, v111, v244
	v_cvt_pk_bf16_f32 v104, v104, v105
	v_cvt_pk_bf16_f32 v105, v106, v107
	v_cvt_pk_bf16_f32 v106, v108, v109
	v_cvt_pk_bf16_f32 v107, v110, v111
	global_store_dwordx4 v247, v[104:107], s[22:23] offset:64
	global_load_dwordx4 v[130:133], v233, s[2:3] offset:256
	global_load_dwordx4 v[134:137], v233, s[2:3] offset:272
	global_load_dwordx4 v[138:141], v233, s[2:3] offset:384
	global_load_dwordx4 v[142:145], v233, s[2:3] offset:400
	global_load_dwordx4 v[146:149], v233, s[16:17] offset:256
	global_load_dwordx4 v[150:153], v233, s[16:17] offset:272
	global_load_dwordx4 v[154:157], v233, s[16:17] offset:384
	global_load_dwordx4 v[158:161], v233, s[16:17] offset:400
	global_load_dwordx4 v[162:165], v233, s[0:1] offset:256
	global_load_dwordx4 v[166:169], v233, s[0:1] offset:272
	global_load_dwordx4 v[170:173], v233, s[0:1] offset:384
	global_load_dwordx4 v[174:177], v233, s[0:1] offset:400
	v_add_u32_e32 v236, 0x8000, v230
	v_add_u32_e32 v237, 0x16000, v231
	v_subrev_u32_e32 v240, 0x1600, v237
	global_load_dwordx4 v[202:205], v236, s[22:23] offset:128
	global_load_dwordx4 v[206:209], v236, s[22:23] offset:192
	global_load_dwordx4 v[210:213], v237, s[96:97] offset:128
	global_load_dwordx4 v[214:217], v237, s[96:97] offset:192
	global_load_dwordx4 v[218:221], v240, s[96:97] offset:128
	global_load_dwordx4 v[222:225], v240, s[96:97] offset:192
	v_add_u32_e32 v236, 0xc00, v232
	s_nop 0
	global_load_dword v235, v236, s[96:97] offset:16
	s_waitcnt vmcnt(7)
	s_and_b32 s18, s6, 7
	s_or_b32 s18, s18, s4
	s_cmp_lg_u32 s18, 0
	s_cbranch_scc1 .Lpo_nostart_p4
; __device__ __forceinline__ float bf2f(u16 h) { return __uint_as_float(((unsigned)h) << 16); }
; __device__ __forceinline__ float prevP(const Params& p, const u16* P, int row, int c) {
;   const int rp = row > 0 ? row - 1 : 0;
;   float v = bf2f(P[(size_t)rp * 2816 + 256 + c]);
;   const bool start = (row < NP) ? ((row & 2047) == 0) : (((row - NP) & 3) == 0);
;   if (start) v = (row < NP) ? 0.f : p.in[3][(size_t)((row - NP) >> 2) * 2560 + c];
;   return v;
; template <int EPI> ...
;     ...
;       for (int i = 0; i < 16; i++) {
;         const int rl = rbase + (i & 3) + 8 * (i >> 2);
;         const int row = m0 + rl;
;         float o0 = bf2f(Y[(size_t)row * 1024 + 256 + ch0]);
;         float o1 = bf2f(Y[(size_t)row * 1024 + 256 + ch1]);
;         float mean = hsum32(o0 + o1) * (1.0f / 64.0f);
;         float d0 = o0 - mean, d1 = o1 - mean;
;         float var = hsum32(d0 * d0 + d1 * d1) * (1.0f / 64.0f);
;         float rstd = rsqrtf(var + 64e-5f);
;         float pv0 = bf2f(P[(size_t)row * 2816 + 256 + 1536 + ch0]);
;         float pv1 = bf2f(P[(size_t)row * 2816 + 256 + 1536 + ch1]);
;         float pp0 = prevP(p, P, row, 1536 + ch0), pp1 = prevP(p, P, row, 1536 + ch1);
;         float vv0 = pv0 + (pp0 - pv0) * mu0, vv1 = pv1 + (pp1 - pv1) * mu1;
;         float b = bs[((size_t)row * 12 + hh) * 4 + 2];
;         float y0 = (d0 * rstd * gg0 + gb0 + b * vv0) * acc0[i];
;         float y1 = (d1 * rstd * gg1 + gb1 + b * vv1) * acc1[i];
;         Y[(size_t)row * 1024 + 256 + ch0] = f2bf(y0);
;         Y[(size_t)row * 1024 + 256 + ch1] = f2bf(y1);
;       }
	v_cmp_eq_u32_e32 vcc, 0, v248
	s_nop 1
	v_cndmask_b32_e64 v194, v194, 0, vcc
	v_cndmask_b32_e64 v195, v195, 0, vcc
	v_cndmask_b32_e64 v196, v196, 0, vcc
	v_cndmask_b32_e64 v197, v197, 0, vcc
	v_cndmask_b32_e64 v198, v198, 0, vcc
	v_cndmask_b32_e64 v199, v199, 0, vcc
	v_cndmask_b32_e64 v200, v200, 0, vcc
	v_cndmask_b32_e64 v201, v201, 0, vcc
.Lpo_nostart_p4:
	v_lshlrev_b32_e32 v240, 16, v178
	v_and_b32_e32 v241, 0xffff0000, v178
	v_add_f32_e32 v244, v240, v241
	v_lshlrev_b32_e32 v240, 16, v179
	v_and_b32_e32 v241, 0xffff0000, v179
	v_add_f32_e32 v244, v244, v240
	v_add_f32_e32 v244, v244, v241
	v_lshlrev_b32_e32 v240, 16, v180
	v_and_b32_e32 v241, 0xffff0000, v180
	v_add_f32_e32 v244, v244, v240
	v_add_f32_e32 v244, v244, v241
	v_lshlrev_b32_e32 v240, 16, v181
	v_and_b32_e32 v241, 0xffff0000, v181
	v_add_f32_e32 v244, v244, v240
	v_add_f32_e32 v244, v244, v241
	v_lshlrev_b32_e32 v240, 16, v182
	v_and_b32_e32 v241, 0xffff0000, v182
	v_add_f32_e32 v244, v244, v240
	v_add_f32_e32 v244, v244, v241
	v_lshlrev_b32_e32 v240, 16, v183
	v_and_b32_e32 v241, 0xffff0000, v183
	v_add_f32_e32 v244, v244, v240
	v_add_f32_e32 v244, v244, v241
	v_lshlrev_b32_e32 v240, 16, v184
	v_and_b32_e32 v241, 0xffff0000, v184
	v_add_f32_e32 v244, v244, v240
	v_add_f32_e32 v244, v244, v241
	v_lshlrev_b32_e32 v240, 16, v185
	v_and_b32_e32 v241, 0xffff0000, v185
	v_add_f32_e32 v244, v244, v240
	v_add_f32_e32 v244, v244, v241
	v_mov_b32_e32 v240, v244
	s_nop 1
	v_permlane16_swap_b32_e32 v240, v244
	v_add_f32_e32 v244, v244, v240
	v_mov_b32_e32 v240, v244
	s_nop 1
	v_permlane32_swap_b32_e32 v240, v244
	v_add_f32_e32 v244, v244, v240
	v_mul_f32_e32 v238, 0x3c800000, v244
	v_lshlrev_b32_e32 v240, 16, v178
	v_and_b32_e32 v241, 0xffff0000, v178
	v_sub_f32_e32 v240, v240, v238
	v_sub_f32_e32 v241, v241, v238
	v_mul_f32_e32 v245, v240, v240
	v_fmac_f32_e32 v245, v241, v241
	v_lshlrev_b32_e32 v240, 16, v179
	v_and_b32_e32 v241, 0xffff0000, v179
	v_sub_f32_e32 v240, v240, v238
	v_sub_f32_e32 v241, v241, v238
	v_fmac_f32_e32 v245, v240, v240
	v_fmac_f32_e32 v245, v241, v241
	v_lshlrev_b32_e32 v240, 16, v180
	v_and_b32_e32 v241, 0xffff0000, v180
	v_sub_f32_e32 v240, v240, v238
	v_sub_f32_e32 v241, v241, v238
	v_fmac_f32_e32 v245, v240, v240
	v_fmac_f32_e32 v245, v241, v241
	v_lshlrev_b32_e32 v240, 16, v181
	v_and_b32_e32 v241, 0xffff0000, v181
	v_sub_f32_e32 v240, v240, v238
	v_sub_f32_e32 v241, v241, v238
	v_fmac_f32_e32 v245, v240, v240
	v_fmac_f32_e32 v245, v241, v241
	v_lshlrev_b32_e32 v240, 16, v182
	v_and_b32_e32 v241, 0xffff0000, v182
	v_sub_f32_e32 v240, v240, v238
	v_sub_f32_e32 v241, v241, v238
	v_fmac_f32_e32 v245, v240, v240
	v_fmac_f32_e32 v245, v241, v241
	v_lshlrev_b32_e32 v240, 16, v183
	v_and_b32_e32 v241, 0xffff0000, v183
	v_sub_f32_e32 v240, v240, v238
	v_sub_f32_e32 v241, v241, v238
	v_fmac_f32_e32 v245, v240, v240
	v_fmac_f32_e32 v245, v241, v241
	v_lshlrev_b32_e32 v240, 16, v184
	v_and_b32_e32 v241, 0xffff0000, v184
	v_sub_f32_e32 v240, v240, v238
	v_sub_f32_e32 v241, v241, v238
	v_fmac_f32_e32 v245, v240, v240
	v_fmac_f32_e32 v245, v241, v241
	v_lshlrev_b32_e32 v240, 16, v185
	v_and_b32_e32 v241, 0xffff0000, v185
	v_sub_f32_e32 v240, v240, v238
	v_sub_f32_e32 v241, v241, v238
	v_fmac_f32_e32 v245, v240, v240
	v_fmac_f32_e32 v245, v241, v241
	v_mov_b32_e32 v240, v245
	s_nop 1
	v_permlane16_swap_b32_e32 v240, v245
	v_add_f32_e32 v245, v245, v240
	v_mov_b32_e32 v240, v245
	s_nop 1
	v_permlane32_swap_b32_e32 v240, v245
	v_add_f32_e32 v245, v245, v240
	v_mov_b32_e32 v240, 0x3a27c5ac
	v_fmamk_f32 v245, v245, 0x3c800000, v240
	v_rsq_f32_e32 v239, v245
	v_add_u32_e32 v247, 0x0, v230
	v_lshlrev_b32_e32 v240, 16, v178
	v_and_b32_e32 v244, 0xffff0000, v178
	v_sub_f32_e32 v240, v240, v238
	v_sub_f32_e32 v244, v244, v238
	v_mul_f32_e32 v240, v240, v239
	v_mul_f32_e32 v244, v244, v239
	v_fma_f32 v240, v130, v240, v146
	v_fma_f32 v244, v131, v244, v147
	v_lshlrev_b32_e32 v241, 16, v186
	v_and_b32_e32 v245, 0xffff0000, v186
	v_lshlrev_b32_e32 v243, 16, v194
	v_and_b32_e32 v246, 0xffff0000, v194
	v_sub_f32_e32 v243, v243, v241
	v_sub_f32_e32 v246, v246, v245
	v_fmac_f32_e32 v241, v162, v243
	v_fmac_f32_e32 v245, v163, v246
	v_fmac_f32_e32 v240, v234, v241
	v_fmac_f32_e32 v244, v234, v245
	v_mul_f32_e32 v16, v16, v240
	v_mul_f32_e32 v17, v17, v244
	v_lshlrev_b32_e32 v240, 16, v179
	v_and_b32_e32 v244, 0xffff0000, v179
	v_sub_f32_e32 v240, v240, v238
	v_sub_f32_e32 v244, v244, v238
	v_mul_f32_e32 v240, v240, v239
	v_mul_f32_e32 v244, v244, v239
	v_fma_f32 v240, v132, v240, v148
	v_fma_f32 v244, v133, v244, v149
	v_lshlrev_b32_e32 v241, 16, v187
	v_and_b32_e32 v245, 0xffff0000, v187
	v_lshlrev_b32_e32 v243, 16, v195
	v_and_b32_e32 v246, 0xffff0000, v195
	v_sub_f32_e32 v243, v243, v241
	v_sub_f32_e32 v246, v246, v245
	v_fmac_f32_e32 v241, v164, v243
	v_fmac_f32_e32 v245, v165, v246
	v_fmac_f32_e32 v240, v234, v241
	v_fmac_f32_e32 v244, v234, v245
	v_mul_f32_e32 v18, v18, v240
	v_mul_f32_e32 v19, v19, v244
	v_lshlrev_b32_e32 v240, 16, v180
	v_and_b32_e32 v244, 0xffff0000, v180
	v_sub_f32_e32 v240, v240, v238
	v_sub_f32_e32 v244, v244, v238
	v_mul_f32_e32 v240, v240, v239
	v_mul_f32_e32 v244, v244, v239
	v_fma_f32 v240, v134, v240, v150
	v_fma_f32 v244, v135, v244, v151
	v_lshlrev_b32_e32 v241, 16, v188
	v_and_b32_e32 v245, 0xffff0000, v188
	v_lshlrev_b32_e32 v243, 16, v196
	v_and_b32_e32 v246, 0xffff0000, v196
	v_sub_f32_e32 v243, v243, v241
	v_sub_f32_e32 v246, v246, v245
	v_fmac_f32_e32 v241, v166, v243
	v_fmac_f32_e32 v245, v167, v246
	v_fmac_f32_e32 v240, v234, v241
	v_fmac_f32_e32 v244, v234, v245
	v_mul_f32_e32 v20, v20, v240
	v_mul_f32_e32 v21, v21, v244
; __device__ __forceinline__ float bf2f(u16 h) { return __uint_as_float(((unsigned)h) << 16); }
; template <int EPI> ...
;     ...
;       for (int i = 0; i < 16; i++) {
;         const int rl = rbase + (i & 3) + 8 * (i >> 2);
;         const int row = m0 + rl;
;         float o0 = bf2f(Y[(size_t)row * 1024 + 256 + ch0]);
;         float o1 = bf2f(Y[(size_t)row * 1024 + 256 + ch1]);
;         float mean = hsum32(o0 + o1) * (1.0f / 64.0f);
;         float d0 = o0 - mean, d1 = o1 - mean;
;         float var = hsum32(d0 * d0 + d1 * d1) * (1.0f / 64.0f);
;         float rstd = rsqrtf(var + 64e-5f);
;         float pv0 = bf2f(P[(size_t)row * 2816 + 256 + 1536 + ch0]);
;         float pv1 = bf2f(P[(size_t)row * 2816 + 256 + 1536 + ch1]);
;         float pp0 = prevP(p, P, row, 1536 + ch0), pp1 = prevP(p, P, row, 1536 + ch1);
;         float vv0 = pv0 + (pp0 - pv0) * mu0, vv1 = pv1 + (pp1 - pv1) * mu1;
;         float b = bs[((size_t)row * 12 + hh) * 4 + 2];
;         float y0 = (d0 * rstd * gg0 + gb0 + b * vv0) * acc0[i];
;         float y1 = (d1 * rstd * gg1 + gb1 + b * vv1) * acc1[i];
;         Y[(size_t)row * 1024 + 256 + ch0] = f2bf(y0);
;         Y[(size_t)row * 1024 + 256 + ch1] = f2bf(y1);
;       }
	v_lshlrev_b32_e32 v240, 16, v181
	v_and_b32_e32 v244, 0xffff0000, v181
	v_sub_f32_e32 v240, v240, v238
	v_sub_f32_e32 v244, v244, v238
	v_mul_f32_e32 v240, v240, v239
	v_mul_f32_e32 v244, v244, v239
	v_fma_f32 v240, v136, v240, v152
	v_fma_f32 v244, v137, v244, v153
	v_lshlrev_b32_e32 v241, 16, v189
	v_and_b32_e32 v245, 0xffff0000, v189
	v_lshlrev_b32_e32 v243, 16, v197
	v_and_b32_e32 v246, 0xffff0000, v197
	v_sub_f32_e32 v243, v243, v241
	v_sub_f32_e32 v246, v246, v245
	v_fmac_f32_e32 v241, v168, v243
	v_fmac_f32_e32 v245, v169, v246
	v_fmac_f32_e32 v240, v234, v241
	v_fmac_f32_e32 v244, v234, v245
	v_mul_f32_e32 v22, v22, v240
	v_mul_f32_e32 v23, v23, v244
	v_cvt_pk_bf16_f32 v16, v16, v17
	v_cvt_pk_bf16_f32 v17, v18, v19
	v_cvt_pk_bf16_f32 v18, v20, v21
	v_cvt_pk_bf16_f32 v19, v22, v23
	global_store_dwordx4 v247, v[16:19], s[22:23] offset:128
	v_lshlrev_b32_e32 v240, 16, v182
	v_and_b32_e32 v244, 0xffff0000, v182
	v_sub_f32_e32 v240, v240, v238
	v_sub_f32_e32 v244, v244, v238
	v_mul_f32_e32 v240, v240, v239
	v_mul_f32_e32 v244, v244, v239
	v_fma_f32 v240, v138, v240, v154
	v_fma_f32 v244, v139, v244, v155
	v_lshlrev_b32_e32 v241, 16, v190
	v_and_b32_e32 v245, 0xffff0000, v190
	v_lshlrev_b32_e32 v243, 16, v198
	v_and_b32_e32 v246, 0xffff0000, v198
	v_sub_f32_e32 v243, v243, v241
	v_sub_f32_e32 v246, v246, v245
	v_fmac_f32_e32 v241, v170, v243
	v_fmac_f32_e32 v245, v171, v246
	v_fmac_f32_e32 v240, v234, v241
	v_fmac_f32_e32 v244, v234, v245
	v_mul_f32_e32 v24, v24, v240
	v_mul_f32_e32 v25, v25, v244
	v_lshlrev_b32_e32 v240, 16, v183
	v_and_b32_e32 v244, 0xffff0000, v183
	v_sub_f32_e32 v240, v240, v238
	v_sub_f32_e32 v244, v244, v238
	v_mul_f32_e32 v240, v240, v239
	v_mul_f32_e32 v244, v244, v239
	v_fma_f32 v240, v140, v240, v156
	v_fma_f32 v244, v141, v244, v157
	v_lshlrev_b32_e32 v241, 16, v191
	v_and_b32_e32 v245, 0xffff0000, v191
	v_lshlrev_b32_e32 v243, 16, v199
	v_and_b32_e32 v246, 0xffff0000, v199
	v_sub_f32_e32 v243, v243, v241
	v_sub_f32_e32 v246, v246, v245
	v_fmac_f32_e32 v241, v172, v243
	v_fmac_f32_e32 v245, v173, v246
	v_fmac_f32_e32 v240, v234, v241
	v_fmac_f32_e32 v244, v234, v245
	v_mul_f32_e32 v26, v26, v240
	v_mul_f32_e32 v27, v27, v244
	v_lshlrev_b32_e32 v240, 16, v184
	v_and_b32_e32 v244, 0xffff0000, v184
	v_sub_f32_e32 v240, v240, v238
	v_sub_f32_e32 v244, v244, v238
	v_mul_f32_e32 v240, v240, v239
	v_mul_f32_e32 v244, v244, v239
	v_fma_f32 v240, v142, v240, v158
	v_fma_f32 v244, v143, v244, v159
	v_lshlrev_b32_e32 v241, 16, v192
	v_and_b32_e32 v245, 0xffff0000, v192
	v_lshlrev_b32_e32 v243, 16, v200
	v_and_b32_e32 v246, 0xffff0000, v200
	v_sub_f32_e32 v243, v243, v241
	v_sub_f32_e32 v246, v246, v245
	v_fmac_f32_e32 v241, v174, v243
	v_fmac_f32_e32 v245, v175, v246
	v_fmac_f32_e32 v240, v234, v241
	v_fmac_f32_e32 v244, v234, v245
	v_mul_f32_e32 v28, v28, v240
	v_mul_f32_e32 v29, v29, v244
	v_lshlrev_b32_e32 v240, 16, v185
	v_and_b32_e32 v244, 0xffff0000, v185
	v_sub_f32_e32 v240, v240, v238
	v_sub_f32_e32 v244, v244, v238
	v_mul_f32_e32 v240, v240, v239
	v_mul_f32_e32 v244, v244, v239
	v_fma_f32 v240, v144, v240, v160
	v_fma_f32 v244, v145, v244, v161
	v_lshlrev_b32_e32 v241, 16, v193
	v_and_b32_e32 v245, 0xffff0000, v193
	v_lshlrev_b32_e32 v243, 16, v201
	v_and_b32_e32 v246, 0xffff0000, v201
	v_sub_f32_e32 v243, v243, v241
	v_sub_f32_e32 v246, v246, v245
	v_fmac_f32_e32 v241, v176, v243
	v_fmac_f32_e32 v245, v177, v246
	v_fmac_f32_e32 v240, v234, v241
	v_fmac_f32_e32 v244, v234, v245
	v_mul_f32_e32 v30, v30, v240
	v_mul_f32_e32 v31, v31, v244
	v_cvt_pk_bf16_f32 v24, v24, v25
	v_cvt_pk_bf16_f32 v25, v26, v27
	v_cvt_pk_bf16_f32 v26, v28, v29
	v_cvt_pk_bf16_f32 v27, v30, v31
	global_store_dwordx4 v247, v[24:27], s[22:23] offset:192
	v_add_u32_e32 v236, 0x10000, v230
	v_add_u32_e32 v237, 0x2c000, v231
	v_subrev_u32_e32 v240, 0x1600, v237
	global_load_dwordx4 v[178:181], v236, s[22:23] offset:128
	global_load_dwordx4 v[182:185], v236, s[22:23] offset:192
	global_load_dwordx4 v[186:189], v237, s[96:97] offset:128
	global_load_dwordx4 v[190:193], v237, s[96:97] offset:192
	global_load_dwordx4 v[194:197], v240, s[96:97] offset:128
	global_load_dwordx4 v[198:201], v240, s[96:97] offset:192
	v_add_u32_e32 v236, 0x1800, v232
	s_nop 0
	global_load_dword v234, v236, s[96:97] offset:16
	s_waitcnt vmcnt(9)
; __device__ __forceinline__ float bf2f(u16 h) { return __uint_as_float(((unsigned)h) << 16); }
; template <int EPI> ...
;     ...
;       for (int i = 0; i < 16; i++) {
;         const int rl = rbase + (i & 3) + 8 * (i >> 2);
;         const int row = m0 + rl;
;         float o0 = bf2f(Y[(size_t)row * 1024 + 256 + ch0]);
;         float o1 = bf2f(Y[(size_t)row * 1024 + 256 + ch1]);
;         float mean = hsum32(o0 + o1) * (1.0f / 64.0f);
;         float d0 = o0 - mean, d1 = o1 - mean;
;         float var = hsum32(d0 * d0 + d1 * d1) * (1.0f / 64.0f);
;         float rstd = rsqrtf(var + 64e-5f);
;         float pv0 = bf2f(P[(size_t)row * 2816 + 256 + 1536 + ch0]);
;         float pv1 = bf2f(P[(size_t)row * 2816 + 256 + 1536 + ch1]);
;         float pp0 = prevP(p, P, row, 1536 + ch0), pp1 = prevP(p, P, row, 1536 + ch1);
;         float vv0 = pv0 + (pp0 - pv0) * mu0, vv1 = pv1 + (pp1 - pv1) * mu1;
;         float b = bs[((size_t)row * 12 + hh) * 4 + 2];
;         float y0 = (d0 * rstd * gg0 + gb0 + b * vv0) * acc0[i];
;         float y1 = (d1 * rstd * gg1 + gb1 + b * vv1) * acc1[i];
;         Y[(size_t)row * 1024 + 256 + ch0] = f2bf(y0);
;         Y[(size_t)row * 1024 + 256 + ch1] = f2bf(y1);
;       }
	v_lshlrev_b32_e32 v240, 16, v202
	v_and_b32_e32 v241, 0xffff0000, v202
	v_add_f32_e32 v244, v240, v241
	v_lshlrev_b32_e32 v240, 16, v203
	v_and_b32_e32 v241, 0xffff0000, v203
	v_add_f32_e32 v244, v244, v240
	v_add_f32_e32 v244, v244, v241
	v_lshlrev_b32_e32 v240, 16, v204
	v_and_b32_e32 v241, 0xffff0000, v204
	v_add_f32_e32 v244, v244, v240
	v_add_f32_e32 v244, v244, v241
	v_lshlrev_b32_e32 v240, 16, v205
	v_and_b32_e32 v241, 0xffff0000, v205
	v_add_f32_e32 v244, v244, v240
	v_add_f32_e32 v244, v244, v241
	v_lshlrev_b32_e32 v240, 16, v206
	v_and_b32_e32 v241, 0xffff0000, v206
	v_add_f32_e32 v244, v244, v240
	v_add_f32_e32 v244, v244, v241
	v_lshlrev_b32_e32 v240, 16, v207
	v_and_b32_e32 v241, 0xffff0000, v207
	v_add_f32_e32 v244, v244, v240
	v_add_f32_e32 v244, v244, v241
	v_lshlrev_b32_e32 v240, 16, v208
	v_and_b32_e32 v241, 0xffff0000, v208
	v_add_f32_e32 v244, v244, v240
	v_add_f32_e32 v244, v244, v241
	v_lshlrev_b32_e32 v240, 16, v209
	v_and_b32_e32 v241, 0xffff0000, v209
	v_add_f32_e32 v244, v244, v240
	v_add_f32_e32 v244, v244, v241
	v_mov_b32_e32 v240, v244
	s_nop 1
	v_permlane16_swap_b32_e32 v240, v244
	v_add_f32_e32 v244, v244, v240
	v_mov_b32_e32 v240, v244
	s_nop 1
	v_permlane32_swap_b32_e32 v240, v244
	v_add_f32_e32 v244, v244, v240
	v_mul_f32_e32 v238, 0x3c800000, v244
	v_lshlrev_b32_e32 v240, 16, v202
	v_and_b32_e32 v241, 0xffff0000, v202
	v_sub_f32_e32 v240, v240, v238
	v_sub_f32_e32 v241, v241, v238
	v_mul_f32_e32 v245, v240, v240
	v_fmac_f32_e32 v245, v241, v241
	v_lshlrev_b32_e32 v240, 16, v203
	v_and_b32_e32 v241, 0xffff0000, v203
	v_sub_f32_e32 v240, v240, v238
	v_sub_f32_e32 v241, v241, v238
	v_fmac_f32_e32 v245, v240, v240
	v_fmac_f32_e32 v245, v241, v241
	v_lshlrev_b32_e32 v240, 16, v204
	v_and_b32_e32 v241, 0xffff0000, v204
	v_sub_f32_e32 v240, v240, v238
	v_sub_f32_e32 v241, v241, v238
	v_fmac_f32_e32 v245, v240, v240
	v_fmac_f32_e32 v245, v241, v241
	v_lshlrev_b32_e32 v240, 16, v205
	v_and_b32_e32 v241, 0xffff0000, v205
	v_sub_f32_e32 v240, v240, v238
	v_sub_f32_e32 v241, v241, v238
	v_fmac_f32_e32 v245, v240, v240
	v_fmac_f32_e32 v245, v241, v241
	v_lshlrev_b32_e32 v240, 16, v206
	v_and_b32_e32 v241, 0xffff0000, v206
	v_sub_f32_e32 v240, v240, v238
	v_sub_f32_e32 v241, v241, v238
	v_fmac_f32_e32 v245, v240, v240
	v_fmac_f32_e32 v245, v241, v241
	v_lshlrev_b32_e32 v240, 16, v207
	v_and_b32_e32 v241, 0xffff0000, v207
	v_sub_f32_e32 v240, v240, v238
	v_sub_f32_e32 v241, v241, v238
	v_fmac_f32_e32 v245, v240, v240
	v_fmac_f32_e32 v245, v241, v241
	v_lshlrev_b32_e32 v240, 16, v208
	v_and_b32_e32 v241, 0xffff0000, v208
	v_sub_f32_e32 v240, v240, v238
	v_sub_f32_e32 v241, v241, v238
	v_fmac_f32_e32 v245, v240, v240
	v_fmac_f32_e32 v245, v241, v241
	v_lshlrev_b32_e32 v240, 16, v209
	v_and_b32_e32 v241, 0xffff0000, v209
	v_sub_f32_e32 v240, v240, v238
	v_sub_f32_e32 v241, v241, v238
	v_fmac_f32_e32 v245, v240, v240
	v_fmac_f32_e32 v245, v241, v241
	v_mov_b32_e32 v240, v245
	s_nop 1
	v_permlane16_swap_b32_e32 v240, v245
	v_add_f32_e32 v245, v245, v240
	v_mov_b32_e32 v240, v245
	s_nop 1
	v_permlane32_swap_b32_e32 v240, v245
	v_add_f32_e32 v245, v245, v240
	v_mov_b32_e32 v240, 0x3a27c5ac
	v_fmamk_f32 v245, v245, 0x3c800000, v240
	v_rsq_f32_e32 v239, v245
	v_add_u32_e32 v247, 0x8000, v230
	v_lshlrev_b32_e32 v240, 16, v202
	v_and_b32_e32 v244, 0xffff0000, v202
	v_sub_f32_e32 v240, v240, v238
	v_sub_f32_e32 v244, v244, v238
	v_mul_f32_e32 v240, v240, v239
	v_mul_f32_e32 v244, v244, v239
	v_fma_f32 v240, v130, v240, v146
	v_fma_f32 v244, v131, v244, v147
	v_lshlrev_b32_e32 v241, 16, v210
	v_and_b32_e32 v245, 0xffff0000, v210
	v_lshlrev_b32_e32 v243, 16, v218
	v_and_b32_e32 v246, 0xffff0000, v218
	v_sub_f32_e32 v243, v243, v241
	v_sub_f32_e32 v246, v246, v245
	v_fmac_f32_e32 v241, v162, v243
	v_fmac_f32_e32 v245, v163, v246
	v_fmac_f32_e32 v240, v235, v241
	v_fmac_f32_e32 v244, v235, v245
	v_mul_f32_e32 v48, v48, v240
	v_mul_f32_e32 v49, v49, v244
	v_lshlrev_b32_e32 v240, 16, v203
	v_and_b32_e32 v244, 0xffff0000, v203
	v_sub_f32_e32 v240, v240, v238
	v_sub_f32_e32 v244, v244, v238
	v_mul_f32_e32 v240, v240, v239
	v_mul_f32_e32 v244, v244, v239
	v_fma_f32 v240, v132, v240, v148
	v_fma_f32 v244, v133, v244, v149
	v_lshlrev_b32_e32 v241, 16, v211
	v_and_b32_e32 v245, 0xffff0000, v211
	v_lshlrev_b32_e32 v243, 16, v219
	v_and_b32_e32 v246, 0xffff0000, v219
	v_sub_f32_e32 v243, v243, v241
	v_sub_f32_e32 v246, v246, v245
	v_fmac_f32_e32 v241, v164, v243
	v_fmac_f32_e32 v245, v165, v246
	v_fmac_f32_e32 v240, v235, v241
	v_fmac_f32_e32 v244, v235, v245
	v_mul_f32_e32 v50, v50, v240
	v_mul_f32_e32 v51, v51, v244
	v_lshlrev_b32_e32 v240, 16, v204
	v_and_b32_e32 v244, 0xffff0000, v204
	v_sub_f32_e32 v240, v240, v238
	v_sub_f32_e32 v244, v244, v238
	v_mul_f32_e32 v240, v240, v239
	v_mul_f32_e32 v244, v244, v239
	v_fma_f32 v240, v134, v240, v150
	v_fma_f32 v244, v135, v244, v151
	v_lshlrev_b32_e32 v241, 16, v212
	v_and_b32_e32 v245, 0xffff0000, v212
	v_lshlrev_b32_e32 v243, 16, v220
	v_and_b32_e32 v246, 0xffff0000, v220
	v_sub_f32_e32 v243, v243, v241
	v_sub_f32_e32 v246, v246, v245
	v_fmac_f32_e32 v241, v166, v243
	v_fmac_f32_e32 v245, v167, v246
	v_fmac_f32_e32 v240, v235, v241
	v_fmac_f32_e32 v244, v235, v245
	v_mul_f32_e32 v52, v52, v240
	v_mul_f32_e32 v53, v53, v244
	v_lshlrev_b32_e32 v240, 16, v205
	v_and_b32_e32 v244, 0xffff0000, v205
	v_sub_f32_e32 v240, v240, v238
	v_sub_f32_e32 v244, v244, v238
	v_mul_f32_e32 v240, v240, v239
	v_mul_f32_e32 v244, v244, v239
	v_fma_f32 v240, v136, v240, v152
	v_fma_f32 v244, v137, v244, v153
	v_lshlrev_b32_e32 v241, 16, v213
	v_and_b32_e32 v245, 0xffff0000, v213
	v_lshlrev_b32_e32 v243, 16, v221
; __device__ __forceinline__ float bf2f(u16 h) { return __uint_as_float(((unsigned)h) << 16); }
; template <int EPI> ...
;     ...
;       for (int i = 0; i < 16; i++) {
;         const int rl = rbase + (i & 3) + 8 * (i >> 2);
;         const int row = m0 + rl;
;         float o0 = bf2f(Y[(size_t)row * 1024 + 256 + ch0]);
;         float o1 = bf2f(Y[(size_t)row * 1024 + 256 + ch1]);
;         float mean = hsum32(o0 + o1) * (1.0f / 64.0f);
;         float d0 = o0 - mean, d1 = o1 - mean;
;         float var = hsum32(d0 * d0 + d1 * d1) * (1.0f / 64.0f);
;         float rstd = rsqrtf(var + 64e-5f);
;         float pv0 = bf2f(P[(size_t)row * 2816 + 256 + 1536 + ch0]);
;         float pv1 = bf2f(P[(size_t)row * 2816 + 256 + 1536 + ch1]);
;         float pp0 = prevP(p, P, row, 1536 + ch0), pp1 = prevP(p, P, row, 1536 + ch1);
;         float vv0 = pv0 + (pp0 - pv0) * mu0, vv1 = pv1 + (pp1 - pv1) * mu1;
;         float b = bs[((size_t)row * 12 + hh) * 4 + 2];
;         float y0 = (d0 * rstd * gg0 + gb0 + b * vv0) * acc0[i];
;         float y1 = (d1 * rstd * gg1 + gb1 + b * vv1) * acc1[i];
;         Y[(size_t)row * 1024 + 256 + ch0] = f2bf(y0);
;         Y[(size_t)row * 1024 + 256 + ch1] = f2bf(y1);
;       }
	v_and_b32_e32 v246, 0xffff0000, v221
	v_sub_f32_e32 v243, v243, v241
	v_sub_f32_e32 v246, v246, v245
	v_fmac_f32_e32 v241, v168, v243
	v_fmac_f32_e32 v245, v169, v246
	v_fmac_f32_e32 v240, v235, v241
	v_fmac_f32_e32 v244, v235, v245
	v_mul_f32_e32 v54, v54, v240
	v_mul_f32_e32 v55, v55, v244
	v_cvt_pk_bf16_f32 v48, v48, v49
	v_cvt_pk_bf16_f32 v49, v50, v51
	v_cvt_pk_bf16_f32 v50, v52, v53
	v_cvt_pk_bf16_f32 v51, v54, v55
	global_store_dwordx4 v247, v[48:51], s[22:23] offset:128
	v_lshlrev_b32_e32 v240, 16, v206
	v_and_b32_e32 v244, 0xffff0000, v206
	v_sub_f32_e32 v240, v240, v238
	v_sub_f32_e32 v244, v244, v238
	v_mul_f32_e32 v240, v240, v239
	v_mul_f32_e32 v244, v244, v239
	v_fma_f32 v240, v138, v240, v154
	v_fma_f32 v244, v139, v244, v155
	v_lshlrev_b32_e32 v241, 16, v214
	v_and_b32_e32 v245, 0xffff0000, v214
	v_lshlrev_b32_e32 v243, 16, v222
	v_and_b32_e32 v246, 0xffff0000, v222
	v_sub_f32_e32 v243, v243, v241
	v_sub_f32_e32 v246, v246, v245
	v_fmac_f32_e32 v241, v170, v243
	v_fmac_f32_e32 v245, v171, v246
	v_fmac_f32_e32 v240, v235, v241
	v_fmac_f32_e32 v244, v235, v245
	v_mul_f32_e32 v56, v56, v240
	v_mul_f32_e32 v57, v57, v244
	v_lshlrev_b32_e32 v240, 16, v207
	v_and_b32_e32 v244, 0xffff0000, v207
	v_sub_f32_e32 v240, v240, v238
	v_sub_f32_e32 v244, v244, v238
	v_mul_f32_e32 v240, v240, v239
	v_mul_f32_e32 v244, v244, v239
	v_fma_f32 v240, v140, v240, v156
	v_fma_f32 v244, v141, v244, v157
	v_lshlrev_b32_e32 v241, 16, v215
	v_and_b32_e32 v245, 0xffff0000, v215
	v_lshlrev_b32_e32 v243, 16, v223
	v_and_b32_e32 v246, 0xffff0000, v223
	v_sub_f32_e32 v243, v243, v241
	v_sub_f32_e32 v246, v246, v245
	v_fmac_f32_e32 v241, v172, v243
	v_fmac_f32_e32 v245, v173, v246
	v_fmac_f32_e32 v240, v235, v241
	v_fmac_f32_e32 v244, v235, v245
	v_mul_f32_e32 v58, v58, v240
	v_mul_f32_e32 v59, v59, v244
	v_lshlrev_b32_e32 v240, 16, v208
	v_and_b32_e32 v244, 0xffff0000, v208
	v_sub_f32_e32 v240, v240, v238
	v_sub_f32_e32 v244, v244, v238
	v_mul_f32_e32 v240, v240, v239
	v_mul_f32_e32 v244, v244, v239
	v_fma_f32 v240, v142, v240, v158
	v_fma_f32 v244, v143, v244, v159
	v_lshlrev_b32_e32 v241, 16, v216
	v_and_b32_e32 v245, 0xffff0000, v216
	v_lshlrev_b32_e32 v243, 16, v224
	v_and_b32_e32 v246, 0xffff0000, v224
	v_sub_f32_e32 v243, v243, v241
	v_sub_f32_e32 v246, v246, v245
	v_fmac_f32_e32 v241, v174, v243
	v_fmac_f32_e32 v245, v175, v246
	v_fmac_f32_e32 v240, v235, v241
	v_fmac_f32_e32 v244, v235, v245
	v_mul_f32_e32 v60, v60, v240
	v_mul_f32_e32 v61, v61, v244
	v_lshlrev_b32_e32 v240, 16, v209
	v_and_b32_e32 v244, 0xffff0000, v209
	v_sub_f32_e32 v240, v240, v238
	v_sub_f32_e32 v244, v244, v238
	v_mul_f32_e32 v240, v240, v239
	v_mul_f32_e32 v244, v244, v239
	v_fma_f32 v240, v144, v240, v160
	v_fma_f32 v244, v145, v244, v161
	v_lshlrev_b32_e32 v241, 16, v217
	v_and_b32_e32 v245, 0xffff0000, v217
	v_lshlrev_b32_e32 v243, 16, v225
	v_and_b32_e32 v246, 0xffff0000, v225
	v_sub_f32_e32 v243, v243, v241
	v_sub_f32_e32 v246, v246, v245
	v_fmac_f32_e32 v241, v176, v243
	v_fmac_f32_e32 v245, v177, v246
	v_fmac_f32_e32 v240, v235, v241
	v_fmac_f32_e32 v244, v235, v245
	v_mul_f32_e32 v62, v62, v240
	v_mul_f32_e32 v63, v63, v244
	v_cvt_pk_bf16_f32 v56, v56, v57
	v_cvt_pk_bf16_f32 v57, v58, v59
	v_cvt_pk_bf16_f32 v58, v60, v61
	v_cvt_pk_bf16_f32 v59, v62, v63
	global_store_dwordx4 v247, v[56:59], s[22:23] offset:192
	v_add_u32_e32 v236, 0x18000, v230
	v_add_u32_e32 v237, 0x42000, v231
	v_subrev_u32_e32 v240, 0x1600, v237
	global_load_dwordx4 v[202:205], v236, s[22:23] offset:128
	global_load_dwordx4 v[206:209], v236, s[22:23] offset:192
	global_load_dwordx4 v[210:213], v237, s[96:97] offset:128
	global_load_dwordx4 v[214:217], v237, s[96:97] offset:192
	global_load_dwordx4 v[218:221], v240, s[96:97] offset:128
	global_load_dwordx4 v[222:225], v240, s[96:97] offset:192
	v_add_u32_e32 v236, 0x2400, v232
	s_nop 0
	global_load_dword v235, v236, s[96:97] offset:16
	s_waitcnt vmcnt(9)
	v_lshlrev_b32_e32 v240, 16, v178
	v_and_b32_e32 v241, 0xffff0000, v178
	v_add_f32_e32 v244, v240, v241
	v_lshlrev_b32_e32 v240, 16, v179
	v_and_b32_e32 v241, 0xffff0000, v179
	v_add_f32_e32 v244, v244, v240
	v_add_f32_e32 v244, v244, v241
	v_lshlrev_b32_e32 v240, 16, v180
	v_and_b32_e32 v241, 0xffff0000, v180
	v_add_f32_e32 v244, v244, v240
	v_add_f32_e32 v244, v244, v241
	v_lshlrev_b32_e32 v240, 16, v181
	v_and_b32_e32 v241, 0xffff0000, v181
	v_add_f32_e32 v244, v244, v240
	v_add_f32_e32 v244, v244, v241
	v_lshlrev_b32_e32 v240, 16, v182
	v_and_b32_e32 v241, 0xffff0000, v182
	v_add_f32_e32 v244, v244, v240
	v_add_f32_e32 v244, v244, v241
	v_lshlrev_b32_e32 v240, 16, v183
	v_and_b32_e32 v241, 0xffff0000, v183
	v_add_f32_e32 v244, v244, v240
	v_add_f32_e32 v244, v244, v241
	v_lshlrev_b32_e32 v240, 16, v184
	v_and_b32_e32 v241, 0xffff0000, v184
	v_add_f32_e32 v244, v244, v240
	v_add_f32_e32 v244, v244, v241
	v_lshlrev_b32_e32 v240, 16, v185
	v_and_b32_e32 v241, 0xffff0000, v185
	v_add_f32_e32 v244, v244, v240
	v_add_f32_e32 v244, v244, v241
	v_mov_b32_e32 v240, v244
	s_nop 1
	v_permlane16_swap_b32_e32 v240, v244
	v_add_f32_e32 v244, v244, v240
	v_mov_b32_e32 v240, v244
	s_nop 1
	v_permlane32_swap_b32_e32 v240, v244
	v_add_f32_e32 v244, v244, v240
	v_mul_f32_e32 v238, 0x3c800000, v244
	v_lshlrev_b32_e32 v240, 16, v178
	v_and_b32_e32 v241, 0xffff0000, v178
	v_sub_f32_e32 v240, v240, v238
	v_sub_f32_e32 v241, v241, v238
	v_mul_f32_e32 v245, v240, v240
	v_fmac_f32_e32 v245, v241, v241
	v_lshlrev_b32_e32 v240, 16, v179
	v_and_b32_e32 v241, 0xffff0000, v179
	v_sub_f32_e32 v240, v240, v238
	v_sub_f32_e32 v241, v241, v238
	v_fmac_f32_e32 v245, v240, v240
	v_fmac_f32_e32 v245, v241, v241
; __device__ __forceinline__ float bf2f(u16 h) { return __uint_as_float(((unsigned)h) << 16); }
; template <int EPI> ...
;     ...
;       for (int i = 0; i < 16; i++) {
;         const int rl = rbase + (i & 3) + 8 * (i >> 2);
;         const int row = m0 + rl;
;         float o0 = bf2f(Y[(size_t)row * 1024 + 256 + ch0]);
;         float o1 = bf2f(Y[(size_t)row * 1024 + 256 + ch1]);
;         float mean = hsum32(o0 + o1) * (1.0f / 64.0f);
;         float d0 = o0 - mean, d1 = o1 - mean;
;         float var = hsum32(d0 * d0 + d1 * d1) * (1.0f / 64.0f);
;         float rstd = rsqrtf(var + 64e-5f);
;         float pv0 = bf2f(P[(size_t)row * 2816 + 256 + 1536 + ch0]);
;         float pv1 = bf2f(P[(size_t)row * 2816 + 256 + 1536 + ch1]);
;         float pp0 = prevP(p, P, row, 1536 + ch0), pp1 = prevP(p, P, row, 1536 + ch1);
;         float vv0 = pv0 + (pp0 - pv0) * mu0, vv1 = pv1 + (pp1 - pv1) * mu1;
;         float b = bs[((size_t)row * 12 + hh) * 4 + 2];
;         float y0 = (d0 * rstd * gg0 + gb0 + b * vv0) * acc0[i];
;         float y1 = (d1 * rstd * gg1 + gb1 + b * vv1) * acc1[i];
;         Y[(size_t)row * 1024 + 256 + ch0] = f2bf(y0);
;         Y[(size_t)row * 1024 + 256 + ch1] = f2bf(y1);
;       }
	v_lshlrev_b32_e32 v240, 16, v180
	v_and_b32_e32 v241, 0xffff0000, v180
	v_sub_f32_e32 v240, v240, v238
	v_sub_f32_e32 v241, v241, v238
	v_fmac_f32_e32 v245, v240, v240
	v_fmac_f32_e32 v245, v241, v241
	v_lshlrev_b32_e32 v240, 16, v181
	v_and_b32_e32 v241, 0xffff0000, v181
	v_sub_f32_e32 v240, v240, v238
	v_sub_f32_e32 v241, v241, v238
	v_fmac_f32_e32 v245, v240, v240
	v_fmac_f32_e32 v245, v241, v241
	v_lshlrev_b32_e32 v240, 16, v182
	v_and_b32_e32 v241, 0xffff0000, v182
	v_sub_f32_e32 v240, v240, v238
	v_sub_f32_e32 v241, v241, v238
	v_fmac_f32_e32 v245, v240, v240
	v_fmac_f32_e32 v245, v241, v241
	v_lshlrev_b32_e32 v240, 16, v183
	v_and_b32_e32 v241, 0xffff0000, v183
	v_sub_f32_e32 v240, v240, v238
	v_sub_f32_e32 v241, v241, v238
	v_fmac_f32_e32 v245, v240, v240
	v_fmac_f32_e32 v245, v241, v241
	v_lshlrev_b32_e32 v240, 16, v184
	v_and_b32_e32 v241, 0xffff0000, v184
	v_sub_f32_e32 v240, v240, v238
	v_sub_f32_e32 v241, v241, v238
	v_fmac_f32_e32 v245, v240, v240
	v_fmac_f32_e32 v245, v241, v241
	v_lshlrev_b32_e32 v240, 16, v185
	v_and_b32_e32 v241, 0xffff0000, v185
	v_sub_f32_e32 v240, v240, v238
	v_sub_f32_e32 v241, v241, v238
	v_fmac_f32_e32 v245, v240, v240
	v_fmac_f32_e32 v245, v241, v241
	v_mov_b32_e32 v240, v245
	s_nop 1
	v_permlane16_swap_b32_e32 v240, v245
	v_add_f32_e32 v245, v245, v240
	v_mov_b32_e32 v240, v245
	s_nop 1
	v_permlane32_swap_b32_e32 v240, v245
	v_add_f32_e32 v245, v245, v240
	v_mov_b32_e32 v240, 0x3a27c5ac
	v_fmamk_f32 v245, v245, 0x3c800000, v240
	v_rsq_f32_e32 v239, v245
	v_add_u32_e32 v247, 0x10000, v230
	v_lshlrev_b32_e32 v240, 16, v178
	v_and_b32_e32 v244, 0xffff0000, v178
	v_sub_f32_e32 v240, v240, v238
	v_sub_f32_e32 v244, v244, v238
	v_mul_f32_e32 v240, v240, v239
	v_mul_f32_e32 v244, v244, v239
	v_fma_f32 v240, v130, v240, v146
	v_fma_f32 v244, v131, v244, v147
	v_lshlrev_b32_e32 v241, 16, v186
	v_and_b32_e32 v245, 0xffff0000, v186
	v_lshlrev_b32_e32 v243, 16, v194
	v_and_b32_e32 v246, 0xffff0000, v194
	v_sub_f32_e32 v243, v243, v241
	v_sub_f32_e32 v246, v246, v245
	v_fmac_f32_e32 v241, v162, v243
	v_fmac_f32_e32 v245, v163, v246
	v_fmac_f32_e32 v240, v234, v241
	v_fmac_f32_e32 v244, v234, v245
	v_mul_f32_e32 v80, v80, v240
	v_mul_f32_e32 v81, v81, v244
	v_lshlrev_b32_e32 v240, 16, v179
	v_and_b32_e32 v244, 0xffff0000, v179
	v_sub_f32_e32 v240, v240, v238
	v_sub_f32_e32 v244, v244, v238
	v_mul_f32_e32 v240, v240, v239
	v_mul_f32_e32 v244, v244, v239
	v_fma_f32 v240, v132, v240, v148
	v_fma_f32 v244, v133, v244, v149
	v_lshlrev_b32_e32 v241, 16, v187
	v_and_b32_e32 v245, 0xffff0000, v187
	v_lshlrev_b32_e32 v243, 16, v195
	v_and_b32_e32 v246, 0xffff0000, v195
	v_sub_f32_e32 v243, v243, v241
	v_sub_f32_e32 v246, v246, v245
	v_fmac_f32_e32 v241, v164, v243
	v_fmac_f32_e32 v245, v165, v246
	v_fmac_f32_e32 v240, v234, v241
	v_fmac_f32_e32 v244, v234, v245
	v_mul_f32_e32 v82, v82, v240
	v_mul_f32_e32 v83, v83, v244
	v_lshlrev_b32_e32 v240, 16, v180
	v_and_b32_e32 v244, 0xffff0000, v180
	v_sub_f32_e32 v240, v240, v238
	v_sub_f32_e32 v244, v244, v238
	v_mul_f32_e32 v240, v240, v239
	v_mul_f32_e32 v244, v244, v239
	v_fma_f32 v240, v134, v240, v150
	v_fma_f32 v244, v135, v244, v151
	v_lshlrev_b32_e32 v241, 16, v188
	v_and_b32_e32 v245, 0xffff0000, v188
	v_lshlrev_b32_e32 v243, 16, v196
	v_and_b32_e32 v246, 0xffff0000, v196
	v_sub_f32_e32 v243, v243, v241
	v_sub_f32_e32 v246, v246, v245
	v_fmac_f32_e32 v241, v166, v243
	v_fmac_f32_e32 v245, v167, v246
	v_fmac_f32_e32 v240, v234, v241
	v_fmac_f32_e32 v244, v234, v245
	v_mul_f32_e32 v84, v84, v240
	v_mul_f32_e32 v85, v85, v244
	v_lshlrev_b32_e32 v240, 16, v181
	v_and_b32_e32 v244, 0xffff0000, v181
	v_sub_f32_e32 v240, v240, v238
	v_sub_f32_e32 v244, v244, v238
	v_mul_f32_e32 v240, v240, v239
	v_mul_f32_e32 v244, v244, v239
	v_fma_f32 v240, v136, v240, v152
	v_fma_f32 v244, v137, v244, v153
	v_lshlrev_b32_e32 v241, 16, v189
	v_and_b32_e32 v245, 0xffff0000, v189
	v_lshlrev_b32_e32 v243, 16, v197
	v_and_b32_e32 v246, 0xffff0000, v197
	v_sub_f32_e32 v243, v243, v241
	v_sub_f32_e32 v246, v246, v245
	v_fmac_f32_e32 v241, v168, v243
	v_fmac_f32_e32 v245, v169, v246
	v_fmac_f32_e32 v240, v234, v241
	v_fmac_f32_e32 v244, v234, v245
	v_mul_f32_e32 v86, v86, v240
	v_mul_f32_e32 v87, v87, v244
	v_cvt_pk_bf16_f32 v80, v80, v81
	v_cvt_pk_bf16_f32 v81, v82, v83
	v_cvt_pk_bf16_f32 v82, v84, v85
	v_cvt_pk_bf16_f32 v83, v86, v87
	global_store_dwordx4 v247, v[80:83], s[22:23] offset:128
	v_lshlrev_b32_e32 v240, 16, v182
	v_and_b32_e32 v244, 0xffff0000, v182
	v_sub_f32_e32 v240, v240, v238
	v_sub_f32_e32 v244, v244, v238
	v_mul_f32_e32 v240, v240, v239
	v_mul_f32_e32 v244, v244, v239
	v_fma_f32 v240, v138, v240, v154
	v_fma_f32 v244, v139, v244, v155
	v_lshlrev_b32_e32 v241, 16, v190
	v_and_b32_e32 v245, 0xffff0000, v190
	v_lshlrev_b32_e32 v243, 16, v198
	v_and_b32_e32 v246, 0xffff0000, v198
	v_sub_f32_e32 v243, v243, v241
	v_sub_f32_e32 v246, v246, v245
	v_fmac_f32_e32 v241, v170, v243
	v_fmac_f32_e32 v245, v171, v246
	v_fmac_f32_e32 v240, v234, v241
	v_fmac_f32_e32 v244, v234, v245
	v_mul_f32_e32 v88, v88, v240
	v_mul_f32_e32 v89, v89, v244
	v_lshlrev_b32_e32 v240, 16, v183
	v_and_b32_e32 v244, 0xffff0000, v183
	v_sub_f32_e32 v240, v240, v238
	v_sub_f32_e32 v244, v244, v238
	v_mul_f32_e32 v240, v240, v239
	v_mul_f32_e32 v244, v244, v239
	v_fma_f32 v240, v140, v240, v156
	v_fma_f32 v244, v141, v244, v157
	v_lshlrev_b32_e32 v241, 16, v191
	v_and_b32_e32 v245, 0xffff0000, v191
	v_lshlrev_b32_e32 v243, 16, v199
	v_and_b32_e32 v246, 0xffff0000, v199
	v_sub_f32_e32 v243, v243, v241
	v_sub_f32_e32 v246, v246, v245
	v_fmac_f32_e32 v241, v172, v243
	v_fmac_f32_e32 v245, v173, v246
; __device__ __forceinline__ float bf2f(u16 h) { return __uint_as_float(((unsigned)h) << 16); }
; template <int EPI> ...
;     ...
;       for (int i = 0; i < 16; i++) {
;         const int rl = rbase + (i & 3) + 8 * (i >> 2);
;         const int row = m0 + rl;
;         float o0 = bf2f(Y[(size_t)row * 1024 + 256 + ch0]);
;         float o1 = bf2f(Y[(size_t)row * 1024 + 256 + ch1]);
;         float mean = hsum32(o0 + o1) * (1.0f / 64.0f);
;         float d0 = o0 - mean, d1 = o1 - mean;
;         float var = hsum32(d0 * d0 + d1 * d1) * (1.0f / 64.0f);
;         float rstd = rsqrtf(var + 64e-5f);
;         float pv0 = bf2f(P[(size_t)row * 2816 + 256 + 1536 + ch0]);
;         float pv1 = bf2f(P[(size_t)row * 2816 + 256 + 1536 + ch1]);
;         float pp0 = prevP(p, P, row, 1536 + ch0), pp1 = prevP(p, P, row, 1536 + ch1);
;         float vv0 = pv0 + (pp0 - pv0) * mu0, vv1 = pv1 + (pp1 - pv1) * mu1;
;         float b = bs[((size_t)row * 12 + hh) * 4 + 2];
;         float y0 = (d0 * rstd * gg0 + gb0 + b * vv0) * acc0[i];
;         float y1 = (d1 * rstd * gg1 + gb1 + b * vv1) * acc1[i];
;         Y[(size_t)row * 1024 + 256 + ch0] = f2bf(y0);
;         Y[(size_t)row * 1024 + 256 + ch1] = f2bf(y1);
;       }
	v_fmac_f32_e32 v240, v234, v241
	v_fmac_f32_e32 v244, v234, v245
	v_mul_f32_e32 v90, v90, v240
	v_mul_f32_e32 v91, v91, v244
	v_lshlrev_b32_e32 v240, 16, v184
	v_and_b32_e32 v244, 0xffff0000, v184
	v_sub_f32_e32 v240, v240, v238
	v_sub_f32_e32 v244, v244, v238
	v_mul_f32_e32 v240, v240, v239
	v_mul_f32_e32 v244, v244, v239
	v_fma_f32 v240, v142, v240, v158
	v_fma_f32 v244, v143, v244, v159
	v_lshlrev_b32_e32 v241, 16, v192
	v_and_b32_e32 v245, 0xffff0000, v192
	v_lshlrev_b32_e32 v243, 16, v200
	v_and_b32_e32 v246, 0xffff0000, v200
	v_sub_f32_e32 v243, v243, v241
	v_sub_f32_e32 v246, v246, v245
	v_fmac_f32_e32 v241, v174, v243
	v_fmac_f32_e32 v245, v175, v246
	v_fmac_f32_e32 v240, v234, v241
	v_fmac_f32_e32 v244, v234, v245
	v_mul_f32_e32 v92, v92, v240
	v_mul_f32_e32 v93, v93, v244
	v_lshlrev_b32_e32 v240, 16, v185
	v_and_b32_e32 v244, 0xffff0000, v185
	v_sub_f32_e32 v240, v240, v238
	v_sub_f32_e32 v244, v244, v238
	v_mul_f32_e32 v240, v240, v239
	v_mul_f32_e32 v244, v244, v239
	v_fma_f32 v240, v144, v240, v160
	v_fma_f32 v244, v145, v244, v161
	v_lshlrev_b32_e32 v241, 16, v193
	v_and_b32_e32 v245, 0xffff0000, v193
	v_lshlrev_b32_e32 v243, 16, v201
	v_and_b32_e32 v246, 0xffff0000, v201
	v_sub_f32_e32 v243, v243, v241
	v_sub_f32_e32 v246, v246, v245
	v_fmac_f32_e32 v241, v176, v243
	v_fmac_f32_e32 v245, v177, v246
	v_fmac_f32_e32 v240, v234, v241
	v_fmac_f32_e32 v244, v234, v245
	v_mul_f32_e32 v94, v94, v240
	v_mul_f32_e32 v95, v95, v244
	v_cvt_pk_bf16_f32 v88, v88, v89
	v_cvt_pk_bf16_f32 v89, v90, v91
	v_cvt_pk_bf16_f32 v90, v92, v93
	v_cvt_pk_bf16_f32 v91, v94, v95
	global_store_dwordx4 v247, v[88:91], s[22:23] offset:192
	s_waitcnt vmcnt(2)
	v_lshlrev_b32_e32 v240, 16, v202
	v_and_b32_e32 v241, 0xffff0000, v202
	v_add_f32_e32 v244, v240, v241
	v_lshlrev_b32_e32 v240, 16, v203
	v_and_b32_e32 v241, 0xffff0000, v203
	v_add_f32_e32 v244, v244, v240
	v_add_f32_e32 v244, v244, v241
	v_lshlrev_b32_e32 v240, 16, v204
	v_and_b32_e32 v241, 0xffff0000, v204
	v_add_f32_e32 v244, v244, v240
	v_add_f32_e32 v244, v244, v241
	v_lshlrev_b32_e32 v240, 16, v205
	v_and_b32_e32 v241, 0xffff0000, v205
	v_add_f32_e32 v244, v244, v240
	v_add_f32_e32 v244, v244, v241
	v_lshlrev_b32_e32 v240, 16, v206
	v_and_b32_e32 v241, 0xffff0000, v206
	v_add_f32_e32 v244, v244, v240
	v_add_f32_e32 v244, v244, v241
	v_lshlrev_b32_e32 v240, 16, v207
	v_and_b32_e32 v241, 0xffff0000, v207
	v_add_f32_e32 v244, v244, v240
	v_add_f32_e32 v244, v244, v241
	v_lshlrev_b32_e32 v240, 16, v208
	v_and_b32_e32 v241, 0xffff0000, v208
	v_add_f32_e32 v244, v244, v240
	v_add_f32_e32 v244, v244, v241
	v_lshlrev_b32_e32 v240, 16, v209
	v_and_b32_e32 v241, 0xffff0000, v209
	v_add_f32_e32 v244, v244, v240
	v_add_f32_e32 v244, v244, v241
	v_mov_b32_e32 v240, v244
	s_nop 1
	v_permlane16_swap_b32_e32 v240, v244
	v_add_f32_e32 v244, v244, v240
	v_mov_b32_e32 v240, v244
	s_nop 1
	v_permlane32_swap_b32_e32 v240, v244
	v_add_f32_e32 v244, v244, v240
	v_mul_f32_e32 v238, 0x3c800000, v244
	v_lshlrev_b32_e32 v240, 16, v202
	v_and_b32_e32 v241, 0xffff0000, v202
	v_sub_f32_e32 v240, v240, v238
	v_sub_f32_e32 v241, v241, v238
	v_mul_f32_e32 v245, v240, v240
	v_fmac_f32_e32 v245, v241, v241
	v_lshlrev_b32_e32 v240, 16, v203
	v_and_b32_e32 v241, 0xffff0000, v203
	v_sub_f32_e32 v240, v240, v238
	v_sub_f32_e32 v241, v241, v238
	v_fmac_f32_e32 v245, v240, v240
	v_fmac_f32_e32 v245, v241, v241
	v_lshlrev_b32_e32 v240, 16, v204
	v_and_b32_e32 v241, 0xffff0000, v204
	v_sub_f32_e32 v240, v240, v238
	v_sub_f32_e32 v241, v241, v238
	v_fmac_f32_e32 v245, v240, v240
	v_fmac_f32_e32 v245, v241, v241
	v_lshlrev_b32_e32 v240, 16, v205
	v_and_b32_e32 v241, 0xffff0000, v205
	v_sub_f32_e32 v240, v240, v238
	v_sub_f32_e32 v241, v241, v238
	v_fmac_f32_e32 v245, v240, v240
	v_fmac_f32_e32 v245, v241, v241
	v_lshlrev_b32_e32 v240, 16, v206
	v_and_b32_e32 v241, 0xffff0000, v206
	v_sub_f32_e32 v240, v240, v238
	v_sub_f32_e32 v241, v241, v238
	v_fmac_f32_e32 v245, v240, v240
	v_fmac_f32_e32 v245, v241, v241
	v_lshlrev_b32_e32 v240, 16, v207
	v_and_b32_e32 v241, 0xffff0000, v207
	v_sub_f32_e32 v240, v240, v238
	v_sub_f32_e32 v241, v241, v238
	v_fmac_f32_e32 v245, v240, v240
	v_fmac_f32_e32 v245, v241, v241
	v_lshlrev_b32_e32 v240, 16, v208
	v_and_b32_e32 v241, 0xffff0000, v208
	v_sub_f32_e32 v240, v240, v238
	v_sub_f32_e32 v241, v241, v238
	v_fmac_f32_e32 v245, v240, v240
	v_fmac_f32_e32 v245, v241, v241
	v_lshlrev_b32_e32 v240, 16, v209
	v_and_b32_e32 v241, 0xffff0000, v209
	v_sub_f32_e32 v240, v240, v238
	v_sub_f32_e32 v241, v241, v238
	v_fmac_f32_e32 v245, v240, v240
	v_fmac_f32_e32 v245, v241, v241
	v_mov_b32_e32 v240, v245
	s_nop 1
	v_permlane16_swap_b32_e32 v240, v245
	v_add_f32_e32 v245, v245, v240
	v_mov_b32_e32 v240, v245
	s_nop 1
	v_permlane32_swap_b32_e32 v240, v245
	v_add_f32_e32 v245, v245, v240
	v_mov_b32_e32 v240, 0x3a27c5ac
	v_fmamk_f32 v245, v245, 0x3c800000, v240
	v_rsq_f32_e32 v239, v245
	v_add_u32_e32 v247, 0x18000, v230
	v_lshlrev_b32_e32 v240, 16, v202
	v_and_b32_e32 v244, 0xffff0000, v202
	v_sub_f32_e32 v240, v240, v238
	v_sub_f32_e32 v244, v244, v238
	v_mul_f32_e32 v240, v240, v239
	v_mul_f32_e32 v244, v244, v239
	v_fma_f32 v240, v130, v240, v146
	v_fma_f32 v244, v131, v244, v147
	v_lshlrev_b32_e32 v241, 16, v210
	v_and_b32_e32 v245, 0xffff0000, v210
	v_lshlrev_b32_e32 v243, 16, v218
	v_and_b32_e32 v246, 0xffff0000, v218
	v_sub_f32_e32 v243, v243, v241
	v_sub_f32_e32 v246, v246, v245
	v_fmac_f32_e32 v241, v162, v243
	v_fmac_f32_e32 v245, v163, v246
	v_fmac_f32_e32 v240, v235, v241
	v_fmac_f32_e32 v244, v235, v245
	v_mul_f32_e32 v112, v112, v240
	v_mul_f32_e32 v113, v113, v244
	v_lshlrev_b32_e32 v240, 16, v203
; __device__ __forceinline__ float bf2f(u16 h) { return __uint_as_float(((unsigned)h) << 16); }
; template <int EPI> ...
;     ...
;       for (int i = 0; i < 16; i++) {
;         const int rl = rbase + (i & 3) + 8 * (i >> 2);
;         const int row = m0 + rl;
;         float o0 = bf2f(Y[(size_t)row * 1024 + 256 + ch0]);
;         float o1 = bf2f(Y[(size_t)row * 1024 + 256 + ch1]);
;         float mean = hsum32(o0 + o1) * (1.0f / 64.0f);
;         float d0 = o0 - mean, d1 = o1 - mean;
;         float var = hsum32(d0 * d0 + d1 * d1) * (1.0f / 64.0f);
;         float rstd = rsqrtf(var + 64e-5f);
;         float pv0 = bf2f(P[(size_t)row * 2816 + 256 + 1536 + ch0]);
;         float pv1 = bf2f(P[(size_t)row * 2816 + 256 + 1536 + ch1]);
;         float pp0 = prevP(p, P, row, 1536 + ch0), pp1 = prevP(p, P, row, 1536 + ch1);
;         float vv0 = pv0 + (pp0 - pv0) * mu0, vv1 = pv1 + (pp1 - pv1) * mu1;
;         float b = bs[((size_t)row * 12 + hh) * 4 + 2];
;         float y0 = (d0 * rstd * gg0 + gb0 + b * vv0) * acc0[i];
;         float y1 = (d1 * rstd * gg1 + gb1 + b * vv1) * acc1[i];
;         Y[(size_t)row * 1024 + 256 + ch0] = f2bf(y0);
;         Y[(size_t)row * 1024 + 256 + ch1] = f2bf(y1);
;       }
	v_and_b32_e32 v244, 0xffff0000, v203
	v_sub_f32_e32 v240, v240, v238
	v_sub_f32_e32 v244, v244, v238
	v_mul_f32_e32 v240, v240, v239
	v_mul_f32_e32 v244, v244, v239
	v_fma_f32 v240, v132, v240, v148
	v_fma_f32 v244, v133, v244, v149
	v_lshlrev_b32_e32 v241, 16, v211
	v_and_b32_e32 v245, 0xffff0000, v211
	v_lshlrev_b32_e32 v243, 16, v219
	v_and_b32_e32 v246, 0xffff0000, v219
	v_sub_f32_e32 v243, v243, v241
	v_sub_f32_e32 v246, v246, v245
	v_fmac_f32_e32 v241, v164, v243
	v_fmac_f32_e32 v245, v165, v246
	v_fmac_f32_e32 v240, v235, v241
	v_fmac_f32_e32 v244, v235, v245
	v_mul_f32_e32 v114, v114, v240
	v_mul_f32_e32 v115, v115, v244
	v_lshlrev_b32_e32 v240, 16, v204
	v_and_b32_e32 v244, 0xffff0000, v204
	v_sub_f32_e32 v240, v240, v238
	v_sub_f32_e32 v244, v244, v238
	v_mul_f32_e32 v240, v240, v239
	v_mul_f32_e32 v244, v244, v239
	v_fma_f32 v240, v134, v240, v150
	v_fma_f32 v244, v135, v244, v151
	v_lshlrev_b32_e32 v241, 16, v212
	v_and_b32_e32 v245, 0xffff0000, v212
	v_lshlrev_b32_e32 v243, 16, v220
	v_and_b32_e32 v246, 0xffff0000, v220
	v_sub_f32_e32 v243, v243, v241
	v_sub_f32_e32 v246, v246, v245
	v_fmac_f32_e32 v241, v166, v243
	v_fmac_f32_e32 v245, v167, v246
	v_fmac_f32_e32 v240, v235, v241
	v_fmac_f32_e32 v244, v235, v245
	v_mul_f32_e32 v116, v116, v240
	v_mul_f32_e32 v117, v117, v244
	v_lshlrev_b32_e32 v240, 16, v205
	v_and_b32_e32 v244, 0xffff0000, v205
	v_sub_f32_e32 v240, v240, v238
	v_sub_f32_e32 v244, v244, v238
	v_mul_f32_e32 v240, v240, v239
	v_mul_f32_e32 v244, v244, v239
	v_fma_f32 v240, v136, v240, v152
	v_fma_f32 v244, v137, v244, v153
	v_lshlrev_b32_e32 v241, 16, v213
	v_and_b32_e32 v245, 0xffff0000, v213
	v_lshlrev_b32_e32 v243, 16, v221
	v_and_b32_e32 v246, 0xffff0000, v221
	v_sub_f32_e32 v243, v243, v241
	v_sub_f32_e32 v246, v246, v245
	v_fmac_f32_e32 v241, v168, v243
	v_fmac_f32_e32 v245, v169, v246
	v_fmac_f32_e32 v240, v235, v241
	v_fmac_f32_e32 v244, v235, v245
	v_mul_f32_e32 v118, v118, v240
	v_mul_f32_e32 v119, v119, v244
	v_cvt_pk_bf16_f32 v112, v112, v113
	v_cvt_pk_bf16_f32 v113, v114, v115
	v_cvt_pk_bf16_f32 v114, v116, v117
	v_cvt_pk_bf16_f32 v115, v118, v119
	global_store_dwordx4 v247, v[112:115], s[22:23] offset:128
	v_lshlrev_b32_e32 v240, 16, v206
	v_and_b32_e32 v244, 0xffff0000, v206
	v_sub_f32_e32 v240, v240, v238
	v_sub_f32_e32 v244, v244, v238
	v_mul_f32_e32 v240, v240, v239
	v_mul_f32_e32 v244, v244, v239
	v_fma_f32 v240, v138, v240, v154
	v_fma_f32 v244, v139, v244, v155
	v_lshlrev_b32_e32 v241, 16, v214
	v_and_b32_e32 v245, 0xffff0000, v214
	v_lshlrev_b32_e32 v243, 16, v222
	v_and_b32_e32 v246, 0xffff0000, v222
	v_sub_f32_e32 v243, v243, v241
	v_sub_f32_e32 v246, v246, v245
	v_fmac_f32_e32 v241, v170, v243
	v_fmac_f32_e32 v245, v171, v246
	v_fmac_f32_e32 v240, v235, v241
	v_fmac_f32_e32 v244, v235, v245
	v_mul_f32_e32 v120, v120, v240
	v_mul_f32_e32 v121, v121, v244
	v_lshlrev_b32_e32 v240, 16, v207
	v_and_b32_e32 v244, 0xffff0000, v207
	v_sub_f32_e32 v240, v240, v238
	v_sub_f32_e32 v244, v244, v238
	v_mul_f32_e32 v240, v240, v239
	v_mul_f32_e32 v244, v244, v239
	v_fma_f32 v240, v140, v240, v156
	v_fma_f32 v244, v141, v244, v157
	v_lshlrev_b32_e32 v241, 16, v215
	v_and_b32_e32 v245, 0xffff0000, v215
	v_lshlrev_b32_e32 v243, 16, v223
	v_and_b32_e32 v246, 0xffff0000, v223
	v_sub_f32_e32 v243, v243, v241
	v_sub_f32_e32 v246, v246, v245
	v_fmac_f32_e32 v241, v172, v243
	v_fmac_f32_e32 v245, v173, v246
	v_fmac_f32_e32 v240, v235, v241
	v_fmac_f32_e32 v244, v235, v245
	v_mul_f32_e32 v122, v122, v240
	v_mul_f32_e32 v123, v123, v244
	v_lshlrev_b32_e32 v240, 16, v208
	v_and_b32_e32 v244, 0xffff0000, v208
	v_sub_f32_e32 v240, v240, v238
	v_sub_f32_e32 v244, v244, v238
	v_mul_f32_e32 v240, v240, v239
	v_mul_f32_e32 v244, v244, v239
	v_fma_f32 v240, v142, v240, v158
	v_fma_f32 v244, v143, v244, v159
	v_lshlrev_b32_e32 v241, 16, v216
	v_and_b32_e32 v245, 0xffff0000, v216
	v_lshlrev_b32_e32 v243, 16, v224
	v_and_b32_e32 v246, 0xffff0000, v224
	v_sub_f32_e32 v243, v243, v241
	v_sub_f32_e32 v246, v246, v245
	v_fmac_f32_e32 v241, v174, v243
	v_fmac_f32_e32 v245, v175, v246
	v_fmac_f32_e32 v240, v235, v241
	v_fmac_f32_e32 v244, v235, v245
	v_mul_f32_e32 v124, v124, v240
	v_mul_f32_e32 v125, v125, v244
	v_lshlrev_b32_e32 v240, 16, v209
	v_and_b32_e32 v244, 0xffff0000, v209
	v_sub_f32_e32 v240, v240, v238
	v_sub_f32_e32 v244, v244, v238
	v_mul_f32_e32 v240, v240, v239
	v_mul_f32_e32 v244, v244, v239
	v_fma_f32 v240, v144, v240, v160
	v_fma_f32 v244, v145, v244, v161
	v_lshlrev_b32_e32 v241, 16, v217
	v_and_b32_e32 v245, 0xffff0000, v217
	v_lshlrev_b32_e32 v243, 16, v225
	v_and_b32_e32 v246, 0xffff0000, v225
	v_sub_f32_e32 v243, v243, v241
	v_sub_f32_e32 v246, v246, v245
	v_fmac_f32_e32 v241, v176, v243
	v_fmac_f32_e32 v245, v177, v246
	v_fmac_f32_e32 v240, v235, v241
	v_fmac_f32_e32 v244, v235, v245
	v_mul_f32_e32 v126, v126, v240
	v_mul_f32_e32 v127, v127, v244
	v_cvt_pk_bf16_f32 v120, v120, v121
	v_cvt_pk_bf16_f32 v121, v122, v123
	v_cvt_pk_bf16_f32 v122, v124, v125
	v_cvt_pk_bf16_f32 v123, v126, v127
	global_store_dwordx4 v247, v[120:123], s[22:23] offset:192
	s_branch .Lpo_done
; __device__ __forceinline__ float bf2f(u16 h) { return __uint_as_float(((unsigned)h) << 16); }
; __device__ __forceinline__ float prevP(const Params& p, const u16* P, int row, int c) {
;   const int rp = row > 0 ? row - 1 : 0;
;   float v = bf2f(P[(size_t)rp * 2816 + 256 + c]);
;   const bool start = (row < NP) ? ((row & 2047) == 0) : (((row - NP) & 3) == 0);
;   if (start) v = (row < NP) ? 0.f : p.in[3][(size_t)((row - NP) >> 2) * 2560 + c];
;   return v;
; template <int EPI> ...
;     ...
;       for (int i = 0; i < 16; i++) {
;         const int rl = rbase + (i & 3) + 8 * (i >> 2);
;         const int row = m0 + rl;
;         float o0 = bf2f(Y[(size_t)row * 1024 + 256 + ch0]);
;         float o1 = bf2f(Y[(size_t)row * 1024 + 256 + ch1]);
;         float mean = hsum32(o0 + o1) * (1.0f / 64.0f);
;         float d0 = o0 - mean, d1 = o1 - mean;
;         float var = hsum32(d0 * d0 + d1 * d1) * (1.0f / 64.0f);
;         float rstd = rsqrtf(var + 64e-5f);
;         float pv0 = bf2f(P[(size_t)row * 2816 + 256 + 1536 + ch0]);
;         float pv1 = bf2f(P[(size_t)row * 2816 + 256 + 1536 + ch1]);
;         float pp0 = prevP(p, P, row, 1536 + ch0), pp1 = prevP(p, P, row, 1536 + ch1);
;         float vv0 = pv0 + (pp0 - pv0) * mu0, vv1 = pv1 + (pp1 - pv1) * mu1;
;         float b = bs[((size_t)row * 12 + hh) * 4 + 2];
;         float y0 = (d0 * rstd * gg0 + gb0 + b * vv0) * acc0[i];
;         float y1 = (d1 * rstd * gg1 + gb1 + b * vv1) * acc1[i];
;         Y[(size_t)row * 1024 + 256 + ch0] = f2bf(y0);
;         Y[(size_t)row * 1024 + 256 + ch1] = f2bf(y1);
;       }
.Lpo_sample:
	s_sub_u32 s11, s6, 64
	s_lshl_b32 s11, s11, 6
	s_lshl_b32 s12, s4, 4
	s_add_u32 s11, s11, s12
	v_lshrrev_b32_e32 v247, 2, v248
	v_add_u32_e32 v247, s11, v247
	v_mul_u32_u24_e32 v247, 0x2800, v247
	v_add_u32_e32 v247, v247, v233
	v_add_u32_e32 v247, 0x1800, v247
	global_load_dwordx4 v[130:133], v233, s[2:3] offset:0
	global_load_dwordx4 v[134:137], v233, s[2:3] offset:16
	global_load_dwordx4 v[138:141], v233, s[2:3] offset:128
	global_load_dwordx4 v[142:145], v233, s[2:3] offset:144
	global_load_dwordx4 v[146:149], v233, s[16:17] offset:0
	global_load_dwordx4 v[150:153], v233, s[16:17] offset:16
	global_load_dwordx4 v[154:157], v233, s[16:17] offset:128
	global_load_dwordx4 v[158:161], v233, s[16:17] offset:144
	global_load_dwordx4 v[162:165], v233, s[0:1] offset:0
	global_load_dwordx4 v[166:169], v233, s[0:1] offset:16
	global_load_dwordx4 v[170:173], v233, s[0:1] offset:128
	global_load_dwordx4 v[174:177], v233, s[0:1] offset:144
	v_add_u32_e32 v236, 0x0, v230
	v_add_u32_e32 v237, 0x0, v231
	v_subrev_u32_e32 v240, 0x1600, v237
	global_load_dwordx4 v[178:181], v236, s[22:23] offset:0
	global_load_dwordx4 v[182:185], v236, s[22:23] offset:64
	global_load_dwordx4 v[186:189], v237, s[96:97] offset:0
	global_load_dwordx4 v[190:193], v237, s[96:97] offset:64
	global_load_dwordx4 v[194:197], v240, s[96:97] offset:0
	global_load_dwordx4 v[198:201], v240, s[96:97] offset:64
	v_add_u32_e32 v236, 0x0, v232
	s_nop 0
	global_load_dword v234, v236, s[96:97] offset:0
	v_add_u32_e32 v237, 0x0, v247
	global_load_dwordx4 v[202:205], v237, s[20:21] offset:0
	global_load_dwordx4 v[206:209], v237, s[20:21] offset:16
	global_load_dwordx4 v[210:213], v237, s[20:21] offset:128
	global_load_dwordx4 v[214:217], v237, s[20:21] offset:144
	s_waitcnt vmcnt(0)
	v_lshlrev_b32_e32 v240, 16, v178
	v_and_b32_e32 v241, 0xffff0000, v178
	v_add_f32_e32 v244, v240, v241
	v_lshlrev_b32_e32 v240, 16, v179
	v_and_b32_e32 v241, 0xffff0000, v179
	v_add_f32_e32 v244, v244, v240
	v_add_f32_e32 v244, v244, v241
	v_lshlrev_b32_e32 v240, 16, v180
	v_and_b32_e32 v241, 0xffff0000, v180
	v_add_f32_e32 v244, v244, v240
	v_add_f32_e32 v244, v244, v241
	v_lshlrev_b32_e32 v240, 16, v181
	v_and_b32_e32 v241, 0xffff0000, v181
	v_add_f32_e32 v244, v244, v240
	v_add_f32_e32 v244, v244, v241
	v_lshlrev_b32_e32 v240, 16, v182
	v_and_b32_e32 v241, 0xffff0000, v182
	v_add_f32_e32 v244, v244, v240
	v_add_f32_e32 v244, v244, v241
	v_lshlrev_b32_e32 v240, 16, v183
	v_and_b32_e32 v241, 0xffff0000, v183
	v_add_f32_e32 v244, v244, v240
	v_add_f32_e32 v244, v244, v241
	v_lshlrev_b32_e32 v240, 16, v184
	v_and_b32_e32 v241, 0xffff0000, v184
	v_add_f32_e32 v244, v244, v240
	v_add_f32_e32 v244, v244, v241
	v_lshlrev_b32_e32 v240, 16, v185
	v_and_b32_e32 v241, 0xffff0000, v185
	v_add_f32_e32 v244, v244, v240
	v_add_f32_e32 v244, v244, v241
	v_mov_b32_e32 v240, v244
	s_nop 1
	v_permlane16_swap_b32_e32 v240, v244
	v_add_f32_e32 v244, v244, v240
	v_mov_b32_e32 v240, v244
	s_nop 1
	v_permlane32_swap_b32_e32 v240, v244
	v_add_f32_e32 v244, v244, v240
	v_mul_f32_e32 v238, 0x3c800000, v244
	v_lshlrev_b32_e32 v240, 16, v178
	v_and_b32_e32 v241, 0xffff0000, v178
	v_sub_f32_e32 v240, v240, v238
	v_sub_f32_e32 v241, v241, v238
	v_mul_f32_e32 v245, v240, v240
	v_fmac_f32_e32 v245, v241, v241
	v_lshlrev_b32_e32 v240, 16, v179
	v_and_b32_e32 v241, 0xffff0000, v179
	v_sub_f32_e32 v240, v240, v238
	v_sub_f32_e32 v241, v241, v238
	v_fmac_f32_e32 v245, v240, v240
	v_fmac_f32_e32 v245, v241, v241
	v_lshlrev_b32_e32 v240, 16, v180
	v_and_b32_e32 v241, 0xffff0000, v180
	v_sub_f32_e32 v240, v240, v238
	v_sub_f32_e32 v241, v241, v238
	v_fmac_f32_e32 v245, v240, v240
	v_fmac_f32_e32 v245, v241, v241
	v_lshlrev_b32_e32 v240, 16, v181
	v_and_b32_e32 v241, 0xffff0000, v181
	v_sub_f32_e32 v240, v240, v238
	v_sub_f32_e32 v241, v241, v238
	v_fmac_f32_e32 v245, v240, v240
	v_fmac_f32_e32 v245, v241, v241
	v_lshlrev_b32_e32 v240, 16, v182
	v_and_b32_e32 v241, 0xffff0000, v182
	v_sub_f32_e32 v240, v240, v238
	v_sub_f32_e32 v241, v241, v238
	v_fmac_f32_e32 v245, v240, v240
	v_fmac_f32_e32 v245, v241, v241
	v_lshlrev_b32_e32 v240, 16, v183
	v_and_b32_e32 v241, 0xffff0000, v183
	v_sub_f32_e32 v240, v240, v238
	v_sub_f32_e32 v241, v241, v238
	v_fmac_f32_e32 v245, v240, v240
	v_fmac_f32_e32 v245, v241, v241
	v_lshlrev_b32_e32 v240, 16, v184
	v_and_b32_e32 v241, 0xffff0000, v184
	v_sub_f32_e32 v240, v240, v238
	v_sub_f32_e32 v241, v241, v238
	v_fmac_f32_e32 v245, v240, v240
	v_fmac_f32_e32 v245, v241, v241
	v_lshlrev_b32_e32 v240, 16, v185
	v_and_b32_e32 v241, 0xffff0000, v185
	v_sub_f32_e32 v240, v240, v238
	v_sub_f32_e32 v241, v241, v238
	v_fmac_f32_e32 v245, v240, v240
	v_fmac_f32_e32 v245, v241, v241
	v_mov_b32_e32 v240, v245
	s_nop 1
	v_permlane16_swap_b32_e32 v240, v245
	v_add_f32_e32 v245, v245, v240
	v_mov_b32_e32 v240, v245
	s_nop 1
	v_permlane32_swap_b32_e32 v240, v245
	v_add_f32_e32 v245, v245, v240
	v_mov_b32_e32 v240, 0x3a27c5ac
	v_fmamk_f32 v245, v245, 0x3c800000, v240
	v_rsq_f32_e32 v239, v245
	v_and_b32_e32 v240, 3, v248
	v_cmp_eq_u32_e32 vcc, 0, v240
	s_nop 1
	v_lshlrev_b32_e32 v240, 16, v178
	v_and_b32_e32 v244, 0xffff0000, v178
	v_sub_f32_e32 v240, v240, v238
	v_sub_f32_e32 v244, v244, v238
	v_mul_f32_e32 v240, v240, v239
	v_mul_f32_e32 v244, v244, v239
	v_fma_f32 v240, v130, v240, v146
	v_fma_f32 v244, v131, v244, v147
	v_lshlrev_b32_e32 v241, 16, v186
	v_and_b32_e32 v245, 0xffff0000, v186
	v_lshlrev_b32_e32 v243, 16, v194
	v_and_b32_e32 v246, 0xffff0000, v194
	v_cndmask_b32_e32 v243, v243, v202, vcc
	v_cndmask_b32_e32 v246, v246, v203, vcc
	v_sub_f32_e32 v243, v243, v241
	v_sub_f32_e32 v246, v246, v245
; __device__ __forceinline__ float bf2f(u16 h) { return __uint_as_float(((unsigned)h) << 16); }
; __device__ __forceinline__ float prevP(const Params& p, const u16* P, int row, int c) {
;   const int rp = row > 0 ? row - 1 : 0;
;   float v = bf2f(P[(size_t)rp * 2816 + 256 + c]);
;   const bool start = (row < NP) ? ((row & 2047) == 0) : (((row - NP) & 3) == 0);
;   if (start) v = (row < NP) ? 0.f : p.in[3][(size_t)((row - NP) >> 2) * 2560 + c];
;   return v;
; template <int EPI> ...
;     ...
;       for (int i = 0; i < 16; i++) {
;         const int rl = rbase + (i & 3) + 8 * (i >> 2);
;         const int row = m0 + rl;
;         float o0 = bf2f(Y[(size_t)row * 1024 + 256 + ch0]);
;         float o1 = bf2f(Y[(size_t)row * 1024 + 256 + ch1]);
;         float mean = hsum32(o0 + o1) * (1.0f / 64.0f);
;         float d0 = o0 - mean, d1 = o1 - mean;
;         float var = hsum32(d0 * d0 + d1 * d1) * (1.0f / 64.0f);
;         float rstd = rsqrtf(var + 64e-5f);
;         float pv0 = bf2f(P[(size_t)row * 2816 + 256 + 1536 + ch0]);
;         float pv1 = bf2f(P[(size_t)row * 2816 + 256 + 1536 + ch1]);
;         float pp0 = prevP(p, P, row, 1536 + ch0), pp1 = prevP(p, P, row, 1536 + ch1);
;         float vv0 = pv0 + (pp0 - pv0) * mu0, vv1 = pv1 + (pp1 - pv1) * mu1;
;         float b = bs[((size_t)row * 12 + hh) * 4 + 2];
;         float y0 = (d0 * rstd * gg0 + gb0 + b * vv0) * acc0[i];
;         float y1 = (d1 * rstd * gg1 + gb1 + b * vv1) * acc1[i];
;         Y[(size_t)row * 1024 + 256 + ch0] = f2bf(y0);
;         Y[(size_t)row * 1024 + 256 + ch1] = f2bf(y1);
;       }
	v_fmac_f32_e32 v241, v162, v243
	v_fmac_f32_e32 v245, v163, v246
	v_fmac_f32_e32 v240, v234, v241
	v_fmac_f32_e32 v244, v234, v245
	v_mul_f32_e32 v0, v0, v240
	v_mul_f32_e32 v1, v1, v244
	v_lshlrev_b32_e32 v240, 16, v179
	v_and_b32_e32 v244, 0xffff0000, v179
	v_sub_f32_e32 v240, v240, v238
	v_sub_f32_e32 v244, v244, v238
	v_mul_f32_e32 v240, v240, v239
	v_mul_f32_e32 v244, v244, v239
	v_fma_f32 v240, v132, v240, v148
	v_fma_f32 v244, v133, v244, v149
	v_lshlrev_b32_e32 v241, 16, v187
	v_and_b32_e32 v245, 0xffff0000, v187
	v_lshlrev_b32_e32 v243, 16, v195
	v_and_b32_e32 v246, 0xffff0000, v195
	v_cndmask_b32_e32 v243, v243, v204, vcc
	v_cndmask_b32_e32 v246, v246, v205, vcc
	v_sub_f32_e32 v243, v243, v241
	v_sub_f32_e32 v246, v246, v245
	v_fmac_f32_e32 v241, v164, v243
	v_fmac_f32_e32 v245, v165, v246
	v_fmac_f32_e32 v240, v234, v241
	v_fmac_f32_e32 v244, v234, v245
	v_mul_f32_e32 v2, v2, v240
	v_mul_f32_e32 v3, v3, v244
	v_lshlrev_b32_e32 v240, 16, v180
	v_and_b32_e32 v244, 0xffff0000, v180
	v_sub_f32_e32 v240, v240, v238
	v_sub_f32_e32 v244, v244, v238
	v_mul_f32_e32 v240, v240, v239
	v_mul_f32_e32 v244, v244, v239
	v_fma_f32 v240, v134, v240, v150
	v_fma_f32 v244, v135, v244, v151
	v_lshlrev_b32_e32 v241, 16, v188
	v_and_b32_e32 v245, 0xffff0000, v188
	v_lshlrev_b32_e32 v243, 16, v196
	v_and_b32_e32 v246, 0xffff0000, v196
	v_cndmask_b32_e32 v243, v243, v206, vcc
	v_cndmask_b32_e32 v246, v246, v207, vcc
	v_sub_f32_e32 v243, v243, v241
	v_sub_f32_e32 v246, v246, v245
	v_fmac_f32_e32 v241, v166, v243
	v_fmac_f32_e32 v245, v167, v246
	v_fmac_f32_e32 v240, v234, v241
	v_fmac_f32_e32 v244, v234, v245
	v_mul_f32_e32 v4, v4, v240
	v_mul_f32_e32 v5, v5, v244
	v_lshlrev_b32_e32 v240, 16, v181
	v_and_b32_e32 v244, 0xffff0000, v181
	v_sub_f32_e32 v240, v240, v238
	v_sub_f32_e32 v244, v244, v238
	v_mul_f32_e32 v240, v240, v239
	v_mul_f32_e32 v244, v244, v239
	v_fma_f32 v240, v136, v240, v152
	v_fma_f32 v244, v137, v244, v153
	v_lshlrev_b32_e32 v241, 16, v189
	v_and_b32_e32 v245, 0xffff0000, v189
	v_lshlrev_b32_e32 v243, 16, v197
	v_and_b32_e32 v246, 0xffff0000, v197
	v_cndmask_b32_e32 v243, v243, v208, vcc
	v_cndmask_b32_e32 v246, v246, v209, vcc
	v_sub_f32_e32 v243, v243, v241
	v_sub_f32_e32 v246, v246, v245
	v_fmac_f32_e32 v241, v168, v243
	v_fmac_f32_e32 v245, v169, v246
	v_fmac_f32_e32 v240, v234, v241
	v_fmac_f32_e32 v244, v234, v245
	v_mul_f32_e32 v6, v6, v240
	v_mul_f32_e32 v7, v7, v244
	v_cvt_pk_bf16_f32 v0, v0, v1
	v_cvt_pk_bf16_f32 v1, v2, v3
	v_cvt_pk_bf16_f32 v2, v4, v5
	v_cvt_pk_bf16_f32 v3, v6, v7
	v_add_u32_e32 v236, 0x0, v230
	s_nop 0
	global_store_dwordx4 v236, v[0:3], s[22:23] offset:0
	v_lshlrev_b32_e32 v240, 16, v182
	v_and_b32_e32 v244, 0xffff0000, v182
	v_sub_f32_e32 v240, v240, v238
	v_sub_f32_e32 v244, v244, v238
	v_mul_f32_e32 v240, v240, v239
	v_mul_f32_e32 v244, v244, v239
	v_fma_f32 v240, v138, v240, v154
	v_fma_f32 v244, v139, v244, v155
	v_lshlrev_b32_e32 v241, 16, v190
	v_and_b32_e32 v245, 0xffff0000, v190
	v_lshlrev_b32_e32 v243, 16, v198
	v_and_b32_e32 v246, 0xffff0000, v198
	v_cndmask_b32_e32 v243, v243, v210, vcc
	v_cndmask_b32_e32 v246, v246, v211, vcc
	v_sub_f32_e32 v243, v243, v241
	v_sub_f32_e32 v246, v246, v245
	v_fmac_f32_e32 v241, v170, v243
	v_fmac_f32_e32 v245, v171, v246
	v_fmac_f32_e32 v240, v234, v241
	v_fmac_f32_e32 v244, v234, v245
	v_mul_f32_e32 v8, v8, v240
	v_mul_f32_e32 v9, v9, v244
	v_lshlrev_b32_e32 v240, 16, v183
	v_and_b32_e32 v244, 0xffff0000, v183
	v_sub_f32_e32 v240, v240, v238
	v_sub_f32_e32 v244, v244, v238
	v_mul_f32_e32 v240, v240, v239
	v_mul_f32_e32 v244, v244, v239
	v_fma_f32 v240, v140, v240, v156
	v_fma_f32 v244, v141, v244, v157
	v_lshlrev_b32_e32 v241, 16, v191
	v_and_b32_e32 v245, 0xffff0000, v191
	v_lshlrev_b32_e32 v243, 16, v199
	v_and_b32_e32 v246, 0xffff0000, v199
	v_cndmask_b32_e32 v243, v243, v212, vcc
	v_cndmask_b32_e32 v246, v246, v213, vcc
	v_sub_f32_e32 v243, v243, v241
	v_sub_f32_e32 v246, v246, v245
	v_fmac_f32_e32 v241, v172, v243
	v_fmac_f32_e32 v245, v173, v246
	v_fmac_f32_e32 v240, v234, v241
	v_fmac_f32_e32 v244, v234, v245
	v_mul_f32_e32 v10, v10, v240
	v_mul_f32_e32 v11, v11, v244
	v_lshlrev_b32_e32 v240, 16, v184
	v_and_b32_e32 v244, 0xffff0000, v184
	v_sub_f32_e32 v240, v240, v238
	v_sub_f32_e32 v244, v244, v238
	v_mul_f32_e32 v240, v240, v239
	v_mul_f32_e32 v244, v244, v239
	v_fma_f32 v240, v142, v240, v158
	v_fma_f32 v244, v143, v244, v159
	v_lshlrev_b32_e32 v241, 16, v192
	v_and_b32_e32 v245, 0xffff0000, v192
	v_lshlrev_b32_e32 v243, 16, v200
	v_and_b32_e32 v246, 0xffff0000, v200
	v_cndmask_b32_e32 v243, v243, v214, vcc
	v_cndmask_b32_e32 v246, v246, v215, vcc
	v_sub_f32_e32 v243, v243, v241
	v_sub_f32_e32 v246, v246, v245
	v_fmac_f32_e32 v241, v174, v243
	v_fmac_f32_e32 v245, v175, v246
	v_fmac_f32_e32 v240, v234, v241
	v_fmac_f32_e32 v244, v234, v245
	v_mul_f32_e32 v12, v12, v240
	v_mul_f32_e32 v13, v13, v244
	v_lshlrev_b32_e32 v240, 16, v185
	v_and_b32_e32 v244, 0xffff0000, v185
	v_sub_f32_e32 v240, v240, v238
	v_sub_f32_e32 v244, v244, v238
	v_mul_f32_e32 v240, v240, v239
	v_mul_f32_e32 v244, v244, v239
	v_fma_f32 v240, v144, v240, v160
	v_fma_f32 v244, v145, v244, v161
	v_lshlrev_b32_e32 v241, 16, v193
	v_and_b32_e32 v245, 0xffff0000, v193
	v_lshlrev_b32_e32 v243, 16, v201
	v_and_b32_e32 v246, 0xffff0000, v201
	v_cndmask_b32_e32 v243, v243, v216, vcc
	v_cndmask_b32_e32 v246, v246, v217, vcc
	v_sub_f32_e32 v243, v243, v241
	v_sub_f32_e32 v246, v246, v245
	v_fmac_f32_e32 v241, v176, v243
	v_fmac_f32_e32 v245, v177, v246
	v_fmac_f32_e32 v240, v234, v241
	v_fmac_f32_e32 v244, v234, v245
	v_mul_f32_e32 v14, v14, v240
	v_mul_f32_e32 v15, v15, v244
	v_cvt_pk_bf16_f32 v8, v8, v9
	v_cvt_pk_bf16_f32 v9, v10, v11
	v_cvt_pk_bf16_f32 v10, v12, v13
	v_cvt_pk_bf16_f32 v11, v14, v15
	v_add_u32_e32 v236, 0x0, v230
	s_nop 0
	global_store_dwordx4 v236, v[8:11], s[22:23] offset:64
	v_add_u32_e32 v236, 0x8000, v230
	v_add_u32_e32 v237, 0x16000, v231
	v_subrev_u32_e32 v240, 0x1600, v237
	global_load_dwordx4 v[178:181], v236, s[22:23] offset:0
	global_load_dwordx4 v[182:185], v236, s[22:23] offset:64
	global_load_dwordx4 v[186:189], v237, s[96:97] offset:0
	global_load_dwordx4 v[190:193], v237, s[96:97] offset:64
	global_load_dwordx4 v[194:197], v240, s[96:97] offset:0
	global_load_dwordx4 v[198:201], v240, s[96:97] offset:64
	v_add_u32_e32 v236, 0xc00, v232
	s_nop 0
	global_load_dword v234, v236, s[96:97] offset:0
	v_add_u32_e32 v237, 0xa000, v247
	global_load_dwordx4 v[202:205], v237, s[20:21] offset:0
	global_load_dwordx4 v[206:209], v237, s[20:21] offset:16
	global_load_dwordx4 v[210:213], v237, s[20:21] offset:128
	global_load_dwordx4 v[214:217], v237, s[20:21] offset:144
	s_waitcnt vmcnt(0)
; __device__ __forceinline__ float bf2f(u16 h) { return __uint_as_float(((unsigned)h) << 16); }
; __device__ __forceinline__ float prevP(const Params& p, const u16* P, int row, int c) {
;   const int rp = row > 0 ? row - 1 : 0;
;   float v = bf2f(P[(size_t)rp * 2816 + 256 + c]);
;   const bool start = (row < NP) ? ((row & 2047) == 0) : (((row - NP) & 3) == 0);
;   if (start) v = (row < NP) ? 0.f : p.in[3][(size_t)((row - NP) >> 2) * 2560 + c];
;   return v;
; template <int EPI> ...
;     ...
;       for (int i = 0; i < 16; i++) {
;         const int rl = rbase + (i & 3) + 8 * (i >> 2);
;         const int row = m0 + rl;
;         float o0 = bf2f(Y[(size_t)row * 1024 + 256 + ch0]);
;         float o1 = bf2f(Y[(size_t)row * 1024 + 256 + ch1]);
;         float mean = hsum32(o0 + o1) * (1.0f / 64.0f);
;         float d0 = o0 - mean, d1 = o1 - mean;
;         float var = hsum32(d0 * d0 + d1 * d1) * (1.0f / 64.0f);
;         float rstd = rsqrtf(var + 64e-5f);
;         float pv0 = bf2f(P[(size_t)row * 2816 + 256 + 1536 + ch0]);
;         float pv1 = bf2f(P[(size_t)row * 2816 + 256 + 1536 + ch1]);
;         float pp0 = prevP(p, P, row, 1536 + ch0), pp1 = prevP(p, P, row, 1536 + ch1);
;         float vv0 = pv0 + (pp0 - pv0) * mu0, vv1 = pv1 + (pp1 - pv1) * mu1;
;         float b = bs[((size_t)row * 12 + hh) * 4 + 2];
;         float y0 = (d0 * rstd * gg0 + gb0 + b * vv0) * acc0[i];
;         float y1 = (d1 * rstd * gg1 + gb1 + b * vv1) * acc1[i];
;         Y[(size_t)row * 1024 + 256 + ch0] = f2bf(y0);
;         Y[(size_t)row * 1024 + 256 + ch1] = f2bf(y1);
;       }
	v_lshlrev_b32_e32 v240, 16, v178
	v_and_b32_e32 v241, 0xffff0000, v178
	v_add_f32_e32 v244, v240, v241
	v_lshlrev_b32_e32 v240, 16, v179
	v_and_b32_e32 v241, 0xffff0000, v179
	v_add_f32_e32 v244, v244, v240
	v_add_f32_e32 v244, v244, v241
	v_lshlrev_b32_e32 v240, 16, v180
	v_and_b32_e32 v241, 0xffff0000, v180
	v_add_f32_e32 v244, v244, v240
	v_add_f32_e32 v244, v244, v241
	v_lshlrev_b32_e32 v240, 16, v181
	v_and_b32_e32 v241, 0xffff0000, v181
	v_add_f32_e32 v244, v244, v240
	v_add_f32_e32 v244, v244, v241
	v_lshlrev_b32_e32 v240, 16, v182
	v_and_b32_e32 v241, 0xffff0000, v182
	v_add_f32_e32 v244, v244, v240
	v_add_f32_e32 v244, v244, v241
	v_lshlrev_b32_e32 v240, 16, v183
	v_and_b32_e32 v241, 0xffff0000, v183
	v_add_f32_e32 v244, v244, v240
	v_add_f32_e32 v244, v244, v241
	v_lshlrev_b32_e32 v240, 16, v184
	v_and_b32_e32 v241, 0xffff0000, v184
	v_add_f32_e32 v244, v244, v240
	v_add_f32_e32 v244, v244, v241
	v_lshlrev_b32_e32 v240, 16, v185
	v_and_b32_e32 v241, 0xffff0000, v185
	v_add_f32_e32 v244, v244, v240
	v_add_f32_e32 v244, v244, v241
	v_mov_b32_e32 v240, v244
	s_nop 1
	v_permlane16_swap_b32_e32 v240, v244
	v_add_f32_e32 v244, v244, v240
	v_mov_b32_e32 v240, v244
	s_nop 1
	v_permlane32_swap_b32_e32 v240, v244
	v_add_f32_e32 v244, v244, v240
	v_mul_f32_e32 v238, 0x3c800000, v244
	v_lshlrev_b32_e32 v240, 16, v178
	v_and_b32_e32 v241, 0xffff0000, v178
	v_sub_f32_e32 v240, v240, v238
	v_sub_f32_e32 v241, v241, v238
	v_mul_f32_e32 v245, v240, v240
	v_fmac_f32_e32 v245, v241, v241
	v_lshlrev_b32_e32 v240, 16, v179
	v_and_b32_e32 v241, 0xffff0000, v179
	v_sub_f32_e32 v240, v240, v238
	v_sub_f32_e32 v241, v241, v238
	v_fmac_f32_e32 v245, v240, v240
	v_fmac_f32_e32 v245, v241, v241
	v_lshlrev_b32_e32 v240, 16, v180
	v_and_b32_e32 v241, 0xffff0000, v180
	v_sub_f32_e32 v240, v240, v238
	v_sub_f32_e32 v241, v241, v238
	v_fmac_f32_e32 v245, v240, v240
	v_fmac_f32_e32 v245, v241, v241
	v_lshlrev_b32_e32 v240, 16, v181
	v_and_b32_e32 v241, 0xffff0000, v181
	v_sub_f32_e32 v240, v240, v238
	v_sub_f32_e32 v241, v241, v238
	v_fmac_f32_e32 v245, v240, v240
	v_fmac_f32_e32 v245, v241, v241
	v_lshlrev_b32_e32 v240, 16, v182
	v_and_b32_e32 v241, 0xffff0000, v182
	v_sub_f32_e32 v240, v240, v238
	v_sub_f32_e32 v241, v241, v238
	v_fmac_f32_e32 v245, v240, v240
	v_fmac_f32_e32 v245, v241, v241
	v_lshlrev_b32_e32 v240, 16, v183
	v_and_b32_e32 v241, 0xffff0000, v183
	v_sub_f32_e32 v240, v240, v238
	v_sub_f32_e32 v241, v241, v238
	v_fmac_f32_e32 v245, v240, v240
	v_fmac_f32_e32 v245, v241, v241
	v_lshlrev_b32_e32 v240, 16, v184
	v_and_b32_e32 v241, 0xffff0000, v184
	v_sub_f32_e32 v240, v240, v238
	v_sub_f32_e32 v241, v241, v238
	v_fmac_f32_e32 v245, v240, v240
	v_fmac_f32_e32 v245, v241, v241
	v_lshlrev_b32_e32 v240, 16, v185
	v_and_b32_e32 v241, 0xffff0000, v185
	v_sub_f32_e32 v240, v240, v238
	v_sub_f32_e32 v241, v241, v238
	v_fmac_f32_e32 v245, v240, v240
	v_fmac_f32_e32 v245, v241, v241
	v_mov_b32_e32 v240, v245
	s_nop 1
	v_permlane16_swap_b32_e32 v240, v245
	v_add_f32_e32 v245, v245, v240
	v_mov_b32_e32 v240, v245
	s_nop 1
	v_permlane32_swap_b32_e32 v240, v245
	v_add_f32_e32 v245, v245, v240
	v_mov_b32_e32 v240, 0x3a27c5ac
	v_fmamk_f32 v245, v245, 0x3c800000, v240
	v_rsq_f32_e32 v239, v245
	v_and_b32_e32 v240, 3, v248
	v_cmp_eq_u32_e32 vcc, 0, v240
	s_nop 1
	v_lshlrev_b32_e32 v240, 16, v178
	v_and_b32_e32 v244, 0xffff0000, v178
	v_sub_f32_e32 v240, v240, v238
	v_sub_f32_e32 v244, v244, v238
	v_mul_f32_e32 v240, v240, v239
	v_mul_f32_e32 v244, v244, v239
	v_fma_f32 v240, v130, v240, v146
	v_fma_f32 v244, v131, v244, v147
	v_lshlrev_b32_e32 v241, 16, v186
	v_and_b32_e32 v245, 0xffff0000, v186
	v_lshlrev_b32_e32 v243, 16, v194
	v_and_b32_e32 v246, 0xffff0000, v194
	v_cndmask_b32_e32 v243, v243, v202, vcc
	v_cndmask_b32_e32 v246, v246, v203, vcc
	v_sub_f32_e32 v243, v243, v241
	v_sub_f32_e32 v246, v246, v245
	v_fmac_f32_e32 v241, v162, v243
	v_fmac_f32_e32 v245, v163, v246
	v_fmac_f32_e32 v240, v234, v241
	v_fmac_f32_e32 v244, v234, v245
	v_mul_f32_e32 v32, v32, v240
	v_mul_f32_e32 v33, v33, v244
	v_lshlrev_b32_e32 v240, 16, v179
	v_and_b32_e32 v244, 0xffff0000, v179
	v_sub_f32_e32 v240, v240, v238
	v_sub_f32_e32 v244, v244, v238
	v_mul_f32_e32 v240, v240, v239
	v_mul_f32_e32 v244, v244, v239
	v_fma_f32 v240, v132, v240, v148
	v_fma_f32 v244, v133, v244, v149
	v_lshlrev_b32_e32 v241, 16, v187
	v_and_b32_e32 v245, 0xffff0000, v187
	v_lshlrev_b32_e32 v243, 16, v195
	v_and_b32_e32 v246, 0xffff0000, v195
	v_cndmask_b32_e32 v243, v243, v204, vcc
	v_cndmask_b32_e32 v246, v246, v205, vcc
	v_sub_f32_e32 v243, v243, v241
	v_sub_f32_e32 v246, v246, v245
	v_fmac_f32_e32 v241, v164, v243
	v_fmac_f32_e32 v245, v165, v246
	v_fmac_f32_e32 v240, v234, v241
	v_fmac_f32_e32 v244, v234, v245
	v_mul_f32_e32 v34, v34, v240
	v_mul_f32_e32 v35, v35, v244
	v_lshlrev_b32_e32 v240, 16, v180
	v_and_b32_e32 v244, 0xffff0000, v180
	v_sub_f32_e32 v240, v240, v238
	v_sub_f32_e32 v244, v244, v238
	v_mul_f32_e32 v240, v240, v239
	v_mul_f32_e32 v244, v244, v239
	v_fma_f32 v240, v134, v240, v150
	v_fma_f32 v244, v135, v244, v151
	v_lshlrev_b32_e32 v241, 16, v188
	v_and_b32_e32 v245, 0xffff0000, v188
	v_lshlrev_b32_e32 v243, 16, v196
	v_and_b32_e32 v246, 0xffff0000, v196
	v_cndmask_b32_e32 v243, v243, v206, vcc
	v_cndmask_b32_e32 v246, v246, v207, vcc
	v_sub_f32_e32 v243, v243, v241
	v_sub_f32_e32 v246, v246, v245
	v_fmac_f32_e32 v241, v166, v243
	v_fmac_f32_e32 v245, v167, v246
	v_fmac_f32_e32 v240, v234, v241
	v_fmac_f32_e32 v244, v234, v245
	v_mul_f32_e32 v36, v36, v240
	v_mul_f32_e32 v37, v37, v244
	v_lshlrev_b32_e32 v240, 16, v181
	v_and_b32_e32 v244, 0xffff0000, v181
	v_sub_f32_e32 v240, v240, v238
; __device__ __forceinline__ float bf2f(u16 h) { return __uint_as_float(((unsigned)h) << 16); }
; __device__ __forceinline__ float prevP(const Params& p, const u16* P, int row, int c) {
;   const int rp = row > 0 ? row - 1 : 0;
;   float v = bf2f(P[(size_t)rp * 2816 + 256 + c]);
;   const bool start = (row < NP) ? ((row & 2047) == 0) : (((row - NP) & 3) == 0);
;   if (start) v = (row < NP) ? 0.f : p.in[3][(size_t)((row - NP) >> 2) * 2560 + c];
;   return v;
; template <int EPI> ...
;     ...
;       for (int i = 0; i < 16; i++) {
;         const int rl = rbase + (i & 3) + 8 * (i >> 2);
;         const int row = m0 + rl;
;         float o0 = bf2f(Y[(size_t)row * 1024 + 256 + ch0]);
;         float o1 = bf2f(Y[(size_t)row * 1024 + 256 + ch1]);
;         float mean = hsum32(o0 + o1) * (1.0f / 64.0f);
;         float d0 = o0 - mean, d1 = o1 - mean;
;         float var = hsum32(d0 * d0 + d1 * d1) * (1.0f / 64.0f);
;         float rstd = rsqrtf(var + 64e-5f);
;         float pv0 = bf2f(P[(size_t)row * 2816 + 256 + 1536 + ch0]);
;         float pv1 = bf2f(P[(size_t)row * 2816 + 256 + 1536 + ch1]);
;         float pp0 = prevP(p, P, row, 1536 + ch0), pp1 = prevP(p, P, row, 1536 + ch1);
;         float vv0 = pv0 + (pp0 - pv0) * mu0, vv1 = pv1 + (pp1 - pv1) * mu1;
;         float b = bs[((size_t)row * 12 + hh) * 4 + 2];
;         float y0 = (d0 * rstd * gg0 + gb0 + b * vv0) * acc0[i];
;         float y1 = (d1 * rstd * gg1 + gb1 + b * vv1) * acc1[i];
;         Y[(size_t)row * 1024 + 256 + ch0] = f2bf(y0);
;         Y[(size_t)row * 1024 + 256 + ch1] = f2bf(y1);
;       }
	v_sub_f32_e32 v244, v244, v238
	v_mul_f32_e32 v240, v240, v239
	v_mul_f32_e32 v244, v244, v239
	v_fma_f32 v240, v136, v240, v152
	v_fma_f32 v244, v137, v244, v153
	v_lshlrev_b32_e32 v241, 16, v189
	v_and_b32_e32 v245, 0xffff0000, v189
	v_lshlrev_b32_e32 v243, 16, v197
	v_and_b32_e32 v246, 0xffff0000, v197
	v_cndmask_b32_e32 v243, v243, v208, vcc
	v_cndmask_b32_e32 v246, v246, v209, vcc
	v_sub_f32_e32 v243, v243, v241
	v_sub_f32_e32 v246, v246, v245
	v_fmac_f32_e32 v241, v168, v243
	v_fmac_f32_e32 v245, v169, v246
	v_fmac_f32_e32 v240, v234, v241
	v_fmac_f32_e32 v244, v234, v245
	v_mul_f32_e32 v38, v38, v240
	v_mul_f32_e32 v39, v39, v244
	v_cvt_pk_bf16_f32 v32, v32, v33
	v_cvt_pk_bf16_f32 v33, v34, v35
	v_cvt_pk_bf16_f32 v34, v36, v37
	v_cvt_pk_bf16_f32 v35, v38, v39
	v_add_u32_e32 v236, 0x8000, v230
	s_nop 0
	global_store_dwordx4 v236, v[32:35], s[22:23] offset:0
	v_lshlrev_b32_e32 v240, 16, v182
	v_and_b32_e32 v244, 0xffff0000, v182
	v_sub_f32_e32 v240, v240, v238
	v_sub_f32_e32 v244, v244, v238
	v_mul_f32_e32 v240, v240, v239
	v_mul_f32_e32 v244, v244, v239
	v_fma_f32 v240, v138, v240, v154
	v_fma_f32 v244, v139, v244, v155
	v_lshlrev_b32_e32 v241, 16, v190
	v_and_b32_e32 v245, 0xffff0000, v190
	v_lshlrev_b32_e32 v243, 16, v198
	v_and_b32_e32 v246, 0xffff0000, v198
	v_cndmask_b32_e32 v243, v243, v210, vcc
	v_cndmask_b32_e32 v246, v246, v211, vcc
	v_sub_f32_e32 v243, v243, v241
	v_sub_f32_e32 v246, v246, v245
	v_fmac_f32_e32 v241, v170, v243
	v_fmac_f32_e32 v245, v171, v246
	v_fmac_f32_e32 v240, v234, v241
	v_fmac_f32_e32 v244, v234, v245
	v_mul_f32_e32 v40, v40, v240
	v_mul_f32_e32 v41, v41, v244
	v_lshlrev_b32_e32 v240, 16, v183
	v_and_b32_e32 v244, 0xffff0000, v183
	v_sub_f32_e32 v240, v240, v238
	v_sub_f32_e32 v244, v244, v238
	v_mul_f32_e32 v240, v240, v239
	v_mul_f32_e32 v244, v244, v239
	v_fma_f32 v240, v140, v240, v156
	v_fma_f32 v244, v141, v244, v157
	v_lshlrev_b32_e32 v241, 16, v191
	v_and_b32_e32 v245, 0xffff0000, v191
	v_lshlrev_b32_e32 v243, 16, v199
	v_and_b32_e32 v246, 0xffff0000, v199
	v_cndmask_b32_e32 v243, v243, v212, vcc
	v_cndmask_b32_e32 v246, v246, v213, vcc
	v_sub_f32_e32 v243, v243, v241
	v_sub_f32_e32 v246, v246, v245
	v_fmac_f32_e32 v241, v172, v243
	v_fmac_f32_e32 v245, v173, v246
	v_fmac_f32_e32 v240, v234, v241
	v_fmac_f32_e32 v244, v234, v245
	v_mul_f32_e32 v42, v42, v240
	v_mul_f32_e32 v43, v43, v244
	v_lshlrev_b32_e32 v240, 16, v184
	v_and_b32_e32 v244, 0xffff0000, v184
	v_sub_f32_e32 v240, v240, v238
	v_sub_f32_e32 v244, v244, v238
	v_mul_f32_e32 v240, v240, v239
	v_mul_f32_e32 v244, v244, v239
	v_fma_f32 v240, v142, v240, v158
	v_fma_f32 v244, v143, v244, v159
	v_lshlrev_b32_e32 v241, 16, v192
	v_and_b32_e32 v245, 0xffff0000, v192
	v_lshlrev_b32_e32 v243, 16, v200
	v_and_b32_e32 v246, 0xffff0000, v200
	v_cndmask_b32_e32 v243, v243, v214, vcc
	v_cndmask_b32_e32 v246, v246, v215, vcc
	v_sub_f32_e32 v243, v243, v241
	v_sub_f32_e32 v246, v246, v245
	v_fmac_f32_e32 v241, v174, v243
	v_fmac_f32_e32 v245, v175, v246
	v_fmac_f32_e32 v240, v234, v241
	v_fmac_f32_e32 v244, v234, v245
	v_mul_f32_e32 v44, v44, v240
	v_mul_f32_e32 v45, v45, v244
	v_lshlrev_b32_e32 v240, 16, v185
	v_and_b32_e32 v244, 0xffff0000, v185
	v_sub_f32_e32 v240, v240, v238
	v_sub_f32_e32 v244, v244, v238
	v_mul_f32_e32 v240, v240, v239
	v_mul_f32_e32 v244, v244, v239
	v_fma_f32 v240, v144, v240, v160
	v_fma_f32 v244, v145, v244, v161
	v_lshlrev_b32_e32 v241, 16, v193
	v_and_b32_e32 v245, 0xffff0000, v193
	v_lshlrev_b32_e32 v243, 16, v201
	v_and_b32_e32 v246, 0xffff0000, v201
	v_cndmask_b32_e32 v243, v243, v216, vcc
	v_cndmask_b32_e32 v246, v246, v217, vcc
	v_sub_f32_e32 v243, v243, v241
	v_sub_f32_e32 v246, v246, v245
	v_fmac_f32_e32 v241, v176, v243
	v_fmac_f32_e32 v245, v177, v246
	v_fmac_f32_e32 v240, v234, v241
	v_fmac_f32_e32 v244, v234, v245
	v_mul_f32_e32 v46, v46, v240
	v_mul_f32_e32 v47, v47, v244
	v_cvt_pk_bf16_f32 v40, v40, v41
	v_cvt_pk_bf16_f32 v41, v42, v43
	v_cvt_pk_bf16_f32 v42, v44, v45
	v_cvt_pk_bf16_f32 v43, v46, v47
	v_add_u32_e32 v236, 0x8000, v230
	s_nop 0
	global_store_dwordx4 v236, v[40:43], s[22:23] offset:64
	v_add_u32_e32 v236, 0x10000, v230
	v_add_u32_e32 v237, 0x2c000, v231
	v_subrev_u32_e32 v240, 0x1600, v237
	global_load_dwordx4 v[178:181], v236, s[22:23] offset:0
	global_load_dwordx4 v[182:185], v236, s[22:23] offset:64
	global_load_dwordx4 v[186:189], v237, s[96:97] offset:0
	global_load_dwordx4 v[190:193], v237, s[96:97] offset:64
	global_load_dwordx4 v[194:197], v240, s[96:97] offset:0
	global_load_dwordx4 v[198:201], v240, s[96:97] offset:64
	v_add_u32_e32 v236, 0x1800, v232
	s_nop 0
	global_load_dword v234, v236, s[96:97] offset:0
	v_add_u32_e32 v237, 0x14000, v247
	global_load_dwordx4 v[202:205], v237, s[20:21] offset:0
	global_load_dwordx4 v[206:209], v237, s[20:21] offset:16
	global_load_dwordx4 v[210:213], v237, s[20:21] offset:128
	global_load_dwordx4 v[214:217], v237, s[20:21] offset:144
	s_waitcnt vmcnt(0)
; __device__ __forceinline__ float bf2f(u16 h) { return __uint_as_float(((unsigned)h) << 16); }
; __device__ __forceinline__ float prevP(const Params& p, const u16* P, int row, int c) {
;   const int rp = row > 0 ? row - 1 : 0;
;   float v = bf2f(P[(size_t)rp * 2816 + 256 + c]);
;   const bool start = (row < NP) ? ((row & 2047) == 0) : (((row - NP) & 3) == 0);
;   if (start) v = (row < NP) ? 0.f : p.in[3][(size_t)((row - NP) >> 2) * 2560 + c];
;   return v;
; template <int EPI> ...
;     ...
;       for (int i = 0; i < 16; i++) {
;         const int rl = rbase + (i & 3) + 8 * (i >> 2);
;         const int row = m0 + rl;
;         float o0 = bf2f(Y[(size_t)row * 1024 + 256 + ch0]);
;         float o1 = bf2f(Y[(size_t)row * 1024 + 256 + ch1]);
;         float mean = hsum32(o0 + o1) * (1.0f / 64.0f);
;         float d0 = o0 - mean, d1 = o1 - mean;
;         float var = hsum32(d0 * d0 + d1 * d1) * (1.0f / 64.0f);
;         float rstd = rsqrtf(var + 64e-5f);
;         float pv0 = bf2f(P[(size_t)row * 2816 + 256 + 1536 + ch0]);
;         float pv1 = bf2f(P[(size_t)row * 2816 + 256 + 1536 + ch1]);
;         float pp0 = prevP(p, P, row, 1536 + ch0), pp1 = prevP(p, P, row, 1536 + ch1);
;         float vv0 = pv0 + (pp0 - pv0) * mu0, vv1 = pv1 + (pp1 - pv1) * mu1;
;         float b = bs[((size_t)row * 12 + hh) * 4 + 2];
;         float y0 = (d0 * rstd * gg0 + gb0 + b * vv0) * acc0[i];
;         float y1 = (d1 * rstd * gg1 + gb1 + b * vv1) * acc1[i];
;         Y[(size_t)row * 1024 + 256 + ch0] = f2bf(y0);
;         Y[(size_t)row * 1024 + 256 + ch1] = f2bf(y1);
;       }
	v_lshlrev_b32_e32 v240, 16, v178
	v_and_b32_e32 v241, 0xffff0000, v178
	v_add_f32_e32 v244, v240, v241
	v_lshlrev_b32_e32 v240, 16, v179
	v_and_b32_e32 v241, 0xffff0000, v179
	v_add_f32_e32 v244, v244, v240
	v_add_f32_e32 v244, v244, v241
	v_lshlrev_b32_e32 v240, 16, v180
	v_and_b32_e32 v241, 0xffff0000, v180
	v_add_f32_e32 v244, v244, v240
	v_add_f32_e32 v244, v244, v241
	v_lshlrev_b32_e32 v240, 16, v181
	v_and_b32_e32 v241, 0xffff0000, v181
	v_add_f32_e32 v244, v244, v240
	v_add_f32_e32 v244, v244, v241
	v_lshlrev_b32_e32 v240, 16, v182
	v_and_b32_e32 v241, 0xffff0000, v182
	v_add_f32_e32 v244, v244, v240
	v_add_f32_e32 v244, v244, v241
	v_lshlrev_b32_e32 v240, 16, v183
	v_and_b32_e32 v241, 0xffff0000, v183
	v_add_f32_e32 v244, v244, v240
	v_add_f32_e32 v244, v244, v241
	v_lshlrev_b32_e32 v240, 16, v184
	v_and_b32_e32 v241, 0xffff0000, v184
	v_add_f32_e32 v244, v244, v240
	v_add_f32_e32 v244, v244, v241
	v_lshlrev_b32_e32 v240, 16, v185
	v_and_b32_e32 v241, 0xffff0000, v185
	v_add_f32_e32 v244, v244, v240
	v_add_f32_e32 v244, v244, v241
	v_mov_b32_e32 v240, v244
	s_nop 1
	v_permlane16_swap_b32_e32 v240, v244
	v_add_f32_e32 v244, v244, v240
	v_mov_b32_e32 v240, v244
	s_nop 1
	v_permlane32_swap_b32_e32 v240, v244
	v_add_f32_e32 v244, v244, v240
	v_mul_f32_e32 v238, 0x3c800000, v244
	v_lshlrev_b32_e32 v240, 16, v178
	v_and_b32_e32 v241, 0xffff0000, v178
	v_sub_f32_e32 v240, v240, v238
	v_sub_f32_e32 v241, v241, v238
	v_mul_f32_e32 v245, v240, v240
	v_fmac_f32_e32 v245, v241, v241
	v_lshlrev_b32_e32 v240, 16, v179
	v_and_b32_e32 v241, 0xffff0000, v179
	v_sub_f32_e32 v240, v240, v238
	v_sub_f32_e32 v241, v241, v238
	v_fmac_f32_e32 v245, v240, v240
	v_fmac_f32_e32 v245, v241, v241
	v_lshlrev_b32_e32 v240, 16, v180
	v_and_b32_e32 v241, 0xffff0000, v180
	v_sub_f32_e32 v240, v240, v238
	v_sub_f32_e32 v241, v241, v238
	v_fmac_f32_e32 v245, v240, v240
	v_fmac_f32_e32 v245, v241, v241
	v_lshlrev_b32_e32 v240, 16, v181
	v_and_b32_e32 v241, 0xffff0000, v181
	v_sub_f32_e32 v240, v240, v238
	v_sub_f32_e32 v241, v241, v238
	v_fmac_f32_e32 v245, v240, v240
	v_fmac_f32_e32 v245, v241, v241
	v_lshlrev_b32_e32 v240, 16, v182
	v_and_b32_e32 v241, 0xffff0000, v182
	v_sub_f32_e32 v240, v240, v238
	v_sub_f32_e32 v241, v241, v238
	v_fmac_f32_e32 v245, v240, v240
	v_fmac_f32_e32 v245, v241, v241
	v_lshlrev_b32_e32 v240, 16, v183
	v_and_b32_e32 v241, 0xffff0000, v183
	v_sub_f32_e32 v240, v240, v238
	v_sub_f32_e32 v241, v241, v238
	v_fmac_f32_e32 v245, v240, v240
	v_fmac_f32_e32 v245, v241, v241
	v_lshlrev_b32_e32 v240, 16, v184
	v_and_b32_e32 v241, 0xffff0000, v184
	v_sub_f32_e32 v240, v240, v238
	v_sub_f32_e32 v241, v241, v238
	v_fmac_f32_e32 v245, v240, v240
	v_fmac_f32_e32 v245, v241, v241
	v_lshlrev_b32_e32 v240, 16, v185
	v_and_b32_e32 v241, 0xffff0000, v185
	v_sub_f32_e32 v240, v240, v238
	v_sub_f32_e32 v241, v241, v238
	v_fmac_f32_e32 v245, v240, v240
	v_fmac_f32_e32 v245, v241, v241
	v_mov_b32_e32 v240, v245
	s_nop 1
	v_permlane16_swap_b32_e32 v240, v245
	v_add_f32_e32 v245, v245, v240
	v_mov_b32_e32 v240, v245
	s_nop 1
	v_permlane32_swap_b32_e32 v240, v245
	v_add_f32_e32 v245, v245, v240
	v_mov_b32_e32 v240, 0x3a27c5ac
	v_fmamk_f32 v245, v245, 0x3c800000, v240
	v_rsq_f32_e32 v239, v245
	v_and_b32_e32 v240, 3, v248
	v_cmp_eq_u32_e32 vcc, 0, v240
	s_nop 1
	v_lshlrev_b32_e32 v240, 16, v178
	v_and_b32_e32 v244, 0xffff0000, v178
	v_sub_f32_e32 v240, v240, v238
	v_sub_f32_e32 v244, v244, v238
	v_mul_f32_e32 v240, v240, v239
	v_mul_f32_e32 v244, v244, v239
	v_fma_f32 v240, v130, v240, v146
	v_fma_f32 v244, v131, v244, v147
	v_lshlrev_b32_e32 v241, 16, v186
	v_and_b32_e32 v245, 0xffff0000, v186
	v_lshlrev_b32_e32 v243, 16, v194
	v_and_b32_e32 v246, 0xffff0000, v194
	v_cndmask_b32_e32 v243, v243, v202, vcc
	v_cndmask_b32_e32 v246, v246, v203, vcc
	v_sub_f32_e32 v243, v243, v241
	v_sub_f32_e32 v246, v246, v245
	v_fmac_f32_e32 v241, v162, v243
	v_fmac_f32_e32 v245, v163, v246
	v_fmac_f32_e32 v240, v234, v241
	v_fmac_f32_e32 v244, v234, v245
	v_mul_f32_e32 v64, v64, v240
	v_mul_f32_e32 v65, v65, v244
	v_lshlrev_b32_e32 v240, 16, v179
	v_and_b32_e32 v244, 0xffff0000, v179
	v_sub_f32_e32 v240, v240, v238
	v_sub_f32_e32 v244, v244, v238
	v_mul_f32_e32 v240, v240, v239
	v_mul_f32_e32 v244, v244, v239
	v_fma_f32 v240, v132, v240, v148
	v_fma_f32 v244, v133, v244, v149
	v_lshlrev_b32_e32 v241, 16, v187
	v_and_b32_e32 v245, 0xffff0000, v187
	v_lshlrev_b32_e32 v243, 16, v195
	v_and_b32_e32 v246, 0xffff0000, v195
	v_cndmask_b32_e32 v243, v243, v204, vcc
	v_cndmask_b32_e32 v246, v246, v205, vcc
	v_sub_f32_e32 v243, v243, v241
	v_sub_f32_e32 v246, v246, v245
	v_fmac_f32_e32 v241, v164, v243
	v_fmac_f32_e32 v245, v165, v246
	v_fmac_f32_e32 v240, v234, v241
	v_fmac_f32_e32 v244, v234, v245
	v_mul_f32_e32 v66, v66, v240
	v_mul_f32_e32 v67, v67, v244
	v_lshlrev_b32_e32 v240, 16, v180
	v_and_b32_e32 v244, 0xffff0000, v180
	v_sub_f32_e32 v240, v240, v238
	v_sub_f32_e32 v244, v244, v238
	v_mul_f32_e32 v240, v240, v239
	v_mul_f32_e32 v244, v244, v239
	v_fma_f32 v240, v134, v240, v150
	v_fma_f32 v244, v135, v244, v151
	v_lshlrev_b32_e32 v241, 16, v188
	v_and_b32_e32 v245, 0xffff0000, v188
	v_lshlrev_b32_e32 v243, 16, v196
	v_and_b32_e32 v246, 0xffff0000, v196
	v_cndmask_b32_e32 v243, v243, v206, vcc
	v_cndmask_b32_e32 v246, v246, v207, vcc
	v_sub_f32_e32 v243, v243, v241
	v_sub_f32_e32 v246, v246, v245
	v_fmac_f32_e32 v241, v166, v243
	v_fmac_f32_e32 v245, v167, v246
	v_fmac_f32_e32 v240, v234, v241
	v_fmac_f32_e32 v244, v234, v245
	v_mul_f32_e32 v68, v68, v240
	v_mul_f32_e32 v69, v69, v244
	v_lshlrev_b32_e32 v240, 16, v181
	v_and_b32_e32 v244, 0xffff0000, v181
	v_sub_f32_e32 v240, v240, v238
; __device__ __forceinline__ float bf2f(u16 h) { return __uint_as_float(((unsigned)h) << 16); }
; template <int EPI> ...
;     ...
;       for (int i = 0; i < 16; i++) {
;         const int rl = rbase + (i & 3) + 8 * (i >> 2);
;         const int row = m0 + rl;
;         float o0 = bf2f(Y[(size_t)row * 1024 + 256 + ch0]);
;         float o1 = bf2f(Y[(size_t)row * 1024 + 256 + ch1]);
;         float mean = hsum32(o0 + o1) * (1.0f / 64.0f);
;         float d0 = o0 - mean, d1 = o1 - mean;
;         float var = hsum32(d0 * d0 + d1 * d1) * (1.0f / 64.0f);
;         float rstd = rsqrtf(var + 64e-5f);
;         float pv0 = bf2f(P[(size_t)row * 2816 + 256 + 1536 + ch0]);
;         float pv1 = bf2f(P[(size_t)row * 2816 + 256 + 1536 + ch1]);
;         float pp0 = prevP(p, P, row, 1536 + ch0), pp1 = prevP(p, P, row, 1536 + ch1);
;         float vv0 = pv0 + (pp0 - pv0) * mu0, vv1 = pv1 + (pp1 - pv1) * mu1;
;         float b = bs[((size_t)row * 12 + hh) * 4 + 2];
;         float y0 = (d0 * rstd * gg0 + gb0 + b * vv0) * acc0[i];
;         float y1 = (d1 * rstd * gg1 + gb1 + b * vv1) * acc1[i];
;         Y[(size_t)row * 1024 + 256 + ch0] = f2bf(y0);
;         Y[(size_t)row * 1024 + 256 + ch1] = f2bf(y1);
;       }
	v_sub_f32_e32 v244, v244, v238
	v_mul_f32_e32 v240, v240, v239
	v_mul_f32_e32 v244, v244, v239
	v_fma_f32 v240, v136, v240, v152
	v_fma_f32 v244, v137, v244, v153
	v_lshlrev_b32_e32 v241, 16, v189
	v_and_b32_e32 v245, 0xffff0000, v189
	v_lshlrev_b32_e32 v243, 16, v197
	v_and_b32_e32 v246, 0xffff0000, v197
	v_cndmask_b32_e32 v243, v243, v208, vcc
	v_cndmask_b32_e32 v246, v246, v209, vcc
	v_sub_f32_e32 v243, v243, v241
	v_sub_f32_e32 v246, v246, v245
	v_fmac_f32_e32 v241, v168, v243
	v_fmac_f32_e32 v245, v169, v246
	v_fmac_f32_e32 v240, v234, v241
	v_fmac_f32_e32 v244, v234, v245
	v_mul_f32_e32 v70, v70, v240
	v_mul_f32_e32 v71, v71, v244
	v_cvt_pk_bf16_f32 v64, v64, v65
	v_cvt_pk_bf16_f32 v65, v66, v67
	v_cvt_pk_bf16_f32 v66, v68, v69
	v_cvt_pk_bf16_f32 v67, v70, v71
	v_add_u32_e32 v236, 0x10000, v230
	s_nop 0
	global_store_dwordx4 v236, v[64:67], s[22:23] offset:0
	v_lshlrev_b32_e32 v240, 16, v182
	v_and_b32_e32 v244, 0xffff0000, v182
	v_sub_f32_e32 v240, v240, v238
	v_sub_f32_e32 v244, v244, v238
	v_mul_f32_e32 v240, v240, v239
	v_mul_f32_e32 v244, v244, v239
	v_fma_f32 v240, v138, v240, v154
	v_fma_f32 v244, v139, v244, v155
	v_lshlrev_b32_e32 v241, 16, v190
	v_and_b32_e32 v245, 0xffff0000, v190
	v_lshlrev_b32_e32 v243, 16, v198
	v_and_b32_e32 v246, 0xffff0000, v198
	v_cndmask_b32_e32 v243, v243, v210, vcc
	v_cndmask_b32_e32 v246, v246, v211, vcc
	v_sub_f32_e32 v243, v243, v241
	v_sub_f32_e32 v246, v246, v245
	v_fmac_f32_e32 v241, v170, v243
	v_fmac_f32_e32 v245, v171, v246
	v_fmac_f32_e32 v240, v234, v241
	v_fmac_f32_e32 v244, v234, v245
	v_mul_f32_e32 v72, v72, v240
	v_mul_f32_e32 v73, v73, v244
	v_lshlrev_b32_e32 v240, 16, v183
	v_and_b32_e32 v244, 0xffff0000, v183
	v_sub_f32_e32 v240, v240, v238
	v_sub_f32_e32 v244, v244, v238
	v_mul_f32_e32 v240, v240, v239
	v_mul_f32_e32 v244, v244, v239
	v_fma_f32 v240, v140, v240, v156
	v_fma_f32 v244, v141, v244, v157
	v_lshlrev_b32_e32 v241, 16, v191
	v_and_b32_e32 v245, 0xffff0000, v191
	v_lshlrev_b32_e32 v243, 16, v199
	v_and_b32_e32 v246, 0xffff0000, v199
	v_cndmask_b32_e32 v243, v243, v212, vcc
	v_cndmask_b32_e32 v246, v246, v213, vcc
	v_sub_f32_e32 v243, v243, v241
	v_sub_f32_e32 v246, v246, v245
	v_fmac_f32_e32 v241, v172, v243
	v_fmac_f32_e32 v245, v173, v246
	v_fmac_f32_e32 v240, v234, v241
	v_fmac_f32_e32 v244, v234, v245
	v_mul_f32_e32 v74, v74, v240
	v_mul_f32_e32 v75, v75, v244
	v_lshlrev_b32_e32 v240, 16, v184
	v_and_b32_e32 v244, 0xffff0000, v184
	v_sub_f32_e32 v240, v240, v238
	v_sub_f32_e32 v244, v244, v238
	v_mul_f32_e32 v240, v240, v239
	v_mul_f32_e32 v244, v244, v239
	v_fma_f32 v240, v142, v240, v158
	v_fma_f32 v244, v143, v244, v159
	v_lshlrev_b32_e32 v241, 16, v192
	v_and_b32_e32 v245, 0xffff0000, v192
	v_lshlrev_b32_e32 v243, 16, v200
	v_and_b32_e32 v246, 0xffff0000, v200
	v_cndmask_b32_e32 v243, v243, v214, vcc
	v_cndmask_b32_e32 v246, v246, v215, vcc
	v_sub_f32_e32 v243, v243, v241
	v_sub_f32_e32 v246, v246, v245
	v_fmac_f32_e32 v241, v174, v243
	v_fmac_f32_e32 v245, v175, v246
	v_fmac_f32_e32 v240, v234, v241
	v_fmac_f32_e32 v244, v234, v245
	v_mul_f32_e32 v76, v76, v240
	v_mul_f32_e32 v77, v77, v244
	v_lshlrev_b32_e32 v240, 16, v185
	v_and_b32_e32 v244, 0xffff0000, v185
	v_sub_f32_e32 v240, v240, v238
	v_sub_f32_e32 v244, v244, v238
	v_mul_f32_e32 v240, v240, v239
	v_mul_f32_e32 v244, v244, v239
	v_fma_f32 v240, v144, v240, v160
	v_fma_f32 v244, v145, v244, v161
	v_lshlrev_b32_e32 v241, 16, v193
	v_and_b32_e32 v245, 0xffff0000, v193
	v_lshlrev_b32_e32 v243, 16, v201
	v_and_b32_e32 v246, 0xffff0000, v201
	v_cndmask_b32_e32 v243, v243, v216, vcc
	v_cndmask_b32_e32 v246, v246, v217, vcc
	v_sub_f32_e32 v243, v243, v241
	v_sub_f32_e32 v246, v246, v245
	v_fmac_f32_e32 v241, v176, v243
	v_fmac_f32_e32 v245, v177, v246
	v_fmac_f32_e32 v240, v234, v241
	v_fmac_f32_e32 v244, v234, v245
	v_mul_f32_e32 v78, v78, v240
	v_mul_f32_e32 v79, v79, v244
	v_cvt_pk_bf16_f32 v72, v72, v73
	v_cvt_pk_bf16_f32 v73, v74, v75
	v_cvt_pk_bf16_f32 v74, v76, v77
	v_cvt_pk_bf16_f32 v75, v78, v79
	v_add_u32_e32 v236, 0x10000, v230
	s_nop 0
	global_store_dwordx4 v236, v[72:75], s[22:23] offset:64
	v_add_u32_e32 v236, 0x18000, v230
	v_add_u32_e32 v237, 0x42000, v231
	v_subrev_u32_e32 v240, 0x1600, v237
	global_load_dwordx4 v[178:181], v236, s[22:23] offset:0
	global_load_dwordx4 v[182:185], v236, s[22:23] offset:64
	global_load_dwordx4 v[186:189], v237, s[96:97] offset:0
	global_load_dwordx4 v[190:193], v237, s[96:97] offset:64
	global_load_dwordx4 v[194:197], v240, s[96:97] offset:0
	global_load_dwordx4 v[198:201], v240, s[96:97] offset:64
	v_add_u32_e32 v236, 0x2400, v232
	s_nop 0
	global_load_dword v234, v236, s[96:97] offset:0
	v_add_u32_e32 v237, 0x1e000, v247
	global_load_dwordx4 v[202:205], v237, s[20:21] offset:0
	global_load_dwordx4 v[206:209], v237, s[20:21] offset:16
	global_load_dwordx4 v[210:213], v237, s[20:21] offset:128
	global_load_dwordx4 v[214:217], v237, s[20:21] offset:144
	s_waitcnt vmcnt(0)
; __device__ __forceinline__ float bf2f(u16 h) { return __uint_as_float(((unsigned)h) << 16); }
; template <int EPI> ...
;     ...
;         float o0 = bf2f(Y[(size_t)row * 1024 + 256 + ch0]);
;         float o1 = bf2f(Y[(size_t)row * 1024 + 256 + ch1]);
;         float mean = hsum32(o0 + o1) * (1.0f / 64.0f);
;         float d0 = o0 - mean, d1 = o1 - mean;
;         float var = hsum32(d0 * d0 + d1 * d1) * (1.0f / 64.0f);
;         float rstd = rsqrtf(var + 64e-5f);
;         float pv0 = bf2f(P[(size_t)row * 2816 + 256 + 1536 + ch0]);
;         float pv1 = bf2f(P[(size_t)row * 2816 + 256 + 1536 + ch1]);
;         float pp0 = prevP(p, P, row, 1536 + ch0), pp1 = prevP(p, P, row, 1536 + ch1);
;         float vv0 = pv0 + (pp0 - pv0) * mu0, vv1 = pv1 + (pp1 - pv1) * mu1;
;         float b = bs[((size_t)row * 12 + hh) * 4 + 2];
;         float y0 = (d0 * rstd * gg0 + gb0 + b * vv0) * acc0[i];
;         float y1 = (d1 * rstd * gg1 + gb1 + b * vv1) * acc1[i];
	v_lshlrev_b32_e32 v240, 16, v178
	v_and_b32_e32 v241, 0xffff0000, v178
	v_add_f32_e32 v244, v240, v241
	v_lshlrev_b32_e32 v240, 16, v179
	v_and_b32_e32 v241, 0xffff0000, v179
	v_add_f32_e32 v244, v244, v240
	v_add_f32_e32 v244, v244, v241
	v_lshlrev_b32_e32 v240, 16, v180
	v_and_b32_e32 v241, 0xffff0000, v180
	v_add_f32_e32 v244, v244, v240
	v_add_f32_e32 v244, v244, v241
	v_lshlrev_b32_e32 v240, 16, v181
	v_and_b32_e32 v241, 0xffff0000, v181
	v_add_f32_e32 v244, v244, v240
	v_add_f32_e32 v244, v244, v241
	v_lshlrev_b32_e32 v240, 16, v182
	v_and_b32_e32 v241, 0xffff0000, v182
	v_add_f32_e32 v244, v244, v240
	v_add_f32_e32 v244, v244, v241
	v_lshlrev_b32_e32 v240, 16, v183
	v_and_b32_e32 v241, 0xffff0000, v183
	v_add_f32_e32 v244, v244, v240
	v_add_f32_e32 v244, v244, v241
	v_lshlrev_b32_e32 v240, 16, v184
	v_and_b32_e32 v241, 0xffff0000, v184
	v_add_f32_e32 v244, v244, v240
	v_add_f32_e32 v244, v244, v241
	v_lshlrev_b32_e32 v240, 16, v185
	v_and_b32_e32 v241, 0xffff0000, v185
	v_add_f32_e32 v244, v244, v240
	v_add_f32_e32 v244, v244, v241
	v_mov_b32_e32 v240, v244
	s_nop 1
	v_permlane16_swap_b32_e32 v240, v244
	v_add_f32_e32 v244, v244, v240
	v_mov_b32_e32 v240, v244
	s_nop 1
	v_permlane32_swap_b32_e32 v240, v244
	v_add_f32_e32 v244, v244, v240
	v_mul_f32_e32 v238, 0x3c800000, v244
	v_lshlrev_b32_e32 v240, 16, v178
	v_and_b32_e32 v241, 0xffff0000, v178
	v_sub_f32_e32 v240, v240, v238
	v_sub_f32_e32 v241, v241, v238
	v_mul_f32_e32 v245, v240, v240
	v_fmac_f32_e32 v245, v241, v241
	v_lshlrev_b32_e32 v240, 16, v179
	v_and_b32_e32 v241, 0xffff0000, v179
	v_sub_f32_e32 v240, v240, v238
	v_sub_f32_e32 v241, v241, v238
	v_fmac_f32_e32 v245, v240, v240
	v_fmac_f32_e32 v245, v241, v241
	v_lshlrev_b32_e32 v240, 16, v180
	v_and_b32_e32 v241, 0xffff0000, v180
	v_sub_f32_e32 v240, v240, v238
	v_sub_f32_e32 v241, v241, v238
	v_fmac_f32_e32 v245, v240, v240
	v_fmac_f32_e32 v245, v241, v241
	v_lshlrev_b32_e32 v240, 16, v181
	v_and_b32_e32 v241, 0xffff0000, v181
	v_sub_f32_e32 v240, v240, v238
	v_sub_f32_e32 v241, v241, v238
	v_fmac_f32_e32 v245, v240, v240
	v_fmac_f32_e32 v245, v241, v241
	v_lshlrev_b32_e32 v240, 16, v182
	v_and_b32_e32 v241, 0xffff0000, v182
	v_sub_f32_e32 v240, v240, v238
	v_sub_f32_e32 v241, v241, v238
	v_fmac_f32_e32 v245, v240, v240
	v_fmac_f32_e32 v245, v241, v241
	v_lshlrev_b32_e32 v240, 16, v183
	v_and_b32_e32 v241, 0xffff0000, v183
	v_sub_f32_e32 v240, v240, v238
	v_sub_f32_e32 v241, v241, v238
	v_fmac_f32_e32 v245, v240, v240
	v_fmac_f32_e32 v245, v241, v241
	v_lshlrev_b32_e32 v240, 16, v184
	v_and_b32_e32 v241, 0xffff0000, v184
	v_sub_f32_e32 v240, v240, v238
	v_sub_f32_e32 v241, v241, v238
	v_fmac_f32_e32 v245, v240, v240
	v_fmac_f32_e32 v245, v241, v241
	v_lshlrev_b32_e32 v240, 16, v185
	v_and_b32_e32 v241, 0xffff0000, v185
	v_sub_f32_e32 v240, v240, v238
	v_sub_f32_e32 v241, v241, v238
	v_fmac_f32_e32 v245, v240, v240
	v_fmac_f32_e32 v245, v241, v241
	v_mov_b32_e32 v240, v245
	s_nop 1
	v_permlane16_swap_b32_e32 v240, v245
	v_add_f32_e32 v245, v245, v240
	v_mov_b32_e32 v240, v245
	s_nop 1
	v_permlane32_swap_b32_e32 v240, v245
	v_add_f32_e32 v245, v245, v240
	v_mov_b32_e32 v240, 0x3a27c5ac
	v_fmamk_f32 v245, v245, 0x3c800000, v240
	v_rsq_f32_e32 v239, v245
	v_and_b32_e32 v240, 3, v248
	v_cmp_eq_u32_e32 vcc, 0, v240
	s_nop 1
	v_lshlrev_b32_e32 v240, 16, v178
	v_and_b32_e32 v244, 0xffff0000, v178
	v_sub_f32_e32 v240, v240, v238
	v_sub_f32_e32 v244, v244, v238
	v_mul_f32_e32 v240, v240, v239
	v_mul_f32_e32 v244, v244, v239
	v_fma_f32 v240, v130, v240, v146
	v_fma_f32 v244, v131, v244, v147
	v_lshlrev_b32_e32 v241, 16, v186
	v_and_b32_e32 v245, 0xffff0000, v186
	v_lshlrev_b32_e32 v243, 16, v194
	v_and_b32_e32 v246, 0xffff0000, v194
	v_cndmask_b32_e32 v243, v243, v202, vcc
	v_cndmask_b32_e32 v246, v246, v203, vcc
	v_sub_f32_e32 v243, v243, v241
	v_sub_f32_e32 v246, v246, v245
	v_fmac_f32_e32 v241, v162, v243
	v_fmac_f32_e32 v245, v163, v246
	v_fmac_f32_e32 v240, v234, v241
	v_fmac_f32_e32 v244, v234, v245
	v_mul_f32_e32 v96, v96, v240
	v_mul_f32_e32 v97, v97, v244
	v_lshlrev_b32_e32 v240, 16, v179
	v_and_b32_e32 v244, 0xffff0000, v179
	v_sub_f32_e32 v240, v240, v238
	v_sub_f32_e32 v244, v244, v238
	v_mul_f32_e32 v240, v240, v239
	v_mul_f32_e32 v244, v244, v239
	v_fma_f32 v240, v132, v240, v148
	v_fma_f32 v244, v133, v244, v149
	v_lshlrev_b32_e32 v241, 16, v187
	v_and_b32_e32 v245, 0xffff0000, v187
	v_lshlrev_b32_e32 v243, 16, v195
	v_and_b32_e32 v246, 0xffff0000, v195
	v_cndmask_b32_e32 v243, v243, v204, vcc
	v_cndmask_b32_e32 v246, v246, v205, vcc
	v_sub_f32_e32 v243, v243, v241
	v_sub_f32_e32 v246, v246, v245
	v_fmac_f32_e32 v241, v164, v243
	v_fmac_f32_e32 v245, v165, v246
	v_fmac_f32_e32 v240, v234, v241
	v_fmac_f32_e32 v244, v234, v245
	v_mul_f32_e32 v98, v98, v240
	v_mul_f32_e32 v99, v99, v244
	v_lshlrev_b32_e32 v240, 16, v180
	v_and_b32_e32 v244, 0xffff0000, v180
	v_sub_f32_e32 v240, v240, v238
	v_sub_f32_e32 v244, v244, v238
	v_mul_f32_e32 v240, v240, v239
	v_mul_f32_e32 v244, v244, v239
	v_fma_f32 v240, v134, v240, v150
	v_fma_f32 v244, v135, v244, v151
	v_lshlrev_b32_e32 v241, 16, v188
	v_and_b32_e32 v245, 0xffff0000, v188
	v_lshlrev_b32_e32 v243, 16, v196
	v_and_b32_e32 v246, 0xffff0000, v196
	v_cndmask_b32_e32 v243, v243, v206, vcc
	v_cndmask_b32_e32 v246, v246, v207, vcc
	v_sub_f32_e32 v243, v243, v241
	v_sub_f32_e32 v246, v246, v245
	v_fmac_f32_e32 v241, v166, v243
	v_fmac_f32_e32 v245, v167, v246
	v_fmac_f32_e32 v240, v234, v241
	v_fmac_f32_e32 v244, v234, v245
	v_mul_f32_e32 v100, v100, v240
	v_mul_f32_e32 v101, v101, v244
	v_lshlrev_b32_e32 v240, 16, v181
	v_and_b32_e32 v244, 0xffff0000, v181
; __device__ __forceinline__ float bf2f(u16 h) { return __uint_as_float(((unsigned)h) << 16); }
; template <int EPI> ...
;     ...
;       const float gg0 = p.in[20][ch0], gg1 = p.in[20][ch1];
;       const float gb0 = p.in[21][ch0], gb1 = p.in[21][ch1];
;       const float mu0 = p.in[11][1536 + ch0], mu1 = p.in[11][1536 + ch1];
;     ...
;       for (int i = 0; i < 16; i++) {
;         const int rl = rbase + (i & 3) + 8 * (i >> 2);
;         const int row = m0 + rl;
;         float o0 = bf2f(Y[(size_t)row * 1024 + 256 + ch0]);
;         float o1 = bf2f(Y[(size_t)row * 1024 + 256 + ch1]);
;         float mean = hsum32(o0 + o1) * (1.0f / 64.0f);
;         float d0 = o0 - mean, d1 = o1 - mean;
;         float var = hsum32(d0 * d0 + d1 * d1) * (1.0f / 64.0f);
;         float rstd = rsqrtf(var + 64e-5f);
;         float pv0 = bf2f(P[(size_t)row * 2816 + 256 + 1536 + ch0]);
;         float pv1 = bf2f(P[(size_t)row * 2816 + 256 + 1536 + ch1]);
;         float pp0 = prevP(p, P, row, 1536 + ch0), pp1 = prevP(p, P, row, 1536 + ch1);
;         float vv0 = pv0 + (pp0 - pv0) * mu0, vv1 = pv1 + (pp1 - pv1) * mu1;
;         float b = bs[((size_t)row * 12 + hh) * 4 + 2];
;         float y0 = (d0 * rstd * gg0 + gb0 + b * vv0) * acc0[i];
;         float y1 = (d1 * rstd * gg1 + gb1 + b * vv1) * acc1[i];
;         Y[(size_t)row * 1024 + 256 + ch0] = f2bf(y0);
;         Y[(size_t)row * 1024 + 256 + ch1] = f2bf(y1);
;       }
	v_sub_f32_e32 v240, v240, v238
	v_sub_f32_e32 v244, v244, v238
	v_mul_f32_e32 v240, v240, v239
	v_mul_f32_e32 v244, v244, v239
	v_fma_f32 v240, v136, v240, v152
	v_fma_f32 v244, v137, v244, v153
	v_lshlrev_b32_e32 v241, 16, v189
	v_and_b32_e32 v245, 0xffff0000, v189
	v_lshlrev_b32_e32 v243, 16, v197
	v_and_b32_e32 v246, 0xffff0000, v197
	v_cndmask_b32_e32 v243, v243, v208, vcc
	v_cndmask_b32_e32 v246, v246, v209, vcc
	v_sub_f32_e32 v243, v243, v241
	v_sub_f32_e32 v246, v246, v245
	v_fmac_f32_e32 v241, v168, v243
	v_fmac_f32_e32 v245, v169, v246
	v_fmac_f32_e32 v240, v234, v241
	v_fmac_f32_e32 v244, v234, v245
	v_mul_f32_e32 v102, v102, v240
	v_mul_f32_e32 v103, v103, v244
	v_cvt_pk_bf16_f32 v96, v96, v97
	v_cvt_pk_bf16_f32 v97, v98, v99
	v_cvt_pk_bf16_f32 v98, v100, v101
	v_cvt_pk_bf16_f32 v99, v102, v103
	v_add_u32_e32 v236, 0x18000, v230
	s_nop 0
	global_store_dwordx4 v236, v[96:99], s[22:23] offset:0
	v_lshlrev_b32_e32 v240, 16, v182
	v_and_b32_e32 v244, 0xffff0000, v182
	v_sub_f32_e32 v240, v240, v238
	v_sub_f32_e32 v244, v244, v238
	v_mul_f32_e32 v240, v240, v239
	v_mul_f32_e32 v244, v244, v239
	v_fma_f32 v240, v138, v240, v154
	v_fma_f32 v244, v139, v244, v155
	v_lshlrev_b32_e32 v241, 16, v190
	v_and_b32_e32 v245, 0xffff0000, v190
	v_lshlrev_b32_e32 v243, 16, v198
	v_and_b32_e32 v246, 0xffff0000, v198
	v_cndmask_b32_e32 v243, v243, v210, vcc
	v_cndmask_b32_e32 v246, v246, v211, vcc
	v_sub_f32_e32 v243, v243, v241
	v_sub_f32_e32 v246, v246, v245
	v_fmac_f32_e32 v241, v170, v243
	v_fmac_f32_e32 v245, v171, v246
	v_fmac_f32_e32 v240, v234, v241
	v_fmac_f32_e32 v244, v234, v245
	v_mul_f32_e32 v104, v104, v240
	v_mul_f32_e32 v105, v105, v244
	v_lshlrev_b32_e32 v240, 16, v183
	v_and_b32_e32 v244, 0xffff0000, v183
	v_sub_f32_e32 v240, v240, v238
	v_sub_f32_e32 v244, v244, v238
	v_mul_f32_e32 v240, v240, v239
	v_mul_f32_e32 v244, v244, v239
	v_fma_f32 v240, v140, v240, v156
	v_fma_f32 v244, v141, v244, v157
	v_lshlrev_b32_e32 v241, 16, v191
	v_and_b32_e32 v245, 0xffff0000, v191
	v_lshlrev_b32_e32 v243, 16, v199
	v_and_b32_e32 v246, 0xffff0000, v199
	v_cndmask_b32_e32 v243, v243, v212, vcc
	v_cndmask_b32_e32 v246, v246, v213, vcc
	v_sub_f32_e32 v243, v243, v241
	v_sub_f32_e32 v246, v246, v245
	v_fmac_f32_e32 v241, v172, v243
	v_fmac_f32_e32 v245, v173, v246
	v_fmac_f32_e32 v240, v234, v241
	v_fmac_f32_e32 v244, v234, v245
	v_mul_f32_e32 v106, v106, v240
	v_mul_f32_e32 v107, v107, v244
	v_lshlrev_b32_e32 v240, 16, v184
	v_and_b32_e32 v244, 0xffff0000, v184
	v_sub_f32_e32 v240, v240, v238
	v_sub_f32_e32 v244, v244, v238
	v_mul_f32_e32 v240, v240, v239
	v_mul_f32_e32 v244, v244, v239
	v_fma_f32 v240, v142, v240, v158
	v_fma_f32 v244, v143, v244, v159
	v_lshlrev_b32_e32 v241, 16, v192
	v_and_b32_e32 v245, 0xffff0000, v192
	v_lshlrev_b32_e32 v243, 16, v200
	v_and_b32_e32 v246, 0xffff0000, v200
	v_cndmask_b32_e32 v243, v243, v214, vcc
	v_cndmask_b32_e32 v246, v246, v215, vcc
	v_sub_f32_e32 v243, v243, v241
	v_sub_f32_e32 v246, v246, v245
	v_fmac_f32_e32 v241, v174, v243
	v_fmac_f32_e32 v245, v175, v246
	v_fmac_f32_e32 v240, v234, v241
	v_fmac_f32_e32 v244, v234, v245
	v_mul_f32_e32 v108, v108, v240
	v_mul_f32_e32 v109, v109, v244
	v_lshlrev_b32_e32 v240, 16, v185
	v_and_b32_e32 v244, 0xffff0000, v185
	v_sub_f32_e32 v240, v240, v238
	v_sub_f32_e32 v244, v244, v238
	v_mul_f32_e32 v240, v240, v239
	v_mul_f32_e32 v244, v244, v239
	v_fma_f32 v240, v144, v240, v160
	v_fma_f32 v244, v145, v244, v161
	v_lshlrev_b32_e32 v241, 16, v193
	v_and_b32_e32 v245, 0xffff0000, v193
	v_lshlrev_b32_e32 v243, 16, v201
	v_and_b32_e32 v246, 0xffff0000, v201
	v_cndmask_b32_e32 v243, v243, v216, vcc
	v_cndmask_b32_e32 v246, v246, v217, vcc
	v_sub_f32_e32 v243, v243, v241
	v_sub_f32_e32 v246, v246, v245
	v_fmac_f32_e32 v241, v176, v243
	v_fmac_f32_e32 v245, v177, v246
	v_fmac_f32_e32 v240, v234, v241
	v_fmac_f32_e32 v244, v234, v245
	v_mul_f32_e32 v110, v110, v240
	v_mul_f32_e32 v111, v111, v244
	v_cvt_pk_bf16_f32 v104, v104, v105
	v_cvt_pk_bf16_f32 v105, v106, v107
	v_cvt_pk_bf16_f32 v106, v108, v109
	v_cvt_pk_bf16_f32 v107, v110, v111
	v_add_u32_e32 v236, 0x18000, v230
	s_nop 0
	global_store_dwordx4 v236, v[104:107], s[22:23] offset:64
	global_load_dwordx4 v[130:133], v233, s[2:3] offset:256
	global_load_dwordx4 v[134:137], v233, s[2:3] offset:272
	global_load_dwordx4 v[138:141], v233, s[2:3] offset:384
	global_load_dwordx4 v[142:145], v233, s[2:3] offset:400
	global_load_dwordx4 v[146:149], v233, s[16:17] offset:256
	global_load_dwordx4 v[150:153], v233, s[16:17] offset:272
	global_load_dwordx4 v[154:157], v233, s[16:17] offset:384
	global_load_dwordx4 v[158:161], v233, s[16:17] offset:400
	global_load_dwordx4 v[162:165], v233, s[0:1] offset:256
	global_load_dwordx4 v[166:169], v233, s[0:1] offset:272
	global_load_dwordx4 v[170:173], v233, s[0:1] offset:384
	global_load_dwordx4 v[174:177], v233, s[0:1] offset:400
	v_add_u32_e32 v236, 0x0, v230
	v_add_u32_e32 v237, 0x0, v231
	v_subrev_u32_e32 v240, 0x1600, v237
	global_load_dwordx4 v[178:181], v236, s[22:23] offset:128
	global_load_dwordx4 v[182:185], v236, s[22:23] offset:192
	global_load_dwordx4 v[186:189], v237, s[96:97] offset:128
	global_load_dwordx4 v[190:193], v237, s[96:97] offset:192
	global_load_dwordx4 v[194:197], v240, s[96:97] offset:128
	global_load_dwordx4 v[198:201], v240, s[96:97] offset:192
	v_add_u32_e32 v236, 0x0, v232
	s_nop 0
	global_load_dword v234, v236, s[96:97] offset:16
	v_add_u32_e32 v237, 0x0, v247
	global_load_dwordx4 v[202:205], v237, s[20:21] offset:256
	global_load_dwordx4 v[206:209], v237, s[20:21] offset:272
	global_load_dwordx4 v[210:213], v237, s[20:21] offset:384
	global_load_dwordx4 v[214:217], v237, s[20:21] offset:400
	s_waitcnt vmcnt(0)
; __device__ __forceinline__ float bf2f(u16 h) { return __uint_as_float(((unsigned)h) << 16); }
; template <int EPI> ...
;     ...
;         float o0 = bf2f(Y[(size_t)row * 1024 + 256 + ch0]);
;         float o1 = bf2f(Y[(size_t)row * 1024 + 256 + ch1]);
;         float mean = hsum32(o0 + o1) * (1.0f / 64.0f);
;         float d0 = o0 - mean, d1 = o1 - mean;
;         float var = hsum32(d0 * d0 + d1 * d1) * (1.0f / 64.0f);
;         float rstd = rsqrtf(var + 64e-5f);
;         float pv0 = bf2f(P[(size_t)row * 2816 + 256 + 1536 + ch0]);
;         float pv1 = bf2f(P[(size_t)row * 2816 + 256 + 1536 + ch1]);
;         float pp0 = prevP(p, P, row, 1536 + ch0), pp1 = prevP(p, P, row, 1536 + ch1);
;         float vv0 = pv0 + (pp0 - pv0) * mu0, vv1 = pv1 + (pp1 - pv1) * mu1;
;         float b = bs[((size_t)row * 12 + hh) * 4 + 2];
;         float y0 = (d0 * rstd * gg0 + gb0 + b * vv0) * acc0[i];
;         float y1 = (d1 * rstd * gg1 + gb1 + b * vv1) * acc1[i];
	v_lshlrev_b32_e32 v240, 16, v178
	v_and_b32_e32 v241, 0xffff0000, v178
	v_add_f32_e32 v244, v240, v241
	v_lshlrev_b32_e32 v240, 16, v179
	v_and_b32_e32 v241, 0xffff0000, v179
	v_add_f32_e32 v244, v244, v240
	v_add_f32_e32 v244, v244, v241
	v_lshlrev_b32_e32 v240, 16, v180
	v_and_b32_e32 v241, 0xffff0000, v180
	v_add_f32_e32 v244, v244, v240
	v_add_f32_e32 v244, v244, v241
	v_lshlrev_b32_e32 v240, 16, v181
	v_and_b32_e32 v241, 0xffff0000, v181
	v_add_f32_e32 v244, v244, v240
	v_add_f32_e32 v244, v244, v241
	v_lshlrev_b32_e32 v240, 16, v182
	v_and_b32_e32 v241, 0xffff0000, v182
	v_add_f32_e32 v244, v244, v240
	v_add_f32_e32 v244, v244, v241
	v_lshlrev_b32_e32 v240, 16, v183
	v_and_b32_e32 v241, 0xffff0000, v183
	v_add_f32_e32 v244, v244, v240
	v_add_f32_e32 v244, v244, v241
	v_lshlrev_b32_e32 v240, 16, v184
	v_and_b32_e32 v241, 0xffff0000, v184
	v_add_f32_e32 v244, v244, v240
	v_add_f32_e32 v244, v244, v241
	v_lshlrev_b32_e32 v240, 16, v185
	v_and_b32_e32 v241, 0xffff0000, v185
	v_add_f32_e32 v244, v244, v240
	v_add_f32_e32 v244, v244, v241
	v_mov_b32_e32 v240, v244
	s_nop 1
	v_permlane16_swap_b32_e32 v240, v244
	v_add_f32_e32 v244, v244, v240
	v_mov_b32_e32 v240, v244
	s_nop 1
	v_permlane32_swap_b32_e32 v240, v244
	v_add_f32_e32 v244, v244, v240
	v_mul_f32_e32 v238, 0x3c800000, v244
	v_lshlrev_b32_e32 v240, 16, v178
	v_and_b32_e32 v241, 0xffff0000, v178
	v_sub_f32_e32 v240, v240, v238
	v_sub_f32_e32 v241, v241, v238
	v_mul_f32_e32 v245, v240, v240
	v_fmac_f32_e32 v245, v241, v241
	v_lshlrev_b32_e32 v240, 16, v179
	v_and_b32_e32 v241, 0xffff0000, v179
	v_sub_f32_e32 v240, v240, v238
	v_sub_f32_e32 v241, v241, v238
	v_fmac_f32_e32 v245, v240, v240
	v_fmac_f32_e32 v245, v241, v241
	v_lshlrev_b32_e32 v240, 16, v180
	v_and_b32_e32 v241, 0xffff0000, v180
	v_sub_f32_e32 v240, v240, v238
	v_sub_f32_e32 v241, v241, v238
	v_fmac_f32_e32 v245, v240, v240
	v_fmac_f32_e32 v245, v241, v241
	v_lshlrev_b32_e32 v240, 16, v181
	v_and_b32_e32 v241, 0xffff0000, v181
	v_sub_f32_e32 v240, v240, v238
	v_sub_f32_e32 v241, v241, v238
	v_fmac_f32_e32 v245, v240, v240
	v_fmac_f32_e32 v245, v241, v241
	v_lshlrev_b32_e32 v240, 16, v182
	v_and_b32_e32 v241, 0xffff0000, v182
	v_sub_f32_e32 v240, v240, v238
	v_sub_f32_e32 v241, v241, v238
	v_fmac_f32_e32 v245, v240, v240
	v_fmac_f32_e32 v245, v241, v241
	v_lshlrev_b32_e32 v240, 16, v183
	v_and_b32_e32 v241, 0xffff0000, v183
	v_sub_f32_e32 v240, v240, v238
	v_sub_f32_e32 v241, v241, v238
	v_fmac_f32_e32 v245, v240, v240
	v_fmac_f32_e32 v245, v241, v241
	v_lshlrev_b32_e32 v240, 16, v184
	v_and_b32_e32 v241, 0xffff0000, v184
	v_sub_f32_e32 v240, v240, v238
	v_sub_f32_e32 v241, v241, v238
	v_fmac_f32_e32 v245, v240, v240
	v_fmac_f32_e32 v245, v241, v241
	v_lshlrev_b32_e32 v240, 16, v185
	v_and_b32_e32 v241, 0xffff0000, v185
	v_sub_f32_e32 v240, v240, v238
	v_sub_f32_e32 v241, v241, v238
	v_fmac_f32_e32 v245, v240, v240
	v_fmac_f32_e32 v245, v241, v241
	v_mov_b32_e32 v240, v245
	s_nop 1
	v_permlane16_swap_b32_e32 v240, v245
	v_add_f32_e32 v245, v245, v240
	v_mov_b32_e32 v240, v245
	s_nop 1
	v_permlane32_swap_b32_e32 v240, v245
	v_add_f32_e32 v245, v245, v240
	v_mov_b32_e32 v240, 0x3a27c5ac
	v_fmamk_f32 v245, v245, 0x3c800000, v240
	v_rsq_f32_e32 v239, v245
	v_and_b32_e32 v240, 3, v248
	v_cmp_eq_u32_e32 vcc, 0, v240
	s_nop 1
	v_lshlrev_b32_e32 v240, 16, v178
	v_and_b32_e32 v244, 0xffff0000, v178
	v_sub_f32_e32 v240, v240, v238
	v_sub_f32_e32 v244, v244, v238
	v_mul_f32_e32 v240, v240, v239
	v_mul_f32_e32 v244, v244, v239
	v_fma_f32 v240, v130, v240, v146
	v_fma_f32 v244, v131, v244, v147
	v_lshlrev_b32_e32 v241, 16, v186
	v_and_b32_e32 v245, 0xffff0000, v186
	v_lshlrev_b32_e32 v243, 16, v194
	v_and_b32_e32 v246, 0xffff0000, v194
	v_cndmask_b32_e32 v243, v243, v202, vcc
	v_cndmask_b32_e32 v246, v246, v203, vcc
	v_sub_f32_e32 v243, v243, v241
	v_sub_f32_e32 v246, v246, v245
	v_fmac_f32_e32 v241, v162, v243
	v_fmac_f32_e32 v245, v163, v246
	v_fmac_f32_e32 v240, v234, v241
	v_fmac_f32_e32 v244, v234, v245
	v_mul_f32_e32 v16, v16, v240
	v_mul_f32_e32 v17, v17, v244
	v_lshlrev_b32_e32 v240, 16, v179
	v_and_b32_e32 v244, 0xffff0000, v179
	v_sub_f32_e32 v240, v240, v238
	v_sub_f32_e32 v244, v244, v238
	v_mul_f32_e32 v240, v240, v239
	v_mul_f32_e32 v244, v244, v239
	v_fma_f32 v240, v132, v240, v148
	v_fma_f32 v244, v133, v244, v149
	v_lshlrev_b32_e32 v241, 16, v187
	v_and_b32_e32 v245, 0xffff0000, v187
	v_lshlrev_b32_e32 v243, 16, v195
	v_and_b32_e32 v246, 0xffff0000, v195
	v_cndmask_b32_e32 v243, v243, v204, vcc
	v_cndmask_b32_e32 v246, v246, v205, vcc
	v_sub_f32_e32 v243, v243, v241
	v_sub_f32_e32 v246, v246, v245
	v_fmac_f32_e32 v241, v164, v243
	v_fmac_f32_e32 v245, v165, v246
	v_fmac_f32_e32 v240, v234, v241
	v_fmac_f32_e32 v244, v234, v245
	v_mul_f32_e32 v18, v18, v240
	v_mul_f32_e32 v19, v19, v244
	v_lshlrev_b32_e32 v240, 16, v180
	v_and_b32_e32 v244, 0xffff0000, v180
	v_sub_f32_e32 v240, v240, v238
	v_sub_f32_e32 v244, v244, v238
	v_mul_f32_e32 v240, v240, v239
	v_mul_f32_e32 v244, v244, v239
	v_fma_f32 v240, v134, v240, v150
	v_fma_f32 v244, v135, v244, v151
	v_lshlrev_b32_e32 v241, 16, v188
	v_and_b32_e32 v245, 0xffff0000, v188
	v_lshlrev_b32_e32 v243, 16, v196
	v_and_b32_e32 v246, 0xffff0000, v196
	v_cndmask_b32_e32 v243, v243, v206, vcc
	v_cndmask_b32_e32 v246, v246, v207, vcc
	v_sub_f32_e32 v243, v243, v241
	v_sub_f32_e32 v246, v246, v245
	v_fmac_f32_e32 v241, v166, v243
	v_fmac_f32_e32 v245, v167, v246
	v_fmac_f32_e32 v240, v234, v241
	v_fmac_f32_e32 v244, v234, v245
	v_mul_f32_e32 v20, v20, v240
	v_mul_f32_e32 v21, v21, v244
	v_lshlrev_b32_e32 v240, 16, v181
	v_and_b32_e32 v244, 0xffff0000, v181
	v_sub_f32_e32 v240, v240, v238
; __device__ __forceinline__ float bf2f(u16 h) { return __uint_as_float(((unsigned)h) << 16); }
; template <int EPI> ...
;     ...
;         float pv0 = bf2f(P[(size_t)row * 2816 + 256 + 1536 + ch0]);
;         float pv1 = bf2f(P[(size_t)row * 2816 + 256 + 1536 + ch1]);
;         float pp0 = prevP(p, P, row, 1536 + ch0), pp1 = prevP(p, P, row, 1536 + ch1);
;         float vv0 = pv0 + (pp0 - pv0) * mu0, vv1 = pv1 + (pp1 - pv1) * mu1;
;         float b = bs[((size_t)row * 12 + hh) * 4 + 2];
;         float y0 = (d0 * rstd * gg0 + gb0 + b * vv0) * acc0[i];
;         float y1 = (d1 * rstd * gg1 + gb1 + b * vv1) * acc1[i];
;         Y[(size_t)row * 1024 + 256 + ch0] = f2bf(y0);
;         Y[(size_t)row * 1024 + 256 + ch1] = f2bf(y1);
;       }
	v_sub_f32_e32 v244, v244, v238
	v_mul_f32_e32 v240, v240, v239
	v_mul_f32_e32 v244, v244, v239
	v_fma_f32 v240, v136, v240, v152
	v_fma_f32 v244, v137, v244, v153
	v_lshlrev_b32_e32 v241, 16, v189
	v_and_b32_e32 v245, 0xffff0000, v189
	v_lshlrev_b32_e32 v243, 16, v197
	v_and_b32_e32 v246, 0xffff0000, v197
	v_cndmask_b32_e32 v243, v243, v208, vcc
	v_cndmask_b32_e32 v246, v246, v209, vcc
	v_sub_f32_e32 v243, v243, v241
	v_sub_f32_e32 v246, v246, v245
	v_fmac_f32_e32 v241, v168, v243
	v_fmac_f32_e32 v245, v169, v246
	v_fmac_f32_e32 v240, v234, v241
	v_fmac_f32_e32 v244, v234, v245
	v_mul_f32_e32 v22, v22, v240
	v_mul_f32_e32 v23, v23, v244
	v_cvt_pk_bf16_f32 v16, v16, v17
	v_cvt_pk_bf16_f32 v17, v18, v19
	v_cvt_pk_bf16_f32 v18, v20, v21
	v_cvt_pk_bf16_f32 v19, v22, v23
	v_add_u32_e32 v236, 0x0, v230
	s_nop 0
	global_store_dwordx4 v236, v[16:19], s[22:23] offset:128
	v_lshlrev_b32_e32 v240, 16, v182
	v_and_b32_e32 v244, 0xffff0000, v182
	v_sub_f32_e32 v240, v240, v238
	v_sub_f32_e32 v244, v244, v238
	v_mul_f32_e32 v240, v240, v239
	v_mul_f32_e32 v244, v244, v239
	v_fma_f32 v240, v138, v240, v154
	v_fma_f32 v244, v139, v244, v155
	v_lshlrev_b32_e32 v241, 16, v190
	v_and_b32_e32 v245, 0xffff0000, v190
	v_lshlrev_b32_e32 v243, 16, v198
	v_and_b32_e32 v246, 0xffff0000, v198
	v_cndmask_b32_e32 v243, v243, v210, vcc
	v_cndmask_b32_e32 v246, v246, v211, vcc
	v_sub_f32_e32 v243, v243, v241
	v_sub_f32_e32 v246, v246, v245
	v_fmac_f32_e32 v241, v170, v243
	v_fmac_f32_e32 v245, v171, v246
	v_fmac_f32_e32 v240, v234, v241
	v_fmac_f32_e32 v244, v234, v245
	v_mul_f32_e32 v24, v24, v240
	v_mul_f32_e32 v25, v25, v244
	v_lshlrev_b32_e32 v240, 16, v183
	v_and_b32_e32 v244, 0xffff0000, v183
	v_sub_f32_e32 v240, v240, v238
	v_sub_f32_e32 v244, v244, v238
	v_mul_f32_e32 v240, v240, v239
	v_mul_f32_e32 v244, v244, v239
	v_fma_f32 v240, v140, v240, v156
	v_fma_f32 v244, v141, v244, v157
	v_lshlrev_b32_e32 v241, 16, v191
	v_and_b32_e32 v245, 0xffff0000, v191
	v_lshlrev_b32_e32 v243, 16, v199
	v_and_b32_e32 v246, 0xffff0000, v199
	v_cndmask_b32_e32 v243, v243, v212, vcc
	v_cndmask_b32_e32 v246, v246, v213, vcc
	v_sub_f32_e32 v243, v243, v241
	v_sub_f32_e32 v246, v246, v245
	v_fmac_f32_e32 v241, v172, v243
	v_fmac_f32_e32 v245, v173, v246
	v_fmac_f32_e32 v240, v234, v241
	v_fmac_f32_e32 v244, v234, v245
	v_mul_f32_e32 v26, v26, v240
	v_mul_f32_e32 v27, v27, v244
	v_lshlrev_b32_e32 v240, 16, v184
	v_and_b32_e32 v244, 0xffff0000, v184
	v_sub_f32_e32 v240, v240, v238
	v_sub_f32_e32 v244, v244, v238
	v_mul_f32_e32 v240, v240, v239
	v_mul_f32_e32 v244, v244, v239
	v_fma_f32 v240, v142, v240, v158
	v_fma_f32 v244, v143, v244, v159
	v_lshlrev_b32_e32 v241, 16, v192
	v_and_b32_e32 v245, 0xffff0000, v192
	v_lshlrev_b32_e32 v243, 16, v200
	v_and_b32_e32 v246, 0xffff0000, v200
	v_cndmask_b32_e32 v243, v243, v214, vcc
	v_cndmask_b32_e32 v246, v246, v215, vcc
	v_sub_f32_e32 v243, v243, v241
	v_sub_f32_e32 v246, v246, v245
	v_fmac_f32_e32 v241, v174, v243
	v_fmac_f32_e32 v245, v175, v246
	v_fmac_f32_e32 v240, v234, v241
	v_fmac_f32_e32 v244, v234, v245
	v_mul_f32_e32 v28, v28, v240
	v_mul_f32_e32 v29, v29, v244
	v_lshlrev_b32_e32 v240, 16, v185
	v_and_b32_e32 v244, 0xffff0000, v185
	v_sub_f32_e32 v240, v240, v238
	v_sub_f32_e32 v244, v244, v238
	v_mul_f32_e32 v240, v240, v239
	v_mul_f32_e32 v244, v244, v239
	v_fma_f32 v240, v144, v240, v160
	v_fma_f32 v244, v145, v244, v161
	v_lshlrev_b32_e32 v241, 16, v193
	v_and_b32_e32 v245, 0xffff0000, v193
	v_lshlrev_b32_e32 v243, 16, v201
	v_and_b32_e32 v246, 0xffff0000, v201
	v_cndmask_b32_e32 v243, v243, v216, vcc
	v_cndmask_b32_e32 v246, v246, v217, vcc
	v_sub_f32_e32 v243, v243, v241
	v_sub_f32_e32 v246, v246, v245
	v_fmac_f32_e32 v241, v176, v243
	v_fmac_f32_e32 v245, v177, v246
	v_fmac_f32_e32 v240, v234, v241
	v_fmac_f32_e32 v244, v234, v245
	v_mul_f32_e32 v30, v30, v240
	v_mul_f32_e32 v31, v31, v244
	v_cvt_pk_bf16_f32 v24, v24, v25
	v_cvt_pk_bf16_f32 v25, v26, v27
	v_cvt_pk_bf16_f32 v26, v28, v29
	v_cvt_pk_bf16_f32 v27, v30, v31
	v_add_u32_e32 v236, 0x0, v230
	s_nop 0
	global_store_dwordx4 v236, v[24:27], s[22:23] offset:192
	v_add_u32_e32 v236, 0x8000, v230
	v_add_u32_e32 v237, 0x16000, v231
	v_subrev_u32_e32 v240, 0x1600, v237
	global_load_dwordx4 v[178:181], v236, s[22:23] offset:128
	global_load_dwordx4 v[182:185], v236, s[22:23] offset:192
	global_load_dwordx4 v[186:189], v237, s[96:97] offset:128
	global_load_dwordx4 v[190:193], v237, s[96:97] offset:192
	global_load_dwordx4 v[194:197], v240, s[96:97] offset:128
	global_load_dwordx4 v[198:201], v240, s[96:97] offset:192
	v_add_u32_e32 v236, 0xc00, v232
	s_nop 0
	global_load_dword v234, v236, s[96:97] offset:16
	v_add_u32_e32 v237, 0xa000, v247
	global_load_dwordx4 v[202:205], v237, s[20:21] offset:256
	global_load_dwordx4 v[206:209], v237, s[20:21] offset:272
	global_load_dwordx4 v[210:213], v237, s[20:21] offset:384
	global_load_dwordx4 v[214:217], v237, s[20:21] offset:400
	s_waitcnt vmcnt(0)
; __device__ __forceinline__ float bf2f(u16 h) { return __uint_as_float(((unsigned)h) << 16); }
; template <int EPI> ...
;     ...
;         float o0 = bf2f(Y[(size_t)row * 1024 + 256 + ch0]);
;         float o1 = bf2f(Y[(size_t)row * 1024 + 256 + ch1]);
;         float mean = hsum32(o0 + o1) * (1.0f / 64.0f);
;         float d0 = o0 - mean, d1 = o1 - mean;
;         float var = hsum32(d0 * d0 + d1 * d1) * (1.0f / 64.0f);
;         float rstd = rsqrtf(var + 64e-5f);
;         float pv0 = bf2f(P[(size_t)row * 2816 + 256 + 1536 + ch0]);
;         float pv1 = bf2f(P[(size_t)row * 2816 + 256 + 1536 + ch1]);
;         float pp0 = prevP(p, P, row, 1536 + ch0), pp1 = prevP(p, P, row, 1536 + ch1);
;         float vv0 = pv0 + (pp0 - pv0) * mu0, vv1 = pv1 + (pp1 - pv1) * mu1;
;         float b = bs[((size_t)row * 12 + hh) * 4 + 2];
;         float y0 = (d0 * rstd * gg0 + gb0 + b * vv0) * acc0[i];
;         float y1 = (d1 * rstd * gg1 + gb1 + b * vv1) * acc1[i];
	v_lshlrev_b32_e32 v240, 16, v178
	v_and_b32_e32 v241, 0xffff0000, v178
	v_add_f32_e32 v244, v240, v241
	v_lshlrev_b32_e32 v240, 16, v179
	v_and_b32_e32 v241, 0xffff0000, v179
	v_add_f32_e32 v244, v244, v240
	v_add_f32_e32 v244, v244, v241
	v_lshlrev_b32_e32 v240, 16, v180
	v_and_b32_e32 v241, 0xffff0000, v180
	v_add_f32_e32 v244, v244, v240
	v_add_f32_e32 v244, v244, v241
	v_lshlrev_b32_e32 v240, 16, v181
	v_and_b32_e32 v241, 0xffff0000, v181
	v_add_f32_e32 v244, v244, v240
	v_add_f32_e32 v244, v244, v241
	v_lshlrev_b32_e32 v240, 16, v182
	v_and_b32_e32 v241, 0xffff0000, v182
	v_add_f32_e32 v244, v244, v240
	v_add_f32_e32 v244, v244, v241
	v_lshlrev_b32_e32 v240, 16, v183
	v_and_b32_e32 v241, 0xffff0000, v183
	v_add_f32_e32 v244, v244, v240
	v_add_f32_e32 v244, v244, v241
	v_lshlrev_b32_e32 v240, 16, v184
	v_and_b32_e32 v241, 0xffff0000, v184
	v_add_f32_e32 v244, v244, v240
	v_add_f32_e32 v244, v244, v241
	v_lshlrev_b32_e32 v240, 16, v185
	v_and_b32_e32 v241, 0xffff0000, v185
	v_add_f32_e32 v244, v244, v240
	v_add_f32_e32 v244, v244, v241
	v_mov_b32_e32 v240, v244
	s_nop 1
	v_permlane16_swap_b32_e32 v240, v244
	v_add_f32_e32 v244, v244, v240
	v_mov_b32_e32 v240, v244
	s_nop 1
	v_permlane32_swap_b32_e32 v240, v244
	v_add_f32_e32 v244, v244, v240
	v_mul_f32_e32 v238, 0x3c800000, v244
	v_lshlrev_b32_e32 v240, 16, v178
	v_and_b32_e32 v241, 0xffff0000, v178
	v_sub_f32_e32 v240, v240, v238
	v_sub_f32_e32 v241, v241, v238
	v_mul_f32_e32 v245, v240, v240
	v_fmac_f32_e32 v245, v241, v241
	v_lshlrev_b32_e32 v240, 16, v179
	v_and_b32_e32 v241, 0xffff0000, v179
	v_sub_f32_e32 v240, v240, v238
	v_sub_f32_e32 v241, v241, v238
	v_fmac_f32_e32 v245, v240, v240
	v_fmac_f32_e32 v245, v241, v241
	v_lshlrev_b32_e32 v240, 16, v180
	v_and_b32_e32 v241, 0xffff0000, v180
	v_sub_f32_e32 v240, v240, v238
	v_sub_f32_e32 v241, v241, v238
	v_fmac_f32_e32 v245, v240, v240
	v_fmac_f32_e32 v245, v241, v241
	v_lshlrev_b32_e32 v240, 16, v181
	v_and_b32_e32 v241, 0xffff0000, v181
	v_sub_f32_e32 v240, v240, v238
	v_sub_f32_e32 v241, v241, v238
	v_fmac_f32_e32 v245, v240, v240
	v_fmac_f32_e32 v245, v241, v241
	v_lshlrev_b32_e32 v240, 16, v182
	v_and_b32_e32 v241, 0xffff0000, v182
	v_sub_f32_e32 v240, v240, v238
	v_sub_f32_e32 v241, v241, v238
	v_fmac_f32_e32 v245, v240, v240
	v_fmac_f32_e32 v245, v241, v241
	v_lshlrev_b32_e32 v240, 16, v183
	v_and_b32_e32 v241, 0xffff0000, v183
	v_sub_f32_e32 v240, v240, v238
	v_sub_f32_e32 v241, v241, v238
	v_fmac_f32_e32 v245, v240, v240
	v_fmac_f32_e32 v245, v241, v241
	v_lshlrev_b32_e32 v240, 16, v184
	v_and_b32_e32 v241, 0xffff0000, v184
	v_sub_f32_e32 v240, v240, v238
	v_sub_f32_e32 v241, v241, v238
	v_fmac_f32_e32 v245, v240, v240
	v_fmac_f32_e32 v245, v241, v241
	v_lshlrev_b32_e32 v240, 16, v185
	v_and_b32_e32 v241, 0xffff0000, v185
	v_sub_f32_e32 v240, v240, v238
	v_sub_f32_e32 v241, v241, v238
	v_fmac_f32_e32 v245, v240, v240
	v_fmac_f32_e32 v245, v241, v241
	v_mov_b32_e32 v240, v245
	s_nop 1
	v_permlane16_swap_b32_e32 v240, v245
	v_add_f32_e32 v245, v245, v240
	v_mov_b32_e32 v240, v245
	s_nop 1
	v_permlane32_swap_b32_e32 v240, v245
	v_add_f32_e32 v245, v245, v240
	v_mov_b32_e32 v240, 0x3a27c5ac
	v_fmamk_f32 v245, v245, 0x3c800000, v240
	v_rsq_f32_e32 v239, v245
	v_and_b32_e32 v240, 3, v248
	v_cmp_eq_u32_e32 vcc, 0, v240
	s_nop 1
	v_lshlrev_b32_e32 v240, 16, v178
	v_and_b32_e32 v244, 0xffff0000, v178
	v_sub_f32_e32 v240, v240, v238
	v_sub_f32_e32 v244, v244, v238
	v_mul_f32_e32 v240, v240, v239
	v_mul_f32_e32 v244, v244, v239
	v_fma_f32 v240, v130, v240, v146
	v_fma_f32 v244, v131, v244, v147
	v_lshlrev_b32_e32 v241, 16, v186
	v_and_b32_e32 v245, 0xffff0000, v186
	v_lshlrev_b32_e32 v243, 16, v194
	v_and_b32_e32 v246, 0xffff0000, v194
	v_cndmask_b32_e32 v243, v243, v202, vcc
	v_cndmask_b32_e32 v246, v246, v203, vcc
	v_sub_f32_e32 v243, v243, v241
	v_sub_f32_e32 v246, v246, v245
	v_fmac_f32_e32 v241, v162, v243
	v_fmac_f32_e32 v245, v163, v246
	v_fmac_f32_e32 v240, v234, v241
	v_fmac_f32_e32 v244, v234, v245
	v_mul_f32_e32 v48, v48, v240
	v_mul_f32_e32 v49, v49, v244
	v_lshlrev_b32_e32 v240, 16, v179
	v_and_b32_e32 v244, 0xffff0000, v179
	v_sub_f32_e32 v240, v240, v238
	v_sub_f32_e32 v244, v244, v238
	v_mul_f32_e32 v240, v240, v239
	v_mul_f32_e32 v244, v244, v239
	v_fma_f32 v240, v132, v240, v148
	v_fma_f32 v244, v133, v244, v149
	v_lshlrev_b32_e32 v241, 16, v187
	v_and_b32_e32 v245, 0xffff0000, v187
	v_lshlrev_b32_e32 v243, 16, v195
	v_and_b32_e32 v246, 0xffff0000, v195
	v_cndmask_b32_e32 v243, v243, v204, vcc
	v_cndmask_b32_e32 v246, v246, v205, vcc
	v_sub_f32_e32 v243, v243, v241
	v_sub_f32_e32 v246, v246, v245
	v_fmac_f32_e32 v241, v164, v243
	v_fmac_f32_e32 v245, v165, v246
	v_fmac_f32_e32 v240, v234, v241
	v_fmac_f32_e32 v244, v234, v245
	v_mul_f32_e32 v50, v50, v240
	v_mul_f32_e32 v51, v51, v244
	v_lshlrev_b32_e32 v240, 16, v180
	v_and_b32_e32 v244, 0xffff0000, v180
	v_sub_f32_e32 v240, v240, v238
	v_sub_f32_e32 v244, v244, v238
	v_mul_f32_e32 v240, v240, v239
	v_mul_f32_e32 v244, v244, v239
	v_fma_f32 v240, v134, v240, v150
	v_fma_f32 v244, v135, v244, v151
	v_lshlrev_b32_e32 v241, 16, v188
	v_and_b32_e32 v245, 0xffff0000, v188
	v_lshlrev_b32_e32 v243, 16, v196
	v_and_b32_e32 v246, 0xffff0000, v196
	v_cndmask_b32_e32 v243, v243, v206, vcc
	v_cndmask_b32_e32 v246, v246, v207, vcc
	v_sub_f32_e32 v243, v243, v241
	v_sub_f32_e32 v246, v246, v245
	v_fmac_f32_e32 v241, v166, v243
	v_fmac_f32_e32 v245, v167, v246
	v_fmac_f32_e32 v240, v234, v241
	v_fmac_f32_e32 v244, v234, v245
	v_mul_f32_e32 v52, v52, v240
	v_mul_f32_e32 v53, v53, v244
	v_lshlrev_b32_e32 v240, 16, v181
	v_and_b32_e32 v244, 0xffff0000, v181
	v_sub_f32_e32 v240, v240, v238
; __device__ __forceinline__ float bf2f(u16 h) { return __uint_as_float(((unsigned)h) << 16); }
; template <int EPI> ...
;     ...
;         float pv0 = bf2f(P[(size_t)row * 2816 + 256 + 1536 + ch0]);
;         float pv1 = bf2f(P[(size_t)row * 2816 + 256 + 1536 + ch1]);
;         float pp0 = prevP(p, P, row, 1536 + ch0), pp1 = prevP(p, P, row, 1536 + ch1);
;         float vv0 = pv0 + (pp0 - pv0) * mu0, vv1 = pv1 + (pp1 - pv1) * mu1;
;         float b = bs[((size_t)row * 12 + hh) * 4 + 2];
;         float y0 = (d0 * rstd * gg0 + gb0 + b * vv0) * acc0[i];
;         float y1 = (d1 * rstd * gg1 + gb1 + b * vv1) * acc1[i];
;         Y[(size_t)row * 1024 + 256 + ch0] = f2bf(y0);
;         Y[(size_t)row * 1024 + 256 + ch1] = f2bf(y1);
;       }
	v_sub_f32_e32 v244, v244, v238
	v_mul_f32_e32 v240, v240, v239
	v_mul_f32_e32 v244, v244, v239
	v_fma_f32 v240, v136, v240, v152
	v_fma_f32 v244, v137, v244, v153
	v_lshlrev_b32_e32 v241, 16, v189
	v_and_b32_e32 v245, 0xffff0000, v189
	v_lshlrev_b32_e32 v243, 16, v197
	v_and_b32_e32 v246, 0xffff0000, v197
	v_cndmask_b32_e32 v243, v243, v208, vcc
	v_cndmask_b32_e32 v246, v246, v209, vcc
	v_sub_f32_e32 v243, v243, v241
	v_sub_f32_e32 v246, v246, v245
	v_fmac_f32_e32 v241, v168, v243
	v_fmac_f32_e32 v245, v169, v246
	v_fmac_f32_e32 v240, v234, v241
	v_fmac_f32_e32 v244, v234, v245
	v_mul_f32_e32 v54, v54, v240
	v_mul_f32_e32 v55, v55, v244
	v_cvt_pk_bf16_f32 v48, v48, v49
	v_cvt_pk_bf16_f32 v49, v50, v51
	v_cvt_pk_bf16_f32 v50, v52, v53
	v_cvt_pk_bf16_f32 v51, v54, v55
	v_add_u32_e32 v236, 0x8000, v230
	s_nop 0
	global_store_dwordx4 v236, v[48:51], s[22:23] offset:128
	v_lshlrev_b32_e32 v240, 16, v182
	v_and_b32_e32 v244, 0xffff0000, v182
	v_sub_f32_e32 v240, v240, v238
	v_sub_f32_e32 v244, v244, v238
	v_mul_f32_e32 v240, v240, v239
	v_mul_f32_e32 v244, v244, v239
	v_fma_f32 v240, v138, v240, v154
	v_fma_f32 v244, v139, v244, v155
	v_lshlrev_b32_e32 v241, 16, v190
	v_and_b32_e32 v245, 0xffff0000, v190
	v_lshlrev_b32_e32 v243, 16, v198
	v_and_b32_e32 v246, 0xffff0000, v198
	v_cndmask_b32_e32 v243, v243, v210, vcc
	v_cndmask_b32_e32 v246, v246, v211, vcc
	v_sub_f32_e32 v243, v243, v241
	v_sub_f32_e32 v246, v246, v245
	v_fmac_f32_e32 v241, v170, v243
	v_fmac_f32_e32 v245, v171, v246
	v_fmac_f32_e32 v240, v234, v241
	v_fmac_f32_e32 v244, v234, v245
	v_mul_f32_e32 v56, v56, v240
	v_mul_f32_e32 v57, v57, v244
	v_lshlrev_b32_e32 v240, 16, v183
	v_and_b32_e32 v244, 0xffff0000, v183
	v_sub_f32_e32 v240, v240, v238
	v_sub_f32_e32 v244, v244, v238
	v_mul_f32_e32 v240, v240, v239
	v_mul_f32_e32 v244, v244, v239
	v_fma_f32 v240, v140, v240, v156
	v_fma_f32 v244, v141, v244, v157
	v_lshlrev_b32_e32 v241, 16, v191
	v_and_b32_e32 v245, 0xffff0000, v191
	v_lshlrev_b32_e32 v243, 16, v199
	v_and_b32_e32 v246, 0xffff0000, v199
	v_cndmask_b32_e32 v243, v243, v212, vcc
	v_cndmask_b32_e32 v246, v246, v213, vcc
	v_sub_f32_e32 v243, v243, v241
	v_sub_f32_e32 v246, v246, v245
	v_fmac_f32_e32 v241, v172, v243
	v_fmac_f32_e32 v245, v173, v246
	v_fmac_f32_e32 v240, v234, v241
	v_fmac_f32_e32 v244, v234, v245
	v_mul_f32_e32 v58, v58, v240
	v_mul_f32_e32 v59, v59, v244
	v_lshlrev_b32_e32 v240, 16, v184
	v_and_b32_e32 v244, 0xffff0000, v184
	v_sub_f32_e32 v240, v240, v238
	v_sub_f32_e32 v244, v244, v238
	v_mul_f32_e32 v240, v240, v239
	v_mul_f32_e32 v244, v244, v239
	v_fma_f32 v240, v142, v240, v158
	v_fma_f32 v244, v143, v244, v159
	v_lshlrev_b32_e32 v241, 16, v192
	v_and_b32_e32 v245, 0xffff0000, v192
	v_lshlrev_b32_e32 v243, 16, v200
	v_and_b32_e32 v246, 0xffff0000, v200
	v_cndmask_b32_e32 v243, v243, v214, vcc
	v_cndmask_b32_e32 v246, v246, v215, vcc
	v_sub_f32_e32 v243, v243, v241
	v_sub_f32_e32 v246, v246, v245
	v_fmac_f32_e32 v241, v174, v243
	v_fmac_f32_e32 v245, v175, v246
	v_fmac_f32_e32 v240, v234, v241
	v_fmac_f32_e32 v244, v234, v245
	v_mul_f32_e32 v60, v60, v240
	v_mul_f32_e32 v61, v61, v244
	v_lshlrev_b32_e32 v240, 16, v185
	v_and_b32_e32 v244, 0xffff0000, v185
	v_sub_f32_e32 v240, v240, v238
	v_sub_f32_e32 v244, v244, v238
	v_mul_f32_e32 v240, v240, v239
	v_mul_f32_e32 v244, v244, v239
	v_fma_f32 v240, v144, v240, v160
	v_fma_f32 v244, v145, v244, v161
	v_lshlrev_b32_e32 v241, 16, v193
	v_and_b32_e32 v245, 0xffff0000, v193
	v_lshlrev_b32_e32 v243, 16, v201
	v_and_b32_e32 v246, 0xffff0000, v201
	v_cndmask_b32_e32 v243, v243, v216, vcc
	v_cndmask_b32_e32 v246, v246, v217, vcc
	v_sub_f32_e32 v243, v243, v241
	v_sub_f32_e32 v246, v246, v245
	v_fmac_f32_e32 v241, v176, v243
	v_fmac_f32_e32 v245, v177, v246
	v_fmac_f32_e32 v240, v234, v241
	v_fmac_f32_e32 v244, v234, v245
	v_mul_f32_e32 v62, v62, v240
	v_mul_f32_e32 v63, v63, v244
	v_cvt_pk_bf16_f32 v56, v56, v57
	v_cvt_pk_bf16_f32 v57, v58, v59
	v_cvt_pk_bf16_f32 v58, v60, v61
	v_cvt_pk_bf16_f32 v59, v62, v63
	v_add_u32_e32 v236, 0x8000, v230
	s_nop 0
	global_store_dwordx4 v236, v[56:59], s[22:23] offset:192
	v_add_u32_e32 v236, 0x10000, v230
	v_add_u32_e32 v237, 0x2c000, v231
	v_subrev_u32_e32 v240, 0x1600, v237
	global_load_dwordx4 v[178:181], v236, s[22:23] offset:128
	global_load_dwordx4 v[182:185], v236, s[22:23] offset:192
	global_load_dwordx4 v[186:189], v237, s[96:97] offset:128
	global_load_dwordx4 v[190:193], v237, s[96:97] offset:192
	global_load_dwordx4 v[194:197], v240, s[96:97] offset:128
	global_load_dwordx4 v[198:201], v240, s[96:97] offset:192
	v_add_u32_e32 v236, 0x1800, v232
	s_nop 0
	global_load_dword v234, v236, s[96:97] offset:16
	v_add_u32_e32 v237, 0x14000, v247
	global_load_dwordx4 v[202:205], v237, s[20:21] offset:256
	global_load_dwordx4 v[206:209], v237, s[20:21] offset:272
	global_load_dwordx4 v[210:213], v237, s[20:21] offset:384
	global_load_dwordx4 v[214:217], v237, s[20:21] offset:400
	s_waitcnt vmcnt(0)
; __device__ __forceinline__ float bf2f(u16 h) { return __uint_as_float(((unsigned)h) << 16); }
; template <int EPI> ...
;     ...
;         float o0 = bf2f(Y[(size_t)row * 1024 + 256 + ch0]);
;         float o1 = bf2f(Y[(size_t)row * 1024 + 256 + ch1]);
;         float mean = hsum32(o0 + o1) * (1.0f / 64.0f);
;         float d0 = o0 - mean, d1 = o1 - mean;
;         float var = hsum32(d0 * d0 + d1 * d1) * (1.0f / 64.0f);
;         float rstd = rsqrtf(var + 64e-5f);
;         float pv0 = bf2f(P[(size_t)row * 2816 + 256 + 1536 + ch0]);
;         float pv1 = bf2f(P[(size_t)row * 2816 + 256 + 1536 + ch1]);
;         float pp0 = prevP(p, P, row, 1536 + ch0), pp1 = prevP(p, P, row, 1536 + ch1);
;         float vv0 = pv0 + (pp0 - pv0) * mu0, vv1 = pv1 + (pp1 - pv1) * mu1;
;         float b = bs[((size_t)row * 12 + hh) * 4 + 2];
;         float y0 = (d0 * rstd * gg0 + gb0 + b * vv0) * acc0[i];
;         float y1 = (d1 * rstd * gg1 + gb1 + b * vv1) * acc1[i];
	v_lshlrev_b32_e32 v240, 16, v178
	v_and_b32_e32 v241, 0xffff0000, v178
	v_add_f32_e32 v244, v240, v241
	v_lshlrev_b32_e32 v240, 16, v179
	v_and_b32_e32 v241, 0xffff0000, v179
	v_add_f32_e32 v244, v244, v240
	v_add_f32_e32 v244, v244, v241
	v_lshlrev_b32_e32 v240, 16, v180
	v_and_b32_e32 v241, 0xffff0000, v180
	v_add_f32_e32 v244, v244, v240
	v_add_f32_e32 v244, v244, v241
	v_lshlrev_b32_e32 v240, 16, v181
	v_and_b32_e32 v241, 0xffff0000, v181
	v_add_f32_e32 v244, v244, v240
	v_add_f32_e32 v244, v244, v241
	v_lshlrev_b32_e32 v240, 16, v182
	v_and_b32_e32 v241, 0xffff0000, v182
	v_add_f32_e32 v244, v244, v240
	v_add_f32_e32 v244, v244, v241
	v_lshlrev_b32_e32 v240, 16, v183
	v_and_b32_e32 v241, 0xffff0000, v183
	v_add_f32_e32 v244, v244, v240
	v_add_f32_e32 v244, v244, v241
	v_lshlrev_b32_e32 v240, 16, v184
	v_and_b32_e32 v241, 0xffff0000, v184
	v_add_f32_e32 v244, v244, v240
	v_add_f32_e32 v244, v244, v241
	v_lshlrev_b32_e32 v240, 16, v185
	v_and_b32_e32 v241, 0xffff0000, v185
	v_add_f32_e32 v244, v244, v240
	v_add_f32_e32 v244, v244, v241
	v_mov_b32_e32 v240, v244
	s_nop 1
	v_permlane16_swap_b32_e32 v240, v244
	v_add_f32_e32 v244, v244, v240
	v_mov_b32_e32 v240, v244
	s_nop 1
	v_permlane32_swap_b32_e32 v240, v244
	v_add_f32_e32 v244, v244, v240
	v_mul_f32_e32 v238, 0x3c800000, v244
	v_lshlrev_b32_e32 v240, 16, v178
	v_and_b32_e32 v241, 0xffff0000, v178
	v_sub_f32_e32 v240, v240, v238
	v_sub_f32_e32 v241, v241, v238
	v_mul_f32_e32 v245, v240, v240
	v_fmac_f32_e32 v245, v241, v241
	v_lshlrev_b32_e32 v240, 16, v179
	v_and_b32_e32 v241, 0xffff0000, v179
	v_sub_f32_e32 v240, v240, v238
	v_sub_f32_e32 v241, v241, v238
	v_fmac_f32_e32 v245, v240, v240
	v_fmac_f32_e32 v245, v241, v241
	v_lshlrev_b32_e32 v240, 16, v180
	v_and_b32_e32 v241, 0xffff0000, v180
	v_sub_f32_e32 v240, v240, v238
	v_sub_f32_e32 v241, v241, v238
	v_fmac_f32_e32 v245, v240, v240
	v_fmac_f32_e32 v245, v241, v241
	v_lshlrev_b32_e32 v240, 16, v181
	v_and_b32_e32 v241, 0xffff0000, v181
	v_sub_f32_e32 v240, v240, v238
	v_sub_f32_e32 v241, v241, v238
	v_fmac_f32_e32 v245, v240, v240
	v_fmac_f32_e32 v245, v241, v241
	v_lshlrev_b32_e32 v240, 16, v182
	v_and_b32_e32 v241, 0xffff0000, v182
	v_sub_f32_e32 v240, v240, v238
	v_sub_f32_e32 v241, v241, v238
	v_fmac_f32_e32 v245, v240, v240
	v_fmac_f32_e32 v245, v241, v241
	v_lshlrev_b32_e32 v240, 16, v183
	v_and_b32_e32 v241, 0xffff0000, v183
	v_sub_f32_e32 v240, v240, v238
	v_sub_f32_e32 v241, v241, v238
	v_fmac_f32_e32 v245, v240, v240
	v_fmac_f32_e32 v245, v241, v241
	v_lshlrev_b32_e32 v240, 16, v184
	v_and_b32_e32 v241, 0xffff0000, v184
	v_sub_f32_e32 v240, v240, v238
	v_sub_f32_e32 v241, v241, v238
	v_fmac_f32_e32 v245, v240, v240
	v_fmac_f32_e32 v245, v241, v241
	v_lshlrev_b32_e32 v240, 16, v185
	v_and_b32_e32 v241, 0xffff0000, v185
	v_sub_f32_e32 v240, v240, v238
	v_sub_f32_e32 v241, v241, v238
	v_fmac_f32_e32 v245, v240, v240
	v_fmac_f32_e32 v245, v241, v241
	v_mov_b32_e32 v240, v245
	s_nop 1
	v_permlane16_swap_b32_e32 v240, v245
	v_add_f32_e32 v245, v245, v240
	v_mov_b32_e32 v240, v245
	s_nop 1
	v_permlane32_swap_b32_e32 v240, v245
	v_add_f32_e32 v245, v245, v240
	v_mov_b32_e32 v240, 0x3a27c5ac
	v_fmamk_f32 v245, v245, 0x3c800000, v240
	v_rsq_f32_e32 v239, v245
	v_and_b32_e32 v240, 3, v248
	v_cmp_eq_u32_e32 vcc, 0, v240
	s_nop 1
	v_lshlrev_b32_e32 v240, 16, v178
	v_and_b32_e32 v244, 0xffff0000, v178
	v_sub_f32_e32 v240, v240, v238
	v_sub_f32_e32 v244, v244, v238
	v_mul_f32_e32 v240, v240, v239
	v_mul_f32_e32 v244, v244, v239
	v_fma_f32 v240, v130, v240, v146
	v_fma_f32 v244, v131, v244, v147
	v_lshlrev_b32_e32 v241, 16, v186
	v_and_b32_e32 v245, 0xffff0000, v186
	v_lshlrev_b32_e32 v243, 16, v194
	v_and_b32_e32 v246, 0xffff0000, v194
	v_cndmask_b32_e32 v243, v243, v202, vcc
	v_cndmask_b32_e32 v246, v246, v203, vcc
	v_sub_f32_e32 v243, v243, v241
	v_sub_f32_e32 v246, v246, v245
	v_fmac_f32_e32 v241, v162, v243
	v_fmac_f32_e32 v245, v163, v246
	v_fmac_f32_e32 v240, v234, v241
	v_fmac_f32_e32 v244, v234, v245
	v_mul_f32_e32 v80, v80, v240
	v_mul_f32_e32 v81, v81, v244
	v_lshlrev_b32_e32 v240, 16, v179
	v_and_b32_e32 v244, 0xffff0000, v179
	v_sub_f32_e32 v240, v240, v238
	v_sub_f32_e32 v244, v244, v238
	v_mul_f32_e32 v240, v240, v239
	v_mul_f32_e32 v244, v244, v239
	v_fma_f32 v240, v132, v240, v148
	v_fma_f32 v244, v133, v244, v149
	v_lshlrev_b32_e32 v241, 16, v187
	v_and_b32_e32 v245, 0xffff0000, v187
	v_lshlrev_b32_e32 v243, 16, v195
	v_and_b32_e32 v246, 0xffff0000, v195
	v_cndmask_b32_e32 v243, v243, v204, vcc
	v_cndmask_b32_e32 v246, v246, v205, vcc
	v_sub_f32_e32 v243, v243, v241
	v_sub_f32_e32 v246, v246, v245
	v_fmac_f32_e32 v241, v164, v243
	v_fmac_f32_e32 v245, v165, v246
	v_fmac_f32_e32 v240, v234, v241
	v_fmac_f32_e32 v244, v234, v245
	v_mul_f32_e32 v82, v82, v240
	v_mul_f32_e32 v83, v83, v244
	v_lshlrev_b32_e32 v240, 16, v180
	v_and_b32_e32 v244, 0xffff0000, v180
	v_sub_f32_e32 v240, v240, v238
	v_sub_f32_e32 v244, v244, v238
	v_mul_f32_e32 v240, v240, v239
	v_mul_f32_e32 v244, v244, v239
	v_fma_f32 v240, v134, v240, v150
	v_fma_f32 v244, v135, v244, v151
	v_lshlrev_b32_e32 v241, 16, v188
	v_and_b32_e32 v245, 0xffff0000, v188
	v_lshlrev_b32_e32 v243, 16, v196
	v_and_b32_e32 v246, 0xffff0000, v196
	v_cndmask_b32_e32 v243, v243, v206, vcc
	v_cndmask_b32_e32 v246, v246, v207, vcc
	v_sub_f32_e32 v243, v243, v241
	v_sub_f32_e32 v246, v246, v245
	v_fmac_f32_e32 v241, v166, v243
	v_fmac_f32_e32 v245, v167, v246
	v_fmac_f32_e32 v240, v234, v241
	v_fmac_f32_e32 v244, v234, v245
	v_mul_f32_e32 v84, v84, v240
	v_mul_f32_e32 v85, v85, v244
	v_lshlrev_b32_e32 v240, 16, v181
	v_and_b32_e32 v244, 0xffff0000, v181
	v_sub_f32_e32 v240, v240, v238
; __device__ __forceinline__ float bf2f(u16 h) { return __uint_as_float(((unsigned)h) << 16); }
; template <int EPI> ...
;     ...
;         float pv0 = bf2f(P[(size_t)row * 2816 + 256 + 1536 + ch0]);
;         float pv1 = bf2f(P[(size_t)row * 2816 + 256 + 1536 + ch1]);
;         float pp0 = prevP(p, P, row, 1536 + ch0), pp1 = prevP(p, P, row, 1536 + ch1);
;         float vv0 = pv0 + (pp0 - pv0) * mu0, vv1 = pv1 + (pp1 - pv1) * mu1;
;         float b = bs[((size_t)row * 12 + hh) * 4 + 2];
;         float y0 = (d0 * rstd * gg0 + gb0 + b * vv0) * acc0[i];
;         float y1 = (d1 * rstd * gg1 + gb1 + b * vv1) * acc1[i];
;         Y[(size_t)row * 1024 + 256 + ch0] = f2bf(y0);
;         Y[(size_t)row * 1024 + 256 + ch1] = f2bf(y1);
;       }
	v_sub_f32_e32 v244, v244, v238
	v_mul_f32_e32 v240, v240, v239
	v_mul_f32_e32 v244, v244, v239
	v_fma_f32 v240, v136, v240, v152
	v_fma_f32 v244, v137, v244, v153
	v_lshlrev_b32_e32 v241, 16, v189
	v_and_b32_e32 v245, 0xffff0000, v189
	v_lshlrev_b32_e32 v243, 16, v197
	v_and_b32_e32 v246, 0xffff0000, v197
	v_cndmask_b32_e32 v243, v243, v208, vcc
	v_cndmask_b32_e32 v246, v246, v209, vcc
	v_sub_f32_e32 v243, v243, v241
	v_sub_f32_e32 v246, v246, v245
	v_fmac_f32_e32 v241, v168, v243
	v_fmac_f32_e32 v245, v169, v246
	v_fmac_f32_e32 v240, v234, v241
	v_fmac_f32_e32 v244, v234, v245
	v_mul_f32_e32 v86, v86, v240
	v_mul_f32_e32 v87, v87, v244
	v_cvt_pk_bf16_f32 v80, v80, v81
	v_cvt_pk_bf16_f32 v81, v82, v83
	v_cvt_pk_bf16_f32 v82, v84, v85
	v_cvt_pk_bf16_f32 v83, v86, v87
	v_add_u32_e32 v236, 0x10000, v230
	s_nop 0
	global_store_dwordx4 v236, v[80:83], s[22:23] offset:128
	v_lshlrev_b32_e32 v240, 16, v182
	v_and_b32_e32 v244, 0xffff0000, v182
	v_sub_f32_e32 v240, v240, v238
	v_sub_f32_e32 v244, v244, v238
	v_mul_f32_e32 v240, v240, v239
	v_mul_f32_e32 v244, v244, v239
	v_fma_f32 v240, v138, v240, v154
	v_fma_f32 v244, v139, v244, v155
	v_lshlrev_b32_e32 v241, 16, v190
	v_and_b32_e32 v245, 0xffff0000, v190
	v_lshlrev_b32_e32 v243, 16, v198
	v_and_b32_e32 v246, 0xffff0000, v198
	v_cndmask_b32_e32 v243, v243, v210, vcc
	v_cndmask_b32_e32 v246, v246, v211, vcc
	v_sub_f32_e32 v243, v243, v241
	v_sub_f32_e32 v246, v246, v245
	v_fmac_f32_e32 v241, v170, v243
	v_fmac_f32_e32 v245, v171, v246
	v_fmac_f32_e32 v240, v234, v241
	v_fmac_f32_e32 v244, v234, v245
	v_mul_f32_e32 v88, v88, v240
	v_mul_f32_e32 v89, v89, v244
	v_lshlrev_b32_e32 v240, 16, v183
	v_and_b32_e32 v244, 0xffff0000, v183
	v_sub_f32_e32 v240, v240, v238
	v_sub_f32_e32 v244, v244, v238
	v_mul_f32_e32 v240, v240, v239
	v_mul_f32_e32 v244, v244, v239
	v_fma_f32 v240, v140, v240, v156
	v_fma_f32 v244, v141, v244, v157
	v_lshlrev_b32_e32 v241, 16, v191
	v_and_b32_e32 v245, 0xffff0000, v191
	v_lshlrev_b32_e32 v243, 16, v199
	v_and_b32_e32 v246, 0xffff0000, v199
	v_cndmask_b32_e32 v243, v243, v212, vcc
	v_cndmask_b32_e32 v246, v246, v213, vcc
	v_sub_f32_e32 v243, v243, v241
	v_sub_f32_e32 v246, v246, v245
	v_fmac_f32_e32 v241, v172, v243
	v_fmac_f32_e32 v245, v173, v246
	v_fmac_f32_e32 v240, v234, v241
	v_fmac_f32_e32 v244, v234, v245
	v_mul_f32_e32 v90, v90, v240
	v_mul_f32_e32 v91, v91, v244
	v_lshlrev_b32_e32 v240, 16, v184
	v_and_b32_e32 v244, 0xffff0000, v184
	v_sub_f32_e32 v240, v240, v238
	v_sub_f32_e32 v244, v244, v238
	v_mul_f32_e32 v240, v240, v239
	v_mul_f32_e32 v244, v244, v239
	v_fma_f32 v240, v142, v240, v158
	v_fma_f32 v244, v143, v244, v159
	v_lshlrev_b32_e32 v241, 16, v192
	v_and_b32_e32 v245, 0xffff0000, v192
	v_lshlrev_b32_e32 v243, 16, v200
	v_and_b32_e32 v246, 0xffff0000, v200
	v_cndmask_b32_e32 v243, v243, v214, vcc
	v_cndmask_b32_e32 v246, v246, v215, vcc
	v_sub_f32_e32 v243, v243, v241
	v_sub_f32_e32 v246, v246, v245
	v_fmac_f32_e32 v241, v174, v243
	v_fmac_f32_e32 v245, v175, v246
	v_fmac_f32_e32 v240, v234, v241
	v_fmac_f32_e32 v244, v234, v245
	v_mul_f32_e32 v92, v92, v240
	v_mul_f32_e32 v93, v93, v244
	v_lshlrev_b32_e32 v240, 16, v185
	v_and_b32_e32 v244, 0xffff0000, v185
	v_sub_f32_e32 v240, v240, v238
	v_sub_f32_e32 v244, v244, v238
	v_mul_f32_e32 v240, v240, v239
	v_mul_f32_e32 v244, v244, v239
	v_fma_f32 v240, v144, v240, v160
	v_fma_f32 v244, v145, v244, v161
	v_lshlrev_b32_e32 v241, 16, v193
	v_and_b32_e32 v245, 0xffff0000, v193
	v_lshlrev_b32_e32 v243, 16, v201
	v_and_b32_e32 v246, 0xffff0000, v201
	v_cndmask_b32_e32 v243, v243, v216, vcc
	v_cndmask_b32_e32 v246, v246, v217, vcc
	v_sub_f32_e32 v243, v243, v241
	v_sub_f32_e32 v246, v246, v245
	v_fmac_f32_e32 v241, v176, v243
	v_fmac_f32_e32 v245, v177, v246
	v_fmac_f32_e32 v240, v234, v241
	v_fmac_f32_e32 v244, v234, v245
	v_mul_f32_e32 v94, v94, v240
	v_mul_f32_e32 v95, v95, v244
	v_cvt_pk_bf16_f32 v88, v88, v89
	v_cvt_pk_bf16_f32 v89, v90, v91
	v_cvt_pk_bf16_f32 v90, v92, v93
	v_cvt_pk_bf16_f32 v91, v94, v95
	v_add_u32_e32 v236, 0x10000, v230
	s_nop 0
	global_store_dwordx4 v236, v[88:91], s[22:23] offset:192
	v_add_u32_e32 v236, 0x18000, v230
	v_add_u32_e32 v237, 0x42000, v231
	v_subrev_u32_e32 v240, 0x1600, v237
	global_load_dwordx4 v[178:181], v236, s[22:23] offset:128
	global_load_dwordx4 v[182:185], v236, s[22:23] offset:192
	global_load_dwordx4 v[186:189], v237, s[96:97] offset:128
	global_load_dwordx4 v[190:193], v237, s[96:97] offset:192
	global_load_dwordx4 v[194:197], v240, s[96:97] offset:128
	global_load_dwordx4 v[198:201], v240, s[96:97] offset:192
	v_add_u32_e32 v236, 0x2400, v232
	s_nop 0
	global_load_dword v234, v236, s[96:97] offset:16
	v_add_u32_e32 v237, 0x1e000, v247
	global_load_dwordx4 v[202:205], v237, s[20:21] offset:256
	global_load_dwordx4 v[206:209], v237, s[20:21] offset:272
	global_load_dwordx4 v[210:213], v237, s[20:21] offset:384
	global_load_dwordx4 v[214:217], v237, s[20:21] offset:400
	s_waitcnt vmcnt(0)
; __device__ __forceinline__ float bf2f(u16 h) { return __uint_as_float(((unsigned)h) << 16); }
; template <int EPI> ...
;     ...
;         float o0 = bf2f(Y[(size_t)row * 1024 + 256 + ch0]);
;         float o1 = bf2f(Y[(size_t)row * 1024 + 256 + ch1]);
;         float mean = hsum32(o0 + o1) * (1.0f / 64.0f);
;         float d0 = o0 - mean, d1 = o1 - mean;
;         float var = hsum32(d0 * d0 + d1 * d1) * (1.0f / 64.0f);
;         float rstd = rsqrtf(var + 64e-5f);
;         float pv0 = bf2f(P[(size_t)row * 2816 + 256 + 1536 + ch0]);
;         float pv1 = bf2f(P[(size_t)row * 2816 + 256 + 1536 + ch1]);
;         float pp0 = prevP(p, P, row, 1536 + ch0), pp1 = prevP(p, P, row, 1536 + ch1);
;         float vv0 = pv0 + (pp0 - pv0) * mu0, vv1 = pv1 + (pp1 - pv1) * mu1;
;         float b = bs[((size_t)row * 12 + hh) * 4 + 2];
;         float y0 = (d0 * rstd * gg0 + gb0 + b * vv0) * acc0[i];
;         float y1 = (d1 * rstd * gg1 + gb1 + b * vv1) * acc1[i];
	v_lshlrev_b32_e32 v240, 16, v178
	v_and_b32_e32 v241, 0xffff0000, v178
	v_add_f32_e32 v244, v240, v241
	v_lshlrev_b32_e32 v240, 16, v179
	v_and_b32_e32 v241, 0xffff0000, v179
	v_add_f32_e32 v244, v244, v240
	v_add_f32_e32 v244, v244, v241
	v_lshlrev_b32_e32 v240, 16, v180
	v_and_b32_e32 v241, 0xffff0000, v180
	v_add_f32_e32 v244, v244, v240
	v_add_f32_e32 v244, v244, v241
	v_lshlrev_b32_e32 v240, 16, v181
	v_and_b32_e32 v241, 0xffff0000, v181
	v_add_f32_e32 v244, v244, v240
	v_add_f32_e32 v244, v244, v241
	v_lshlrev_b32_e32 v240, 16, v182
	v_and_b32_e32 v241, 0xffff0000, v182
	v_add_f32_e32 v244, v244, v240
	v_add_f32_e32 v244, v244, v241
	v_lshlrev_b32_e32 v240, 16, v183
	v_and_b32_e32 v241, 0xffff0000, v183
	v_add_f32_e32 v244, v244, v240
	v_add_f32_e32 v244, v244, v241
	v_lshlrev_b32_e32 v240, 16, v184
	v_and_b32_e32 v241, 0xffff0000, v184
	v_add_f32_e32 v244, v244, v240
	v_add_f32_e32 v244, v244, v241
	v_lshlrev_b32_e32 v240, 16, v185
	v_and_b32_e32 v241, 0xffff0000, v185
	v_add_f32_e32 v244, v244, v240
	v_add_f32_e32 v244, v244, v241
	v_mov_b32_e32 v240, v244
	s_nop 1
	v_permlane16_swap_b32_e32 v240, v244
	v_add_f32_e32 v244, v244, v240
	v_mov_b32_e32 v240, v244
	s_nop 1
	v_permlane32_swap_b32_e32 v240, v244
	v_add_f32_e32 v244, v244, v240
	v_mul_f32_e32 v238, 0x3c800000, v244
	v_lshlrev_b32_e32 v240, 16, v178
	v_and_b32_e32 v241, 0xffff0000, v178
	v_sub_f32_e32 v240, v240, v238
	v_sub_f32_e32 v241, v241, v238
	v_mul_f32_e32 v245, v240, v240
	v_fmac_f32_e32 v245, v241, v241
	v_lshlrev_b32_e32 v240, 16, v179
	v_and_b32_e32 v241, 0xffff0000, v179
	v_sub_f32_e32 v240, v240, v238
	v_sub_f32_e32 v241, v241, v238
	v_fmac_f32_e32 v245, v240, v240
	v_fmac_f32_e32 v245, v241, v241
	v_lshlrev_b32_e32 v240, 16, v180
	v_and_b32_e32 v241, 0xffff0000, v180
	v_sub_f32_e32 v240, v240, v238
	v_sub_f32_e32 v241, v241, v238
	v_fmac_f32_e32 v245, v240, v240
	v_fmac_f32_e32 v245, v241, v241
	v_lshlrev_b32_e32 v240, 16, v181
	v_and_b32_e32 v241, 0xffff0000, v181
	v_sub_f32_e32 v240, v240, v238
	v_sub_f32_e32 v241, v241, v238
	v_fmac_f32_e32 v245, v240, v240
	v_fmac_f32_e32 v245, v241, v241
	v_lshlrev_b32_e32 v240, 16, v182
	v_and_b32_e32 v241, 0xffff0000, v182
	v_sub_f32_e32 v240, v240, v238
	v_sub_f32_e32 v241, v241, v238
	v_fmac_f32_e32 v245, v240, v240
	v_fmac_f32_e32 v245, v241, v241
	v_lshlrev_b32_e32 v240, 16, v183
	v_and_b32_e32 v241, 0xffff0000, v183
	v_sub_f32_e32 v240, v240, v238
	v_sub_f32_e32 v241, v241, v238
	v_fmac_f32_e32 v245, v240, v240
	v_fmac_f32_e32 v245, v241, v241
	v_lshlrev_b32_e32 v240, 16, v184
	v_and_b32_e32 v241, 0xffff0000, v184
	v_sub_f32_e32 v240, v240, v238
	v_sub_f32_e32 v241, v241, v238
	v_fmac_f32_e32 v245, v240, v240
	v_fmac_f32_e32 v245, v241, v241
	v_lshlrev_b32_e32 v240, 16, v185
	v_and_b32_e32 v241, 0xffff0000, v185
	v_sub_f32_e32 v240, v240, v238
	v_sub_f32_e32 v241, v241, v238
	v_fmac_f32_e32 v245, v240, v240
	v_fmac_f32_e32 v245, v241, v241
	v_mov_b32_e32 v240, v245
	s_nop 1
	v_permlane16_swap_b32_e32 v240, v245
	v_add_f32_e32 v245, v245, v240
	v_mov_b32_e32 v240, v245
	s_nop 1
	v_permlane32_swap_b32_e32 v240, v245
	v_add_f32_e32 v245, v245, v240
	v_mov_b32_e32 v240, 0x3a27c5ac
	v_fmamk_f32 v245, v245, 0x3c800000, v240
	v_rsq_f32_e32 v239, v245
	v_and_b32_e32 v240, 3, v248
	v_cmp_eq_u32_e32 vcc, 0, v240
	s_nop 1
	v_lshlrev_b32_e32 v240, 16, v178
	v_and_b32_e32 v244, 0xffff0000, v178
	v_sub_f32_e32 v240, v240, v238
	v_sub_f32_e32 v244, v244, v238
	v_mul_f32_e32 v240, v240, v239
	v_mul_f32_e32 v244, v244, v239
	v_fma_f32 v240, v130, v240, v146
	v_fma_f32 v244, v131, v244, v147
	v_lshlrev_b32_e32 v241, 16, v186
	v_and_b32_e32 v245, 0xffff0000, v186
	v_lshlrev_b32_e32 v243, 16, v194
	v_and_b32_e32 v246, 0xffff0000, v194
	v_cndmask_b32_e32 v243, v243, v202, vcc
	v_cndmask_b32_e32 v246, v246, v203, vcc
	v_sub_f32_e32 v243, v243, v241
	v_sub_f32_e32 v246, v246, v245
	v_fmac_f32_e32 v241, v162, v243
	v_fmac_f32_e32 v245, v163, v246
	v_fmac_f32_e32 v240, v234, v241
	v_fmac_f32_e32 v244, v234, v245
	v_mul_f32_e32 v112, v112, v240
	v_mul_f32_e32 v113, v113, v244
	v_lshlrev_b32_e32 v240, 16, v179
	v_and_b32_e32 v244, 0xffff0000, v179
	v_sub_f32_e32 v240, v240, v238
	v_sub_f32_e32 v244, v244, v238
	v_mul_f32_e32 v240, v240, v239
	v_mul_f32_e32 v244, v244, v239
	v_fma_f32 v240, v132, v240, v148
	v_fma_f32 v244, v133, v244, v149
	v_lshlrev_b32_e32 v241, 16, v187
	v_and_b32_e32 v245, 0xffff0000, v187
	v_lshlrev_b32_e32 v243, 16, v195
	v_and_b32_e32 v246, 0xffff0000, v195
	v_cndmask_b32_e32 v243, v243, v204, vcc
	v_cndmask_b32_e32 v246, v246, v205, vcc
	v_sub_f32_e32 v243, v243, v241
	v_sub_f32_e32 v246, v246, v245
	v_fmac_f32_e32 v241, v164, v243
	v_fmac_f32_e32 v245, v165, v246
	v_fmac_f32_e32 v240, v234, v241
	v_fmac_f32_e32 v244, v234, v245
	v_mul_f32_e32 v114, v114, v240
	v_mul_f32_e32 v115, v115, v244
	v_lshlrev_b32_e32 v240, 16, v180
	v_and_b32_e32 v244, 0xffff0000, v180
	v_sub_f32_e32 v240, v240, v238
	v_sub_f32_e32 v244, v244, v238
; __device__ __forceinline__ float bf2f(u16 h) { return __uint_as_float(((unsigned)h) << 16); }
; template <int EPI> ...
;     ...
;         float pv0 = bf2f(P[(size_t)row * 2816 + 256 + 1536 + ch0]);
;         float pv1 = bf2f(P[(size_t)row * 2816 + 256 + 1536 + ch1]);
;         float pp0 = prevP(p, P, row, 1536 + ch0), pp1 = prevP(p, P, row, 1536 + ch1);
;         float vv0 = pv0 + (pp0 - pv0) * mu0, vv1 = pv1 + (pp1 - pv1) * mu1;
;         float b = bs[((size_t)row * 12 + hh) * 4 + 2];
;         float y0 = (d0 * rstd * gg0 + gb0 + b * vv0) * acc0[i];
;         float y1 = (d1 * rstd * gg1 + gb1 + b * vv1) * acc1[i];
;         Y[(size_t)row * 1024 + 256 + ch0] = f2bf(y0);
;         Y[(size_t)row * 1024 + 256 + ch1] = f2bf(y1);
;       }
	v_mul_f32_e32 v240, v240, v239
	v_mul_f32_e32 v244, v244, v239
	v_fma_f32 v240, v134, v240, v150
	v_fma_f32 v244, v135, v244, v151
	v_lshlrev_b32_e32 v241, 16, v188
	v_and_b32_e32 v245, 0xffff0000, v188
	v_lshlrev_b32_e32 v243, 16, v196
	v_and_b32_e32 v246, 0xffff0000, v196
	v_cndmask_b32_e32 v243, v243, v206, vcc
	v_cndmask_b32_e32 v246, v246, v207, vcc
	v_sub_f32_e32 v243, v243, v241
	v_sub_f32_e32 v246, v246, v245
	v_fmac_f32_e32 v241, v166, v243
	v_fmac_f32_e32 v245, v167, v246
	v_fmac_f32_e32 v240, v234, v241
	v_fmac_f32_e32 v244, v234, v245
	v_mul_f32_e32 v116, v116, v240
	v_mul_f32_e32 v117, v117, v244
	v_lshlrev_b32_e32 v240, 16, v181
	v_and_b32_e32 v244, 0xffff0000, v181
	v_sub_f32_e32 v240, v240, v238
	v_sub_f32_e32 v244, v244, v238
	v_mul_f32_e32 v240, v240, v239
	v_mul_f32_e32 v244, v244, v239
	v_fma_f32 v240, v136, v240, v152
	v_fma_f32 v244, v137, v244, v153
	v_lshlrev_b32_e32 v241, 16, v189
	v_and_b32_e32 v245, 0xffff0000, v189
	v_lshlrev_b32_e32 v243, 16, v197
	v_and_b32_e32 v246, 0xffff0000, v197
	v_cndmask_b32_e32 v243, v243, v208, vcc
	v_cndmask_b32_e32 v246, v246, v209, vcc
	v_sub_f32_e32 v243, v243, v241
	v_sub_f32_e32 v246, v246, v245
	v_fmac_f32_e32 v241, v168, v243
	v_fmac_f32_e32 v245, v169, v246
	v_fmac_f32_e32 v240, v234, v241
	v_fmac_f32_e32 v244, v234, v245
	v_mul_f32_e32 v118, v118, v240
	v_mul_f32_e32 v119, v119, v244
	v_cvt_pk_bf16_f32 v112, v112, v113
	v_cvt_pk_bf16_f32 v113, v114, v115
	v_cvt_pk_bf16_f32 v114, v116, v117
	v_cvt_pk_bf16_f32 v115, v118, v119
	v_add_u32_e32 v236, 0x18000, v230
	s_nop 0
	global_store_dwordx4 v236, v[112:115], s[22:23] offset:128
	v_lshlrev_b32_e32 v240, 16, v182
	v_and_b32_e32 v244, 0xffff0000, v182
	v_sub_f32_e32 v240, v240, v238
	v_sub_f32_e32 v244, v244, v238
	v_mul_f32_e32 v240, v240, v239
	v_mul_f32_e32 v244, v244, v239
	v_fma_f32 v240, v138, v240, v154
	v_fma_f32 v244, v139, v244, v155
	v_lshlrev_b32_e32 v241, 16, v190
	v_and_b32_e32 v245, 0xffff0000, v190
	v_lshlrev_b32_e32 v243, 16, v198
	v_and_b32_e32 v246, 0xffff0000, v198
	v_cndmask_b32_e32 v243, v243, v210, vcc
	v_cndmask_b32_e32 v246, v246, v211, vcc
	v_sub_f32_e32 v243, v243, v241
	v_sub_f32_e32 v246, v246, v245
	v_fmac_f32_e32 v241, v170, v243
	v_fmac_f32_e32 v245, v171, v246
	v_fmac_f32_e32 v240, v234, v241
	v_fmac_f32_e32 v244, v234, v245
	v_mul_f32_e32 v120, v120, v240
	v_mul_f32_e32 v121, v121, v244
	v_lshlrev_b32_e32 v240, 16, v183
	v_and_b32_e32 v244, 0xffff0000, v183
	v_sub_f32_e32 v240, v240, v238
	v_sub_f32_e32 v244, v244, v238
	v_mul_f32_e32 v240, v240, v239
	v_mul_f32_e32 v244, v244, v239
	v_fma_f32 v240, v140, v240, v156
	v_fma_f32 v244, v141, v244, v157
	v_lshlrev_b32_e32 v241, 16, v191
	v_and_b32_e32 v245, 0xffff0000, v191
	v_lshlrev_b32_e32 v243, 16, v199
	v_and_b32_e32 v246, 0xffff0000, v199
	v_cndmask_b32_e32 v243, v243, v212, vcc
	v_cndmask_b32_e32 v246, v246, v213, vcc
	v_sub_f32_e32 v243, v243, v241
	v_sub_f32_e32 v246, v246, v245
	v_fmac_f32_e32 v241, v172, v243
	v_fmac_f32_e32 v245, v173, v246
	v_fmac_f32_e32 v240, v234, v241
	v_fmac_f32_e32 v244, v234, v245
	v_mul_f32_e32 v122, v122, v240
	v_mul_f32_e32 v123, v123, v244
	v_lshlrev_b32_e32 v240, 16, v184
	v_and_b32_e32 v244, 0xffff0000, v184
	v_sub_f32_e32 v240, v240, v238
	v_sub_f32_e32 v244, v244, v238
	v_mul_f32_e32 v240, v240, v239
	v_mul_f32_e32 v244, v244, v239
	v_fma_f32 v240, v142, v240, v158
	v_fma_f32 v244, v143, v244, v159
	v_lshlrev_b32_e32 v241, 16, v192
	v_and_b32_e32 v245, 0xffff0000, v192
	v_lshlrev_b32_e32 v243, 16, v200
	v_and_b32_e32 v246, 0xffff0000, v200
	v_cndmask_b32_e32 v243, v243, v214, vcc
	v_cndmask_b32_e32 v246, v246, v215, vcc
	v_sub_f32_e32 v243, v243, v241
	v_sub_f32_e32 v246, v246, v245
	v_fmac_f32_e32 v241, v174, v243
	v_fmac_f32_e32 v245, v175, v246
	v_fmac_f32_e32 v240, v234, v241
	v_fmac_f32_e32 v244, v234, v245
	v_mul_f32_e32 v124, v124, v240
	v_mul_f32_e32 v125, v125, v244
	v_lshlrev_b32_e32 v240, 16, v185
	v_and_b32_e32 v244, 0xffff0000, v185
	v_sub_f32_e32 v240, v240, v238
	v_sub_f32_e32 v244, v244, v238
	v_mul_f32_e32 v240, v240, v239
	v_mul_f32_e32 v244, v244, v239
	v_fma_f32 v240, v144, v240, v160
	v_fma_f32 v244, v145, v244, v161
	v_lshlrev_b32_e32 v241, 16, v193
	v_and_b32_e32 v245, 0xffff0000, v193
	v_lshlrev_b32_e32 v243, 16, v201
	v_and_b32_e32 v246, 0xffff0000, v201
	v_cndmask_b32_e32 v243, v243, v216, vcc
	v_cndmask_b32_e32 v246, v246, v217, vcc
	v_sub_f32_e32 v243, v243, v241
	v_sub_f32_e32 v246, v246, v245
	v_fmac_f32_e32 v241, v176, v243
	v_fmac_f32_e32 v245, v177, v246
	v_fmac_f32_e32 v240, v234, v241
	v_fmac_f32_e32 v244, v234, v245
	v_mul_f32_e32 v126, v126, v240
	v_mul_f32_e32 v127, v127, v244
	v_cvt_pk_bf16_f32 v120, v120, v121
	v_cvt_pk_bf16_f32 v121, v122, v123
	v_cvt_pk_bf16_f32 v122, v124, v125
	v_cvt_pk_bf16_f32 v123, v126, v127
	v_add_u32_e32 v236, 0x18000, v230
	s_nop 0
	global_store_dwordx4 v236, v[120:123], s[22:23] offset:192
.Lpo_done:
	s_branch .Lgc_next

; template <int EPI>
; __device__ __forceinline__ void gemm_phase(const Params& p, const u16* __restrict__ A, int lda, const u16* __restrict__ BT, int ldb,
;                            int K, int N, u16* __restrict__ outb, int ldo, int resid_in, int boff) {
;     ...
;     const int m0 = mt * 256, n0 = nt * 128;
;     const u16* gA = A + (size_t)(m0 + lrow) * lda + lch * 8 + (size_t)kbeg * 64;
;     const u16* gB = BT + (size_t)(n0 + lrow) * ldb + lch * 8 + (size_t)kbeg * 64;
;     uint4 xa0, xa1, xa2, xa3, xb0, xb1;
;     uint4 ya0, ya1, ya2, ya3, yb0, yb1;
.Lgm_producer:
	v_and_b32_e32 v162, 63, v128
	s_sub_u32 s4, s4, 4
	v_and_b32_e32 v160, 7, v162
	v_lshrrev_b32_e32 v161, 4, v162
	v_xor_b32_e32 v163, v160, v161
	v_or_b32_e32 v161, 4, v161
	v_xor_b32_e32 v161, v160, v161
	v_lshlrev_b32_e32 v163, 4, v163
	v_lshlrev_b32_e32 v161, 4, v161
	v_lshrrev_b32_e32 v160, 3, v162
	s_lshl_b32 s6, s4, 6
	v_add_u32_e32 v164, s6, v160
	v_lshlrev_b32_e32 v164, s45, v164
	s_lshl_b32 s7, 8, s45
	v_add_u32_e32 v130, v164, v163
	v_add_u32_e32 v164, s7, v164
	v_add_u32_e32 v131, v164, v161
	v_add_u32_e32 v164, s7, v164
	v_add_u32_e32 v132, v164, v163
	v_add_u32_e32 v164, s7, v164
	v_add_u32_e32 v133, v164, v161
	v_add_u32_e32 v164, s7, v164
	v_add_u32_e32 v134, v164, v163
	v_add_u32_e32 v164, s7, v164
	v_add_u32_e32 v135, v164, v161
	v_add_u32_e32 v164, s7, v164
	v_add_u32_e32 v136, v164, v163
	v_add_u32_e32 v164, s7, v164
	v_add_u32_e32 v137, v164, v161
	s_lshl_b32 s6, s4, 5
	v_add_u32_e32 v164, s6, v160
	v_lshlrev_b32_e32 v164, s46, v164
	s_lshl_b32 s7, 8, s46
	s_cmp_eq_u32 s30, 5
	s_cbranch_scc1 .Lgp_bperm
	v_add_u32_e32 v138, v164, v163
	v_add_u32_e32 v164, s7, v164
	v_add_u32_e32 v139, v164, v161
	v_add_u32_e32 v164, s7, v164
	v_add_u32_e32 v140, v164, v163
	v_add_u32_e32 v164, s7, v164
	v_add_u32_e32 v141, v164, v161
	s_branch .Lgp_bperm_done
.Lgp_bperm:
	v_add_u32_e32 v164, s6, v160
	v_add_u32_e32 v165, 0, v164
	v_and_b32_e32 v138, 0xffffffe0, v165
	v_bfe_u32 v142, v165, 2, 2
	v_lshl_or_b32 v138, v142, 3, v138
	v_bfe_u32 v142, v165, 4, 1
	v_lshl_or_b32 v138, v142, 2, v138
	v_and_b32_e32 v142, 3, v165
	v_or_b32_e32 v138, v138, v142
	v_lshlrev_b32_e32 v138, s46, v138
	v_add_u32_e32 v138, v138, v163
	v_add_u32_e32 v165, 8, v164
	v_and_b32_e32 v139, 0xffffffe0, v165
	v_bfe_u32 v142, v165, 2, 2
	v_lshl_or_b32 v139, v142, 3, v139
	v_bfe_u32 v142, v165, 4, 1
	v_lshl_or_b32 v139, v142, 2, v139
	v_and_b32_e32 v142, 3, v165
	v_or_b32_e32 v139, v139, v142
	v_lshlrev_b32_e32 v139, s46, v139
	v_add_u32_e32 v139, v139, v161
	v_add_u32_e32 v165, 16, v164
	v_and_b32_e32 v140, 0xffffffe0, v165
	v_bfe_u32 v142, v165, 2, 2
	v_lshl_or_b32 v140, v142, 3, v140
	v_bfe_u32 v142, v165, 4, 1
	v_lshl_or_b32 v140, v142, 2, v140
	v_and_b32_e32 v142, 3, v165
	v_or_b32_e32 v140, v140, v142
	v_lshlrev_b32_e32 v140, s46, v140
	v_add_u32_e32 v140, v140, v163
	v_add_u32_e32 v165, 24, v164
	v_and_b32_e32 v141, 0xffffffe0, v165
	v_bfe_u32 v142, v165, 2, 2
	v_lshl_or_b32 v141, v142, 3, v141
	v_bfe_u32 v142, v165, 4, 1
	v_lshl_or_b32 v141, v142, 2, v141
	v_and_b32_e32 v142, 3, v165
	v_or_b32_e32 v141, v141, v142
	v_lshlrev_b32_e32 v141, s46, v141
	v_add_u32_e32 v141, v141, v161
.Lgp_bperm_done:
	s_lshl_b32 s6, s4, 6
	v_add_u32_e32 v165, s6, v162
	v_lshlrev_b32_e32 v164, 2, v165
	v_add_u32_e32 v164, 0x24000, v164
	s_lshl_b32 s32, s4, 13
	s_lshl_b32 s34, s4, 12
	s_add_u32 s34, s34, 0x8000
	s_mov_b32 s31, 0
	s_mov_b32 s33, 0
	s_mov_b32 s12, 0
	s_mov_b32 s10, 0
	s_mov_b32 s35, 0
	s_mov_b32 s36, s5
	s_lshr_b32 s37, s39, s44

; #define PH(n, sync_) if (plo <= (n) && (n) <= phi) { if ((n) > plo && (sync_)) { if ((n) == 1) { grid.sync(); xb = xcd_barrier_post((unsigned*)(ws + O_XBAR), (volatile LAS unsigned*)&xb_words); } else xcd_barrier(xb); }
; __global__ void __launch_bounds__(512) mega(Params p, int plo, int phi) {
;     ...
;   PH(1, 1) gemm_phase<EPI_SCALE>(p, WSB(O_XB), 1024, WSB(O_WIN0), 1024, 1024, 2816, WSO(O_P), 2816, 0, 0); PHEND
;   PH(2, 1) pool_phase(p); PHEND
;   PH(3, 1) gemm_phase<EPI_PLAIN>(p, WSB(O_LIN), 256, WSB(O_WLW), 64, 64, 768, WSO(O_WPRE), 768, 0, 0); PHEND
;   PH(4, 0) gemm_phase<EPI_PLAIN>(p, WSB(O_LIN + 128), 256, WSB(O_WLA), 64, 64, 768, WSO(O_APRE), 768, 0, 140); PHEND
;   PH(5, 1) rwkv_prep_phase(p); PHEND
;   PH(6, 1) scan_phase(p, 0, 0, 3264); pool_queue(p); PHEND
;   PH(7, 1) gemm_phase<EPI_POST>(p, WSB(O_LIN + 256), 256, WSB(O_WLG), 128, 128, 768, nullptr, 0, 0, 0); PHEND
;   PH(8, 1) gemm_phase<EPI_RES>(p, WSB(O_Y), 1024, WSB(O_WOUT0), 1024, 1024, 1024, WSO(O_XB), 1024, 1, 0); PHEND
;   PH(9, 1) res_fix_phase(p); PHEND
;   PH(10, 1) gemm_phase<EPI_FF1>(p, WSB(O_XB), 1024, WSB(O_WF10), 1024, 1024, 4096, WSO(O_H), 4096, 0, 0); PHEND
;   PH(11, 1) gemm_phase<EPI_RES>(p, WSB(O_H), 4096, WSB(O_WF20), 4096, 4096, 1024, WSO(O_XB), 1024, 0, 0); PHEND
;   PH(12, 1) res_fix_phase(p); PHEND
;   PH(13, 1) gemm_phase<EPI_SCALE>(p, WSB(O_XB), 1024, WSB(O_WIN1), 1024, 1024, 2048, WSO(O_P), 2048, 0, 0); PHEND
;   PH(14, 1) mix1_phase(p); PHEND
;   PH(15, 1) lru_fix_phase(p, xb); PHEND
;   PH(16, 1) gemm_phase<EPI_RES>(p, WSB(O_Y), 1024, WSB(O_WOUT1), 1024, 1024, 1024, WSO(O_XB), 1024, 0, 0); PHEND
;   PH(17, 1) res_fix_phase(p); PHEND
;   PH(18, 1) gemm_phase<EPI_FF1>(p, WSB(O_XB), 1024, WSB(O_WF11), 1024, 1024, 4096, WSO(O_H), 4096, 0, 0); PHEND
.Lgm_restore:
	v_readlane_b32 s0, v255, 0
	v_readlane_b32 s1, v255, 1
	v_readlane_b32 s2, v255, 2
	v_readlane_b32 s3, v255, 3
	v_readlane_b32 s4, v255, 4
	v_readlane_b32 s5, v255, 5
	v_readlane_b32 s18, v255, 6
	v_readlane_b32 s19, v255, 7
	v_readlane_b32 s20, v255, 8
	v_readlane_b32 s21, v255, 9
	v_readlane_b32 s22, v255, 10
	v_readlane_b32 s23, v255, 11
	v_readlane_b32 s24, v255, 12
	v_readlane_b32 s25, v255, 13
	v_readlane_b32 s26, v255, 14
	v_readlane_b32 s27, v255, 15
	v_readlane_b32 s28, v255, 16
	v_readlane_b32 s29, v255, 17
	v_readlane_b32 s30, v255, 18
	v_readlane_b32 s31, v255, 19
	v_readlane_b32 s32, v255, 20
	v_readlane_b32 s33, v255, 21
	v_readlane_b32 s34, v255, 22
	v_readlane_b32 s35, v255, 23
	v_readlane_b32 s36, v255, 24
	v_readlane_b32 s37, v255, 25
	v_readlane_b32 s38, v255, 26
	v_readlane_b32 s39, v255, 27
	v_readlane_b32 s44, v255, 28
	v_readlane_b32 s45, v255, 29
	v_readlane_b32 s46, v255, 30
	v_readlane_b32 s47, v255, 31
	v_readlane_b32 s48, v255, 32
	v_readlane_b32 s49, v255, 33
	s_nop 3
	s_cmp_eq_u32 s101, 1
	s_cbranch_scc1 .LBB0_153
	s_cmp_eq_u32 s101, 7
	s_cbranch_scc1 .LBB0_1036
	s_cmp_eq_u32 s101, 8
	s_cbranch_scc1 .LBB0_1188
	s_cmp_eq_u32 s101, 10
	s_cbranch_scc1 .LBB0_1306
	s_cmp_eq_u32 s101, 11
	s_cbranch_scc1 .LBB0_1458
	s_cmp_eq_u32 s101, 13
	s_cbranch_scc1 .LBB0_1576
	s_cmp_eq_u32 s101, 16
	s_cbranch_scc1 .LBB0_1962
	s_cmp_eq_u32 s101, 18
	s_cbranch_scc1 .LBB0_2080
	s_branch .LBB0_2232
